# GEMM loop back-edge rotation; grid-barrier waiters poll the top-level generation word; prep light items spread over all workgroups
# speedup vs baseline: 1.0016x; 1.0016x over previous
.LBB0_780:
	s_or_b64 exec, exec, s[10:11]
	v_cvt_f32_u32_e32 v5, v3
	s_waitcnt vmcnt(0)
	v_readfirstlane_b32 s3, v4
	v_sub_u32_e32 v4, 0, v3
	v_rcp_iflag_f32_e32 v5, v5
	v_add_u32_e32 v6, s3, v2
	v_mul_f32_e32 v5, 0x4f7ffffe, v5
	v_cvt_u32_f32_e32 v5, v5
	v_mul_lo_u32 v2, v4, v5
	v_mul_hi_u32 v2, v5, v2
	v_add_u32_e32 v2, v5, v2
	v_mul_hi_u32 v2, v6, v2
	v_mul_lo_u32 v4, v2, v3
	v_sub_u32_e32 v4, v6, v4
	v_add_u32_e32 v5, 1, v2
	v_cmp_ge_u32_e32 vcc, v4, v3
	s_nop 1
	v_cndmask_b32_e32 v2, v2, v5, vcc
	v_sub_u32_e32 v5, v4, v3
	v_cndmask_b32_e32 v4, v4, v5, vcc
	v_add_u32_e32 v5, 1, v2
	v_cmp_ge_u32_e32 vcc, v4, v3
	v_add_u32_e32 v4, 1, v6
	s_nop 0
	v_cndmask_b32_e32 v2, v2, v5, vcc
	v_mul_lo_u32 v5, v3, v2
	v_add_u32_e32 v3, v5, v3
	v_cmp_ne_u32_e32 vcc, v4, v3
	s_and_saveexec_b64 s[8:9], vcc
	s_xor_b64 s[8:9], exec, s[8:9]
	s_cbranch_execz .LBB0_794
	s_waitcnt lgkmcnt(0)
	s_add_u32 s14, s28, 0xf190900
	s_addc_u32 s15, s29, 0
	v_mov_b32_e32 v1, 0
	global_load_dword v1, v1, s[14:15] sc1
	s_waitcnt vmcnt(0)
	v_cmp_eq_u32_e32 vcc, v1, v2
	s_and_saveexec_b64 s[10:11], vcc
	s_cbranch_execz .LBB0_793
	s_add_u32 s12, s28, 0xf18d600
	s_addc_u32 s13, s29, 0
	s_mov_b32 s3, 1
	s_mov_b64 s[16:17], 0
	v_mov_b32_e32 v1, 0
	s_branch .LBB0_784

.LBB0_833:
	ds_read_b128 v[146:149], v154
	ds_read_b128 v[158:161], v154 offset:1024
	ds_read_b128 v[162:165], v154 offset:2048
	ds_read_b128 v[166:169], v154 offset:3072
	ds_read_b128 v[170:173], v155
	ds_read_b128 v[174:177], v155 offset:1024
	ds_read_b128 v[178:181], v155 offset:2048
	ds_read_b128 v[182:185], v155 offset:3072
	s_add_u32 s68, s66, 0xfffc0080
	s_addc_u32 s69, s67, -1
	s_cmp_eq_u32 s86, 12
	s_cselect_b32 s71, s17, s69
	s_cselect_b32 s70, s62, s68
	s_cselect_b32 s69, s15, s85
	s_cselect_b32 s68, s63, s84
	v_lshl_add_u64 v[150:151], s[66:67], 0, v[138:139]
	s_add_i32 m0, s23, 0xc000
	ds_read_b128 v[186:189], v156
	ds_read_b128 v[190:193], v156 offset:1024
	ds_read_b128 v[194:197], v156 offset:2048
	ds_read_b128 v[198:201], v156 offset:3072
	ds_read_b128 v[202:205], v156 offset:4096
	ds_read_b128 v[206:209], v156 offset:5120
	ds_read_b128 v[210:213], v156 offset:6144
	ds_read_b128 v[214:217], v156 offset:7168
	global_load_lds_dwordx4 v[150:151], off
	v_lshl_add_u64 v[150:151], s[66:67], 0, v[140:141]
	s_add_i32 m0, s23, 0xe000
	s_nop 0
	global_load_lds_dwordx4 v[150:151], off
	s_waitcnt vmcnt(8)
	s_waitcnt lgkmcnt(0)
	s_barrier
	s_setprio 1
	s_waitcnt lgkmcnt(0)
	v_mfma_f32_16x16x32_bf16 v[126:129], v[146:149], v[186:189], v[126:129]
	v_mfma_f32_16x16x32_bf16 v[122:125], v[162:165], v[186:189], v[122:125]
	v_mfma_f32_16x16x32_bf16 v[110:113], v[146:149], v[194:197], v[110:113]
	v_mfma_f32_16x16x32_bf16 v[106:109], v[162:165], v[194:197], v[106:109]
	v_mfma_f32_16x16x32_bf16 v[94:97], v[146:149], v[202:205], v[94:97]
	v_mfma_f32_16x16x32_bf16 v[90:93], v[162:165], v[202:205], v[90:93]
	v_mfma_f32_16x16x32_bf16 v[78:81], v[146:149], v[210:213], v[78:81]
	v_mfma_f32_16x16x32_bf16 v[74:77], v[162:165], v[210:213], v[74:77]
	v_mfma_f32_16x16x32_bf16 v[126:129], v[158:161], v[190:193], v[126:129]
	v_mfma_f32_16x16x32_bf16 v[122:125], v[166:169], v[190:193], v[122:125]
	v_mfma_f32_16x16x32_bf16 v[110:113], v[158:161], v[198:201], v[110:113]
	v_mfma_f32_16x16x32_bf16 v[106:109], v[166:169], v[198:201], v[106:109]
	v_mfma_f32_16x16x32_bf16 v[94:97], v[158:161], v[206:209], v[94:97]
	v_mfma_f32_16x16x32_bf16 v[90:93], v[166:169], v[206:209], v[90:93]
	v_mfma_f32_16x16x32_bf16 v[78:81], v[158:161], v[214:217], v[78:81]
	v_mfma_f32_16x16x32_bf16 v[74:77], v[166:169], v[214:217], v[74:77]
	s_setprio 0
	s_setprio 1
	v_mfma_f32_16x16x32_bf16 v[118:121], v[170:173], v[186:189], v[118:121]
	v_mfma_f32_16x16x32_bf16 v[114:117], v[178:181], v[186:189], v[114:117]
	v_mfma_f32_16x16x32_bf16 v[102:105], v[170:173], v[194:197], v[102:105]
	v_mfma_f32_16x16x32_bf16 v[98:101], v[178:181], v[194:197], v[98:101]
	v_mfma_f32_16x16x32_bf16 v[86:89], v[170:173], v[202:205], v[86:89]
	v_mfma_f32_16x16x32_bf16 v[82:85], v[178:181], v[202:205], v[82:85]
	v_mfma_f32_16x16x32_bf16 v[70:73], v[170:173], v[210:213], v[70:73]
	v_mfma_f32_16x16x32_bf16 v[66:69], v[178:181], v[210:213], v[66:69]
	v_mfma_f32_16x16x32_bf16 v[118:121], v[174:177], v[190:193], v[118:121]
	v_mfma_f32_16x16x32_bf16 v[114:117], v[182:185], v[190:193], v[114:117]
	v_mfma_f32_16x16x32_bf16 v[102:105], v[174:177], v[198:201], v[102:105]
	v_mfma_f32_16x16x32_bf16 v[98:101], v[182:185], v[198:201], v[98:101]
	v_mfma_f32_16x16x32_bf16 v[86:89], v[174:177], v[206:209], v[86:89]
	v_mfma_f32_16x16x32_bf16 v[82:85], v[182:185], v[206:209], v[82:85]
	v_mfma_f32_16x16x32_bf16 v[70:73], v[174:177], v[214:217], v[70:73]
	v_mfma_f32_16x16x32_bf16 v[66:69], v[182:185], v[214:217], v[66:69]
	s_setprio 0
	s_barrier
	s_add_i32 s87, s58, s33
	v_lshl_add_u64 v[150:151], s[68:69], 0, v[132:133]
	s_mov_b32 m0, s87
	ds_read_b128 v[186:189], v156 offset:16384
	ds_read_b128 v[190:193], v156 offset:17408
	ds_read_b128 v[194:197], v156 offset:18432
	ds_read_b128 v[198:201], v156 offset:19456
	ds_read_b128 v[202:205], v156 offset:20480
	ds_read_b128 v[206:209], v156 offset:21504
	ds_read_b128 v[210:213], v156 offset:22528
	ds_read_b128 v[214:217], v156 offset:23552
	global_load_lds_dwordx4 v[150:151], off
	s_add_i32 m0, s87, 0x2000
	s_add_u32 s90, s68, 0x40000
	v_lshl_add_u64 v[218:219], s[68:69], 0, v[136:137]
	s_addc_u32 s91, s69, 0
	s_add_i32 s87, s59, s33
	global_load_lds_dwordx4 v[218:219], off
	v_lshl_add_u64 v[220:221], s[90:91], 0, v[132:133]
	s_mov_b32 m0, s87
	v_lshl_add_u64 v[222:223], s[70:71], 0, v[134:135]
	global_load_lds_dwordx4 v[220:221], off
	v_lshl_add_u64 v[220:221], s[90:91], 0, v[136:137]
	s_add_i32 m0, s87, 0x2000
	s_nop 0
	global_load_lds_dwordx4 v[220:221], off
	v_lshl_add_u64 v[220:221], s[70:71], 0, v[130:131]
	s_mov_b32 m0, s23
	s_nop 0
	global_load_lds_dwordx4 v[220:221], off
	s_mov_b32 m0, s35
	s_nop 0
	global_load_lds_dwordx4 v[222:223], off
	s_waitcnt vmcnt(8)
	s_waitcnt lgkmcnt(0)
	s_barrier
	s_setprio 1
	s_waitcnt lgkmcnt(0)
	v_mfma_f32_16x16x32_bf16 v[62:65], v[146:149], v[186:189], v[62:65]
	v_mfma_f32_16x16x32_bf16 v[58:61], v[162:165], v[186:189], v[58:61]
	v_mfma_f32_16x16x32_bf16 v[46:49], v[146:149], v[194:197], v[46:49]
	v_mfma_f32_16x16x32_bf16 v[42:45], v[162:165], v[194:197], v[42:45]
	v_mfma_f32_16x16x32_bf16 v[30:33], v[146:149], v[202:205], v[30:33]
	v_mfma_f32_16x16x32_bf16 v[26:29], v[162:165], v[202:205], v[26:29]
	v_mfma_f32_16x16x32_bf16 v[14:17], v[146:149], v[210:213], v[14:17]
	v_mfma_f32_16x16x32_bf16 v[10:13], v[162:165], v[210:213], v[10:13]
	v_mfma_f32_16x16x32_bf16 v[62:65], v[158:161], v[190:193], v[62:65]
	v_mfma_f32_16x16x32_bf16 v[58:61], v[166:169], v[190:193], v[58:61]
	v_mfma_f32_16x16x32_bf16 v[46:49], v[158:161], v[198:201], v[46:49]
	v_mfma_f32_16x16x32_bf16 v[42:45], v[166:169], v[198:201], v[42:45]
	v_mfma_f32_16x16x32_bf16 v[30:33], v[158:161], v[206:209], v[30:33]
	v_mfma_f32_16x16x32_bf16 v[26:29], v[166:169], v[206:209], v[26:29]
	v_mfma_f32_16x16x32_bf16 v[14:17], v[158:161], v[214:217], v[14:17]
	v_mfma_f32_16x16x32_bf16 v[10:13], v[166:169], v[214:217], v[10:13]
	s_setprio 0
	s_setprio 1
	v_mfma_f32_16x16x32_bf16 v[54:57], v[170:173], v[186:189], v[54:57]
	v_mfma_f32_16x16x32_bf16 v[50:53], v[178:181], v[186:189], v[50:53]
	v_mfma_f32_16x16x32_bf16 v[38:41], v[170:173], v[194:197], v[38:41]
	v_mfma_f32_16x16x32_bf16 v[34:37], v[178:181], v[194:197], v[34:37]
	v_mfma_f32_16x16x32_bf16 v[22:25], v[170:173], v[202:205], v[22:25]
	v_mfma_f32_16x16x32_bf16 v[18:21], v[178:181], v[202:205], v[18:21]
	v_mfma_f32_16x16x32_bf16 v[6:9], v[170:173], v[210:213], v[6:9]
	v_mfma_f32_16x16x32_bf16 v[2:5], v[178:181], v[210:213], v[2:5]
	v_mfma_f32_16x16x32_bf16 v[54:57], v[174:177], v[190:193], v[54:57]
	v_mfma_f32_16x16x32_bf16 v[50:53], v[182:185], v[190:193], v[50:53]
	v_mfma_f32_16x16x32_bf16 v[38:41], v[174:177], v[198:201], v[38:41]
	v_mfma_f32_16x16x32_bf16 v[34:37], v[182:185], v[198:201], v[34:37]
	v_mfma_f32_16x16x32_bf16 v[22:25], v[174:177], v[206:209], v[22:25]
	v_mfma_f32_16x16x32_bf16 v[18:21], v[182:185], v[206:209], v[18:21]
	v_mfma_f32_16x16x32_bf16 v[6:9], v[174:177], v[214:217], v[6:9]
	v_mfma_f32_16x16x32_bf16 v[2:5], v[182:185], v[214:217], v[2:5]
	s_setprio 0
	s_barrier
	s_add_i32 s87, 0, 0x18000
	v_add_u32_e32 v157, s87, v152
	s_add_i32 s90, 0, 0x1c000
	ds_read_b128 v[146:149], v157
	ds_read_b128 v[158:161], v157 offset:1024
	ds_read_b128 v[162:165], v157 offset:2048
	ds_read_b128 v[166:169], v157 offset:3072
	v_add_u32_e32 v157, s90, v152
	ds_read_b128 v[170:173], v157
	ds_read_b128 v[174:177], v157 offset:1024
	ds_read_b128 v[178:181], v157 offset:2048
	ds_read_b128 v[182:185], v157 offset:3072
	s_add_u32 s70, s70, 0x40000
	s_addc_u32 s71, s71, 0
	s_mov_b32 m0, s52
	v_lshl_add_u64 v[224:225], s[70:71], 0, v[130:131]
	ds_read_b128 v[186:189], v156 offset:32768
	ds_read_b128 v[190:193], v156 offset:33792
	ds_read_b128 v[194:197], v156 offset:34816
	ds_read_b128 v[198:201], v156 offset:35840
	ds_read_b128 v[202:205], v156 offset:36864
	ds_read_b128 v[206:209], v156 offset:37888
	ds_read_b128 v[210:213], v156 offset:38912
	ds_read_b128 v[214:217], v156 offset:39936
	global_load_lds_dwordx4 v[224:225], off
	v_lshl_add_u64 v[224:225], s[70:71], 0, v[134:135]
	s_mov_b32 m0, s53
	s_nop 0
	global_load_lds_dwordx4 v[224:225], off
	s_waitcnt vmcnt(8)
	s_waitcnt lgkmcnt(0)
	s_barrier
	s_setprio 1
	s_waitcnt lgkmcnt(0)
	v_mfma_f32_16x16x32_bf16 v[126:129], v[146:149], v[186:189], v[126:129]
	v_mfma_f32_16x16x32_bf16 v[122:125], v[162:165], v[186:189], v[122:125]
	v_mfma_f32_16x16x32_bf16 v[110:113], v[146:149], v[194:197], v[110:113]
	v_mfma_f32_16x16x32_bf16 v[106:109], v[162:165], v[194:197], v[106:109]
	v_mfma_f32_16x16x32_bf16 v[94:97], v[146:149], v[202:205], v[94:97]
	v_mfma_f32_16x16x32_bf16 v[90:93], v[162:165], v[202:205], v[90:93]
	v_mfma_f32_16x16x32_bf16 v[78:81], v[146:149], v[210:213], v[78:81]
	v_mfma_f32_16x16x32_bf16 v[74:77], v[162:165], v[210:213], v[74:77]
	v_mfma_f32_16x16x32_bf16 v[126:129], v[158:161], v[190:193], v[126:129]
	v_mfma_f32_16x16x32_bf16 v[122:125], v[166:169], v[190:193], v[122:125]
	v_mfma_f32_16x16x32_bf16 v[110:113], v[158:161], v[198:201], v[110:113]
	v_mfma_f32_16x16x32_bf16 v[106:109], v[166:169], v[198:201], v[106:109]
	v_mfma_f32_16x16x32_bf16 v[94:97], v[158:161], v[206:209], v[94:97]
	v_mfma_f32_16x16x32_bf16 v[90:93], v[166:169], v[206:209], v[90:93]
	v_mfma_f32_16x16x32_bf16 v[78:81], v[158:161], v[214:217], v[78:81]
	v_mfma_f32_16x16x32_bf16 v[74:77], v[166:169], v[214:217], v[74:77]
	s_setprio 0
	s_setprio 1
	v_mfma_f32_16x16x32_bf16 v[118:121], v[170:173], v[186:189], v[118:121]
	v_mfma_f32_16x16x32_bf16 v[114:117], v[178:181], v[186:189], v[114:117]
	v_mfma_f32_16x16x32_bf16 v[102:105], v[170:173], v[194:197], v[102:105]
	v_mfma_f32_16x16x32_bf16 v[98:101], v[178:181], v[194:197], v[98:101]
	v_mfma_f32_16x16x32_bf16 v[86:89], v[170:173], v[202:205], v[86:89]
	v_mfma_f32_16x16x32_bf16 v[82:85], v[178:181], v[202:205], v[82:85]
	v_mfma_f32_16x16x32_bf16 v[70:73], v[170:173], v[210:213], v[70:73]
	v_mfma_f32_16x16x32_bf16 v[66:69], v[178:181], v[210:213], v[66:69]
	v_mfma_f32_16x16x32_bf16 v[118:121], v[174:177], v[190:193], v[118:121]
	v_mfma_f32_16x16x32_bf16 v[114:117], v[182:185], v[190:193], v[114:117]
	v_mfma_f32_16x16x32_bf16 v[102:105], v[174:177], v[198:201], v[102:105]
	v_mfma_f32_16x16x32_bf16 v[98:101], v[182:185], v[198:201], v[98:101]
	v_mfma_f32_16x16x32_bf16 v[86:89], v[174:177], v[206:209], v[86:89]
	v_mfma_f32_16x16x32_bf16 v[82:85], v[182:185], v[206:209], v[82:85]
	v_mfma_f32_16x16x32_bf16 v[70:73], v[174:177], v[214:217], v[70:73]
	v_mfma_f32_16x16x32_bf16 v[66:69], v[182:185], v[214:217], v[66:69]
	s_setprio 0
	s_barrier
	s_add_i32 s70, s87, s33
	v_lshl_add_u64 v[150:151], v[150:151], 0, s[10:11]
	s_mov_b32 m0, s70
	ds_read_b128 v[186:189], v156 offset:49152
	ds_read_b128 v[190:193], v156 offset:50176
	ds_read_b128 v[194:197], v156 offset:51200
	ds_read_b128 v[198:201], v156 offset:52224
	ds_read_b128 v[202:205], v156 offset:53248
	ds_read_b128 v[206:209], v156 offset:54272
	ds_read_b128 v[210:213], v156 offset:55296
	ds_read_b128 v[214:217], v156 offset:56320
	global_load_lds_dwordx4 v[150:151], off
	s_add_i32 m0, s70, 0x2000
	s_add_u32 s68, s68, 0x40080
	v_lshl_add_u64 v[150:151], v[218:219], 0, s[10:11]
	s_addc_u32 s69, s69, 0
	s_add_i32 s70, s90, s33
	global_load_lds_dwordx4 v[150:151], off
	v_lshl_add_u64 v[150:151], s[68:69], 0, v[132:133]
	s_mov_b32 m0, s70
	s_nop 0
	global_load_lds_dwordx4 v[150:151], off
	v_lshl_add_u64 v[150:151], s[68:69], 0, v[136:137]
	s_add_i32 m0, s70, 0x2000
	s_nop 0
	global_load_lds_dwordx4 v[150:151], off
	v_lshl_add_u64 v[150:151], v[220:221], 0, s[10:11]
	s_mov_b32 m0, s55
	s_nop 0
	global_load_lds_dwordx4 v[150:151], off
	v_lshl_add_u64 v[150:151], v[222:223], 0, s[10:11]
	s_mov_b32 m0, s56
	s_nop 0
	global_load_lds_dwordx4 v[150:151], off
	s_waitcnt vmcnt(8)
	s_waitcnt lgkmcnt(0)
	s_barrier
	s_setprio 1
	s_waitcnt lgkmcnt(0)
	v_mfma_f32_16x16x32_bf16 v[62:65], v[146:149], v[186:189], v[62:65]
	v_mfma_f32_16x16x32_bf16 v[58:61], v[162:165], v[186:189], v[58:61]
	v_mfma_f32_16x16x32_bf16 v[46:49], v[146:149], v[194:197], v[46:49]
	v_mfma_f32_16x16x32_bf16 v[42:45], v[162:165], v[194:197], v[42:45]
	v_mfma_f32_16x16x32_bf16 v[30:33], v[146:149], v[202:205], v[30:33]
	v_mfma_f32_16x16x32_bf16 v[26:29], v[162:165], v[202:205], v[26:29]
	v_mfma_f32_16x16x32_bf16 v[14:17], v[146:149], v[210:213], v[14:17]
	v_mfma_f32_16x16x32_bf16 v[10:13], v[162:165], v[210:213], v[10:13]
	v_mfma_f32_16x16x32_bf16 v[62:65], v[158:161], v[190:193], v[62:65]
	v_mfma_f32_16x16x32_bf16 v[58:61], v[166:169], v[190:193], v[58:61]
	v_mfma_f32_16x16x32_bf16 v[46:49], v[158:161], v[198:201], v[46:49]
	v_mfma_f32_16x16x32_bf16 v[42:45], v[166:169], v[198:201], v[42:45]
	v_mfma_f32_16x16x32_bf16 v[30:33], v[158:161], v[206:209], v[30:33]
	v_mfma_f32_16x16x32_bf16 v[26:29], v[166:169], v[206:209], v[26:29]
	v_mfma_f32_16x16x32_bf16 v[14:17], v[158:161], v[214:217], v[14:17]
	v_mfma_f32_16x16x32_bf16 v[10:13], v[166:169], v[214:217], v[10:13]
	s_setprio 0
	s_setprio 1
	v_mfma_f32_16x16x32_bf16 v[54:57], v[170:173], v[186:189], v[54:57]
	v_mfma_f32_16x16x32_bf16 v[50:53], v[178:181], v[186:189], v[50:53]
	v_mfma_f32_16x16x32_bf16 v[38:41], v[170:173], v[194:197], v[38:41]
	v_mfma_f32_16x16x32_bf16 v[34:37], v[178:181], v[194:197], v[34:37]
	v_mfma_f32_16x16x32_bf16 v[22:25], v[170:173], v[202:205], v[22:25]
	v_mfma_f32_16x16x32_bf16 v[18:21], v[178:181], v[202:205], v[18:21]
	v_mfma_f32_16x16x32_bf16 v[6:9], v[170:173], v[210:213], v[6:9]
	v_mfma_f32_16x16x32_bf16 v[2:5], v[178:181], v[210:213], v[2:5]
	v_mfma_f32_16x16x32_bf16 v[54:57], v[174:177], v[190:193], v[54:57]
	v_mfma_f32_16x16x32_bf16 v[50:53], v[182:185], v[190:193], v[50:53]
	v_mfma_f32_16x16x32_bf16 v[38:41], v[174:177], v[198:201], v[38:41]
	v_mfma_f32_16x16x32_bf16 v[34:37], v[182:185], v[198:201], v[34:37]
	v_mfma_f32_16x16x32_bf16 v[22:25], v[174:177], v[206:209], v[22:25]
	v_mfma_f32_16x16x32_bf16 v[18:21], v[182:185], v[206:209], v[18:21]
	v_mfma_f32_16x16x32_bf16 v[6:9], v[174:177], v[214:217], v[6:9]
	v_mfma_f32_16x16x32_bf16 v[2:5], v[182:185], v[214:217], v[2:5]
	s_setprio 0
	s_add_i32 s86, s86, 2
	s_add_u32 s66, s66, 0x100
	s_addc_u32 s67, s67, 0
	s_add_u32 s84, s84, 0x100
	s_addc_u32 s85, s85, 0
	s_cmp_gt_u32 s86, 13
	s_barrier
	s_cbranch_scc0 .LBB0_833
	s_and_b64 vcc, exec, s[12:13]
	s_cbranch_vccz .LBB0_836
	s_barrier

.LBB0_918:
	ds_read_b128 v[130:133], v174
	ds_read_b128 v[134:137], v174 offset:1024
	ds_read_b128 v[160:163], v174 offset:2048
	ds_read_b128 v[164:167], v174 offset:3072
	ds_read_b128 v[178:181], v175
	ds_read_b128 v[182:185], v175 offset:1024
	ds_read_b128 v[186:189], v175 offset:2048
	ds_read_b128 v[190:193], v175 offset:3072
	s_add_u32 s66, s8, 0xfff50080
	s_addc_u32 s67, s9, -1
	s_cmp_eq_u32 s96, 40
	s_cselect_b32 s91, s23, s67
	s_cselect_b32 s90, s22, s66
	s_cselect_b32 s71, s69, s95
	s_cselect_b32 s70, s68, s53
	v_lshl_add_u64 v[138:139], s[8:9], 0, v[152:153]
	s_add_i32 m0, s33, 0xc000
	ds_read_b128 v[194:197], v176
	ds_read_b128 v[198:201], v176 offset:1024
	ds_read_b128 v[202:205], v176 offset:2048
	ds_read_b128 v[206:209], v176 offset:3072
	ds_read_b128 v[210:213], v176 offset:4096
	ds_read_b128 v[214:217], v176 offset:5120
	ds_read_b128 v[218:221], v176 offset:6144
	ds_read_b128 v[222:225], v176 offset:7168
	global_load_lds_dwordx4 v[138:139], off
	v_lshl_add_u64 v[138:139], s[8:9], 0, v[154:155]
	s_add_i32 m0, s33, 0xe000
	s_nop 0
	global_load_lds_dwordx4 v[138:139], off
	s_waitcnt vmcnt(8)
	s_waitcnt lgkmcnt(0)
	s_barrier
	s_setprio 1
	s_waitcnt lgkmcnt(0)
	v_mfma_f32_16x16x32_bf16 v[126:129], v[130:133], v[194:197], v[126:129]
	v_mfma_f32_16x16x32_bf16 v[122:125], v[160:163], v[194:197], v[122:125]
	v_mfma_f32_16x16x32_bf16 v[110:113], v[130:133], v[202:205], v[110:113]
	v_mfma_f32_16x16x32_bf16 v[106:109], v[160:163], v[202:205], v[106:109]
	v_mfma_f32_16x16x32_bf16 v[94:97], v[130:133], v[210:213], v[94:97]
	v_mfma_f32_16x16x32_bf16 v[90:93], v[160:163], v[210:213], v[90:93]
	v_mfma_f32_16x16x32_bf16 v[78:81], v[130:133], v[218:221], v[78:81]
	v_mfma_f32_16x16x32_bf16 v[74:77], v[160:163], v[218:221], v[74:77]
	v_mfma_f32_16x16x32_bf16 v[126:129], v[134:137], v[198:201], v[126:129]
	v_mfma_f32_16x16x32_bf16 v[122:125], v[164:167], v[198:201], v[122:125]
	v_mfma_f32_16x16x32_bf16 v[110:113], v[134:137], v[206:209], v[110:113]
	v_mfma_f32_16x16x32_bf16 v[106:109], v[164:167], v[206:209], v[106:109]
	v_mfma_f32_16x16x32_bf16 v[94:97], v[134:137], v[214:217], v[94:97]
	v_mfma_f32_16x16x32_bf16 v[90:93], v[164:167], v[214:217], v[90:93]
	v_mfma_f32_16x16x32_bf16 v[78:81], v[134:137], v[222:225], v[78:81]
	v_mfma_f32_16x16x32_bf16 v[74:77], v[164:167], v[222:225], v[74:77]
	s_setprio 0
	s_setprio 1
	v_mfma_f32_16x16x32_bf16 v[118:121], v[178:181], v[194:197], v[118:121]
	v_mfma_f32_16x16x32_bf16 v[114:117], v[186:189], v[194:197], v[114:117]
	v_mfma_f32_16x16x32_bf16 v[102:105], v[178:181], v[202:205], v[102:105]
	v_mfma_f32_16x16x32_bf16 v[98:101], v[186:189], v[202:205], v[98:101]
	v_mfma_f32_16x16x32_bf16 v[86:89], v[178:181], v[210:213], v[86:89]
	v_mfma_f32_16x16x32_bf16 v[82:85], v[186:189], v[210:213], v[82:85]
	v_mfma_f32_16x16x32_bf16 v[70:73], v[178:181], v[218:221], v[70:73]
	v_mfma_f32_16x16x32_bf16 v[66:69], v[186:189], v[218:221], v[66:69]
	v_mfma_f32_16x16x32_bf16 v[118:121], v[182:185], v[198:201], v[118:121]
	v_mfma_f32_16x16x32_bf16 v[114:117], v[190:193], v[198:201], v[114:117]
	v_mfma_f32_16x16x32_bf16 v[102:105], v[182:185], v[206:209], v[102:105]
	v_mfma_f32_16x16x32_bf16 v[98:101], v[190:193], v[206:209], v[98:101]
	v_mfma_f32_16x16x32_bf16 v[86:89], v[182:185], v[214:217], v[86:89]
	v_mfma_f32_16x16x32_bf16 v[82:85], v[190:193], v[214:217], v[82:85]
	v_mfma_f32_16x16x32_bf16 v[70:73], v[182:185], v[222:225], v[70:73]
	v_mfma_f32_16x16x32_bf16 v[66:69], v[190:193], v[222:225], v[66:69]
	s_setprio 0
	s_barrier
	s_add_i32 s66, s84, s3
	v_lshl_add_u64 v[138:139], s[70:71], 0, v[142:143]
	s_mov_b32 m0, s66
	ds_read_b128 v[194:197], v176 offset:16384
	ds_read_b128 v[198:201], v176 offset:17408
	ds_read_b128 v[202:205], v176 offset:18432
	ds_read_b128 v[206:209], v176 offset:19456
	ds_read_b128 v[210:213], v176 offset:20480
	ds_read_b128 v[214:217], v176 offset:21504
	ds_read_b128 v[218:221], v176 offset:22528
	ds_read_b128 v[222:225], v176 offset:23552
	global_load_lds_dwordx4 v[138:139], off
	s_add_i32 m0, s66, 0x2000
	s_add_u32 vcc_lo, s70, 0xb0000
	v_lshl_add_u64 v[226:227], s[70:71], 0, v[146:147]
	s_addc_u32 vcc_hi, s71, 0
	s_add_i32 s66, s85, s3
	global_load_lds_dwordx4 v[226:227], off
	v_lshl_add_u64 v[228:229], vcc, 0, v[142:143]
	s_mov_b32 m0, s66
	v_lshl_add_u64 v[230:231], s[90:91], 0, v[144:145]
	global_load_lds_dwordx4 v[228:229], off
	v_lshl_add_u64 v[228:229], vcc, 0, v[146:147]
	s_add_i32 m0, s66, 0x2000
	s_nop 0
	global_load_lds_dwordx4 v[228:229], off
	v_lshl_add_u64 v[228:229], s[90:91], 0, v[140:141]
	s_mov_b32 m0, s33
	s_nop 0
	global_load_lds_dwordx4 v[228:229], off
	s_mov_b32 m0, s35
	s_nop 0
	global_load_lds_dwordx4 v[230:231], off
	s_waitcnt vmcnt(8)
	s_waitcnt lgkmcnt(0)
	s_barrier
	s_setprio 1
	s_waitcnt lgkmcnt(0)
	v_mfma_f32_16x16x32_bf16 v[62:65], v[130:133], v[194:197], v[62:65]
	v_mfma_f32_16x16x32_bf16 v[58:61], v[160:163], v[194:197], v[58:61]
	v_mfma_f32_16x16x32_bf16 v[46:49], v[130:133], v[202:205], v[46:49]
	v_mfma_f32_16x16x32_bf16 v[42:45], v[160:163], v[202:205], v[42:45]
	v_mfma_f32_16x16x32_bf16 v[30:33], v[130:133], v[210:213], v[30:33]
	v_mfma_f32_16x16x32_bf16 v[26:29], v[160:163], v[210:213], v[26:29]
	v_mfma_f32_16x16x32_bf16 v[14:17], v[130:133], v[218:221], v[14:17]
	v_mfma_f32_16x16x32_bf16 v[10:13], v[160:163], v[218:221], v[10:13]
	v_mfma_f32_16x16x32_bf16 v[62:65], v[134:137], v[198:201], v[62:65]
	v_mfma_f32_16x16x32_bf16 v[58:61], v[164:167], v[198:201], v[58:61]
	v_mfma_f32_16x16x32_bf16 v[46:49], v[134:137], v[206:209], v[46:49]
	v_mfma_f32_16x16x32_bf16 v[42:45], v[164:167], v[206:209], v[42:45]
	v_mfma_f32_16x16x32_bf16 v[30:33], v[134:137], v[214:217], v[30:33]
	v_mfma_f32_16x16x32_bf16 v[26:29], v[164:167], v[214:217], v[26:29]
	v_mfma_f32_16x16x32_bf16 v[14:17], v[134:137], v[222:225], v[14:17]
	v_mfma_f32_16x16x32_bf16 v[10:13], v[164:167], v[222:225], v[10:13]
	s_setprio 0
	s_setprio 1
	v_mfma_f32_16x16x32_bf16 v[54:57], v[178:181], v[194:197], v[54:57]
	v_mfma_f32_16x16x32_bf16 v[50:53], v[186:189], v[194:197], v[50:53]
	v_mfma_f32_16x16x32_bf16 v[38:41], v[178:181], v[202:205], v[38:41]
	v_mfma_f32_16x16x32_bf16 v[34:37], v[186:189], v[202:205], v[34:37]
	v_mfma_f32_16x16x32_bf16 v[22:25], v[178:181], v[210:213], v[22:25]
	v_mfma_f32_16x16x32_bf16 v[18:21], v[186:189], v[210:213], v[18:21]
	v_mfma_f32_16x16x32_bf16 v[6:9], v[178:181], v[218:221], v[6:9]
	v_mfma_f32_16x16x32_bf16 v[2:5], v[186:189], v[218:221], v[2:5]
	v_mfma_f32_16x16x32_bf16 v[54:57], v[182:185], v[198:201], v[54:57]
	v_mfma_f32_16x16x32_bf16 v[50:53], v[190:193], v[198:201], v[50:53]
	v_mfma_f32_16x16x32_bf16 v[38:41], v[182:185], v[206:209], v[38:41]
	v_mfma_f32_16x16x32_bf16 v[34:37], v[190:193], v[206:209], v[34:37]
	v_mfma_f32_16x16x32_bf16 v[22:25], v[182:185], v[214:217], v[22:25]
	v_mfma_f32_16x16x32_bf16 v[18:21], v[190:193], v[214:217], v[18:21]
	v_mfma_f32_16x16x32_bf16 v[6:9], v[182:185], v[222:225], v[6:9]
	v_mfma_f32_16x16x32_bf16 v[2:5], v[190:193], v[222:225], v[2:5]
	s_setprio 0
	s_barrier
	s_add_i32 s66, 0, 0x18000
	v_add_u32_e32 v148, s66, v172
	s_add_i32 s67, 0, 0x1c000
	ds_read_b128 v[130:133], v148
	ds_read_b128 v[134:137], v148 offset:1024
	ds_read_b128 v[160:163], v148 offset:2048
	ds_read_b128 v[164:167], v148 offset:3072
	v_add_u32_e32 v148, s67, v172
	ds_read_b128 v[178:181], v148
	ds_read_b128 v[182:185], v148 offset:1024
	ds_read_b128 v[186:189], v148 offset:2048
	ds_read_b128 v[190:193], v148 offset:3072
	s_add_u32 s90, s90, 0xb0000
	s_addc_u32 s91, s91, 0
	s_mov_b32 m0, s54
	v_lshl_add_u64 v[232:233], s[90:91], 0, v[140:141]
	ds_read_b128 v[194:197], v176 offset:32768
	ds_read_b128 v[198:201], v176 offset:33792
	ds_read_b128 v[202:205], v176 offset:34816
	ds_read_b128 v[206:209], v176 offset:35840
	ds_read_b128 v[210:213], v176 offset:36864
	ds_read_b128 v[214:217], v176 offset:37888
	ds_read_b128 v[218:221], v176 offset:38912
	ds_read_b128 v[222:225], v176 offset:39936
	global_load_lds_dwordx4 v[232:233], off
	v_lshl_add_u64 v[232:233], s[90:91], 0, v[144:145]
	s_mov_b32 m0, s55
	s_nop 0
	global_load_lds_dwordx4 v[232:233], off
	s_waitcnt vmcnt(8)
	s_waitcnt lgkmcnt(0)
	s_barrier
	s_setprio 1
	s_waitcnt lgkmcnt(0)
	v_mfma_f32_16x16x32_bf16 v[126:129], v[130:133], v[194:197], v[126:129]
	v_mfma_f32_16x16x32_bf16 v[122:125], v[160:163], v[194:197], v[122:125]
	v_mfma_f32_16x16x32_bf16 v[110:113], v[130:133], v[202:205], v[110:113]
	v_mfma_f32_16x16x32_bf16 v[106:109], v[160:163], v[202:205], v[106:109]
	v_mfma_f32_16x16x32_bf16 v[94:97], v[130:133], v[210:213], v[94:97]
	v_mfma_f32_16x16x32_bf16 v[90:93], v[160:163], v[210:213], v[90:93]
	v_mfma_f32_16x16x32_bf16 v[78:81], v[130:133], v[218:221], v[78:81]
	v_mfma_f32_16x16x32_bf16 v[74:77], v[160:163], v[218:221], v[74:77]
	v_mfma_f32_16x16x32_bf16 v[126:129], v[134:137], v[198:201], v[126:129]
	v_mfma_f32_16x16x32_bf16 v[122:125], v[164:167], v[198:201], v[122:125]
	v_mfma_f32_16x16x32_bf16 v[110:113], v[134:137], v[206:209], v[110:113]
	v_mfma_f32_16x16x32_bf16 v[106:109], v[164:167], v[206:209], v[106:109]
	v_mfma_f32_16x16x32_bf16 v[94:97], v[134:137], v[214:217], v[94:97]
	v_mfma_f32_16x16x32_bf16 v[90:93], v[164:167], v[214:217], v[90:93]
	v_mfma_f32_16x16x32_bf16 v[78:81], v[134:137], v[222:225], v[78:81]
	v_mfma_f32_16x16x32_bf16 v[74:77], v[164:167], v[222:225], v[74:77]
	s_setprio 0
	s_setprio 1
	v_mfma_f32_16x16x32_bf16 v[118:121], v[178:181], v[194:197], v[118:121]
	v_mfma_f32_16x16x32_bf16 v[114:117], v[186:189], v[194:197], v[114:117]
	v_mfma_f32_16x16x32_bf16 v[102:105], v[178:181], v[202:205], v[102:105]
	v_mfma_f32_16x16x32_bf16 v[98:101], v[186:189], v[202:205], v[98:101]
	v_mfma_f32_16x16x32_bf16 v[86:89], v[178:181], v[210:213], v[86:89]
	v_mfma_f32_16x16x32_bf16 v[82:85], v[186:189], v[210:213], v[82:85]
	v_mfma_f32_16x16x32_bf16 v[70:73], v[178:181], v[218:221], v[70:73]
	v_mfma_f32_16x16x32_bf16 v[66:69], v[186:189], v[218:221], v[66:69]
	v_mfma_f32_16x16x32_bf16 v[118:121], v[182:185], v[198:201], v[118:121]
	v_mfma_f32_16x16x32_bf16 v[114:117], v[190:193], v[198:201], v[114:117]
	v_mfma_f32_16x16x32_bf16 v[102:105], v[182:185], v[206:209], v[102:105]
	v_mfma_f32_16x16x32_bf16 v[98:101], v[190:193], v[206:209], v[98:101]
	v_mfma_f32_16x16x32_bf16 v[86:89], v[182:185], v[214:217], v[86:89]
	v_mfma_f32_16x16x32_bf16 v[82:85], v[190:193], v[214:217], v[82:85]
	v_mfma_f32_16x16x32_bf16 v[70:73], v[182:185], v[222:225], v[70:73]
	v_mfma_f32_16x16x32_bf16 v[66:69], v[190:193], v[222:225], v[66:69]
	s_setprio 0
	s_barrier
	s_add_i32 s66, s66, s3
	v_lshl_add_u64 v[138:139], v[138:139], 0, s[18:19]
	s_mov_b32 m0, s66
	ds_read_b128 v[194:197], v176 offset:49152
	ds_read_b128 v[198:201], v176 offset:50176
	ds_read_b128 v[202:205], v176 offset:51200
	ds_read_b128 v[206:209], v176 offset:52224
	ds_read_b128 v[210:213], v176 offset:53248
	ds_read_b128 v[214:217], v176 offset:54272
	ds_read_b128 v[218:221], v176 offset:55296
	ds_read_b128 v[222:225], v176 offset:56320
	global_load_lds_dwordx4 v[138:139], off
	s_add_i32 m0, s66, 0x2000
	s_add_u32 s70, s70, 0xb0080
	v_lshl_add_u64 v[138:139], v[226:227], 0, s[18:19]
	s_addc_u32 s71, s71, 0
	s_add_i32 s66, s67, s3
	global_load_lds_dwordx4 v[138:139], off
	v_lshl_add_u64 v[138:139], s[70:71], 0, v[142:143]
	s_mov_b32 m0, s66
	s_nop 0
	global_load_lds_dwordx4 v[138:139], off
	v_lshl_add_u64 v[138:139], s[70:71], 0, v[146:147]
	s_add_i32 m0, s66, 0x2000
	s_nop 0
	global_load_lds_dwordx4 v[138:139], off
	v_lshl_add_u64 v[138:139], v[228:229], 0, s[18:19]
	s_mov_b32 m0, s58
	s_nop 0
	global_load_lds_dwordx4 v[138:139], off
	v_lshl_add_u64 v[138:139], v[230:231], 0, s[18:19]
	s_mov_b32 m0, s59
	s_nop 0
	global_load_lds_dwordx4 v[138:139], off
	s_waitcnt vmcnt(8)
	s_waitcnt lgkmcnt(0)
	s_barrier
	s_setprio 1
	s_waitcnt lgkmcnt(0)
	v_mfma_f32_16x16x32_bf16 v[62:65], v[130:133], v[194:197], v[62:65]
	v_mfma_f32_16x16x32_bf16 v[58:61], v[160:163], v[194:197], v[58:61]
	v_mfma_f32_16x16x32_bf16 v[46:49], v[130:133], v[202:205], v[46:49]
	v_mfma_f32_16x16x32_bf16 v[42:45], v[160:163], v[202:205], v[42:45]
	v_mfma_f32_16x16x32_bf16 v[30:33], v[130:133], v[210:213], v[30:33]
	v_mfma_f32_16x16x32_bf16 v[26:29], v[160:163], v[210:213], v[26:29]
	v_mfma_f32_16x16x32_bf16 v[14:17], v[130:133], v[218:221], v[14:17]
	v_mfma_f32_16x16x32_bf16 v[10:13], v[160:163], v[218:221], v[10:13]
	v_mfma_f32_16x16x32_bf16 v[62:65], v[134:137], v[198:201], v[62:65]
	v_mfma_f32_16x16x32_bf16 v[58:61], v[164:167], v[198:201], v[58:61]
	v_mfma_f32_16x16x32_bf16 v[46:49], v[134:137], v[206:209], v[46:49]
	v_mfma_f32_16x16x32_bf16 v[42:45], v[164:167], v[206:209], v[42:45]
	v_mfma_f32_16x16x32_bf16 v[30:33], v[134:137], v[214:217], v[30:33]
	v_mfma_f32_16x16x32_bf16 v[26:29], v[164:167], v[214:217], v[26:29]
	v_mfma_f32_16x16x32_bf16 v[14:17], v[134:137], v[222:225], v[14:17]
	v_mfma_f32_16x16x32_bf16 v[10:13], v[164:167], v[222:225], v[10:13]
	s_setprio 0
	s_setprio 1
	v_mfma_f32_16x16x32_bf16 v[54:57], v[178:181], v[194:197], v[54:57]
	v_mfma_f32_16x16x32_bf16 v[50:53], v[186:189], v[194:197], v[50:53]
	v_mfma_f32_16x16x32_bf16 v[38:41], v[178:181], v[202:205], v[38:41]
	v_mfma_f32_16x16x32_bf16 v[34:37], v[186:189], v[202:205], v[34:37]
	v_mfma_f32_16x16x32_bf16 v[22:25], v[178:181], v[210:213], v[22:25]
	v_mfma_f32_16x16x32_bf16 v[18:21], v[186:189], v[210:213], v[18:21]
	v_mfma_f32_16x16x32_bf16 v[6:9], v[178:181], v[218:221], v[6:9]
	v_mfma_f32_16x16x32_bf16 v[2:5], v[186:189], v[218:221], v[2:5]
	v_mfma_f32_16x16x32_bf16 v[54:57], v[182:185], v[198:201], v[54:57]
	v_mfma_f32_16x16x32_bf16 v[50:53], v[190:193], v[198:201], v[50:53]
	v_mfma_f32_16x16x32_bf16 v[38:41], v[182:185], v[206:209], v[38:41]
	v_mfma_f32_16x16x32_bf16 v[34:37], v[190:193], v[206:209], v[34:37]
	v_mfma_f32_16x16x32_bf16 v[22:25], v[182:185], v[214:217], v[22:25]
	v_mfma_f32_16x16x32_bf16 v[18:21], v[190:193], v[214:217], v[18:21]
	v_mfma_f32_16x16x32_bf16 v[6:9], v[182:185], v[222:225], v[6:9]
	v_mfma_f32_16x16x32_bf16 v[2:5], v[190:193], v[222:225], v[2:5]
	s_setprio 0
	s_add_i32 s96, s96, 2
	s_add_u32 s8, s8, 0x100
	s_addc_u32 s9, s9, 0
	s_add_u32 s53, s53, 0x100
	s_addc_u32 s95, s95, 0
	s_cmp_gt_u32 s96, 41
	s_barrier
	s_cbranch_scc0 .LBB0_918
	s_and_b64 vcc, exec, s[20:21]
	s_cbranch_vccz .LBB0_921
	s_barrier

.LBB0_1159:
	ds_read_b128 v[130:133], v184
	ds_read_b128 v[134:137], v184 offset:1024
	ds_read_b128 v[138:141], v184 offset:2048
	ds_read_b128 v[142:145], v184 offset:3072
	ds_read_b128 v[172:175], v185
	ds_read_b128 v[176:179], v185 offset:1024
	ds_read_b128 v[190:193], v185 offset:2048
	ds_read_b128 v[194:197], v185 offset:3072
	s_add_u32 s22, s8, 0xfffc0080
	s_addc_u32 s23, s9, -1
	s_cmp_eq_u32 s84, 12
	s_cselect_b32 vcc_hi, s56, s23
	s_cselect_b32 vcc_lo, s57, s22
	s_cselect_b32 s97, s58, s69
	s_cselect_b32 s96, s59, s63
	v_lshl_add_u64 v[180:181], s[8:9], 0, v[164:165]
	s_add_i32 m0, s55, 0xc000
	ds_read_b128 v[198:201], v186
	ds_read_b128 v[202:205], v186 offset:1024
	ds_read_b128 v[206:209], v186 offset:2048
	ds_read_b128 v[210:213], v186 offset:3072
	ds_read_b128 v[214:217], v186 offset:4096
	ds_read_b128 v[218:221], v186 offset:5120
	ds_read_b128 v[222:225], v186 offset:6144
	ds_read_b128 v[226:229], v186 offset:7168
	global_load_lds_dwordx4 v[180:181], off
	v_lshl_add_u64 v[180:181], s[8:9], 0, v[166:167]
	s_add_i32 m0, s55, 0xe000
	s_nop 0
	global_load_lds_dwordx4 v[180:181], off
	s_waitcnt vmcnt(8)
	s_waitcnt lgkmcnt(0)
	s_barrier
	s_setprio 1
	s_waitcnt lgkmcnt(0)
	v_mfma_f32_16x16x32_bf16 v[126:129], v[130:133], v[198:201], v[126:129]
	v_mfma_f32_16x16x32_bf16 v[122:125], v[138:141], v[198:201], v[122:125]
	v_mfma_f32_16x16x32_bf16 v[110:113], v[130:133], v[206:209], v[110:113]
	v_mfma_f32_16x16x32_bf16 v[106:109], v[138:141], v[206:209], v[106:109]
	v_mfma_f32_16x16x32_bf16 v[94:97], v[130:133], v[214:217], v[94:97]
	v_mfma_f32_16x16x32_bf16 v[90:93], v[138:141], v[214:217], v[90:93]
	v_mfma_f32_16x16x32_bf16 v[78:81], v[130:133], v[222:225], v[78:81]
	v_mfma_f32_16x16x32_bf16 v[74:77], v[138:141], v[222:225], v[74:77]
	v_mfma_f32_16x16x32_bf16 v[126:129], v[134:137], v[202:205], v[126:129]
	v_mfma_f32_16x16x32_bf16 v[122:125], v[142:145], v[202:205], v[122:125]
	v_mfma_f32_16x16x32_bf16 v[110:113], v[134:137], v[210:213], v[110:113]
	v_mfma_f32_16x16x32_bf16 v[106:109], v[142:145], v[210:213], v[106:109]
	v_mfma_f32_16x16x32_bf16 v[94:97], v[134:137], v[218:221], v[94:97]
	v_mfma_f32_16x16x32_bf16 v[90:93], v[142:145], v[218:221], v[90:93]
	v_mfma_f32_16x16x32_bf16 v[78:81], v[134:137], v[226:229], v[78:81]
	v_mfma_f32_16x16x32_bf16 v[74:77], v[142:145], v[226:229], v[74:77]
	s_setprio 0
	s_setprio 1
	v_mfma_f32_16x16x32_bf16 v[118:121], v[172:175], v[198:201], v[118:121]
	v_mfma_f32_16x16x32_bf16 v[114:117], v[190:193], v[198:201], v[114:117]
	v_mfma_f32_16x16x32_bf16 v[102:105], v[172:175], v[206:209], v[102:105]
	v_mfma_f32_16x16x32_bf16 v[98:101], v[190:193], v[206:209], v[98:101]
	v_mfma_f32_16x16x32_bf16 v[86:89], v[172:175], v[214:217], v[86:89]
	v_mfma_f32_16x16x32_bf16 v[82:85], v[190:193], v[214:217], v[82:85]
	v_mfma_f32_16x16x32_bf16 v[70:73], v[172:175], v[222:225], v[70:73]
	v_mfma_f32_16x16x32_bf16 v[66:69], v[190:193], v[222:225], v[66:69]
	v_mfma_f32_16x16x32_bf16 v[118:121], v[176:179], v[202:205], v[118:121]
	v_mfma_f32_16x16x32_bf16 v[114:117], v[194:197], v[202:205], v[114:117]
	v_mfma_f32_16x16x32_bf16 v[102:105], v[176:179], v[210:213], v[102:105]
	v_mfma_f32_16x16x32_bf16 v[98:101], v[194:197], v[210:213], v[98:101]
	v_mfma_f32_16x16x32_bf16 v[86:89], v[176:179], v[218:221], v[86:89]
	v_mfma_f32_16x16x32_bf16 v[82:85], v[194:197], v[218:221], v[82:85]
	v_mfma_f32_16x16x32_bf16 v[70:73], v[176:179], v[226:229], v[70:73]
	v_mfma_f32_16x16x32_bf16 v[66:69], v[194:197], v[226:229], v[66:69]
	s_setprio 0
	s_barrier
	s_add_i32 s22, s12, s35
	v_lshl_add_u64 v[180:181], s[96:97], 0, v[148:149]
	s_mov_b32 m0, s22
	ds_read_b128 v[198:201], v186 offset:16384
	ds_read_b128 v[202:205], v186 offset:17408
	ds_read_b128 v[206:209], v186 offset:18432
	ds_read_b128 v[210:213], v186 offset:19456
	ds_read_b128 v[214:217], v186 offset:20480
	ds_read_b128 v[218:221], v186 offset:21504
	ds_read_b128 v[222:225], v186 offset:22528
	ds_read_b128 v[226:229], v186 offset:23552
	global_load_lds_dwordx4 v[180:181], off
	s_add_i32 m0, s22, 0x2000
	s_add_u32 s22, s96, 0x40000
	v_lshl_add_u64 v[230:231], s[96:97], 0, v[152:153]
	s_addc_u32 s23, s97, 0
	s_add_i32 s66, s13, s35
	global_load_lds_dwordx4 v[230:231], off
	v_lshl_add_u64 v[232:233], s[22:23], 0, v[148:149]
	s_mov_b32 m0, s66
	v_lshl_add_u64 v[234:235], vcc, 0, v[150:151]
	global_load_lds_dwordx4 v[232:233], off
	v_lshl_add_u64 v[232:233], s[22:23], 0, v[152:153]
	s_add_i32 m0, s66, 0x2000
	s_nop 0
	global_load_lds_dwordx4 v[232:233], off
	v_lshl_add_u64 v[232:233], vcc, 0, v[146:147]
	s_mov_b32 m0, s55
	s_nop 0
	global_load_lds_dwordx4 v[232:233], off
	s_mov_b32 m0, s60
	s_nop 0
	global_load_lds_dwordx4 v[234:235], off
	s_waitcnt vmcnt(8)
	s_waitcnt lgkmcnt(0)
	s_barrier
	s_setprio 1
	s_waitcnt lgkmcnt(0)
	v_mfma_f32_16x16x32_bf16 v[62:65], v[130:133], v[198:201], v[62:65]
	v_mfma_f32_16x16x32_bf16 v[58:61], v[138:141], v[198:201], v[58:61]
	v_mfma_f32_16x16x32_bf16 v[46:49], v[130:133], v[206:209], v[46:49]
	v_mfma_f32_16x16x32_bf16 v[42:45], v[138:141], v[206:209], v[42:45]
	v_mfma_f32_16x16x32_bf16 v[30:33], v[130:133], v[214:217], v[30:33]
	v_mfma_f32_16x16x32_bf16 v[26:29], v[138:141], v[214:217], v[26:29]
	v_mfma_f32_16x16x32_bf16 v[14:17], v[130:133], v[222:225], v[14:17]
	v_mfma_f32_16x16x32_bf16 v[10:13], v[138:141], v[222:225], v[10:13]
	v_mfma_f32_16x16x32_bf16 v[62:65], v[134:137], v[202:205], v[62:65]
	v_mfma_f32_16x16x32_bf16 v[58:61], v[142:145], v[202:205], v[58:61]
	v_mfma_f32_16x16x32_bf16 v[46:49], v[134:137], v[210:213], v[46:49]
	v_mfma_f32_16x16x32_bf16 v[42:45], v[142:145], v[210:213], v[42:45]
	v_mfma_f32_16x16x32_bf16 v[30:33], v[134:137], v[218:221], v[30:33]
	v_mfma_f32_16x16x32_bf16 v[26:29], v[142:145], v[218:221], v[26:29]
	v_mfma_f32_16x16x32_bf16 v[14:17], v[134:137], v[226:229], v[14:17]
	v_mfma_f32_16x16x32_bf16 v[10:13], v[142:145], v[226:229], v[10:13]
	s_setprio 0
	s_setprio 1
	v_mfma_f32_16x16x32_bf16 v[54:57], v[172:175], v[198:201], v[54:57]
	v_mfma_f32_16x16x32_bf16 v[50:53], v[190:193], v[198:201], v[50:53]
	v_mfma_f32_16x16x32_bf16 v[38:41], v[172:175], v[206:209], v[38:41]
	v_mfma_f32_16x16x32_bf16 v[34:37], v[190:193], v[206:209], v[34:37]
	v_mfma_f32_16x16x32_bf16 v[22:25], v[172:175], v[214:217], v[22:25]
	v_mfma_f32_16x16x32_bf16 v[18:21], v[190:193], v[214:217], v[18:21]
	v_mfma_f32_16x16x32_bf16 v[6:9], v[172:175], v[222:225], v[6:9]
	v_mfma_f32_16x16x32_bf16 v[2:5], v[190:193], v[222:225], v[2:5]
	v_mfma_f32_16x16x32_bf16 v[54:57], v[176:179], v[202:205], v[54:57]
	v_mfma_f32_16x16x32_bf16 v[50:53], v[194:197], v[202:205], v[50:53]
	v_mfma_f32_16x16x32_bf16 v[38:41], v[176:179], v[210:213], v[38:41]
	v_mfma_f32_16x16x32_bf16 v[34:37], v[194:197], v[210:213], v[34:37]
	v_mfma_f32_16x16x32_bf16 v[22:25], v[176:179], v[218:221], v[22:25]
	v_mfma_f32_16x16x32_bf16 v[18:21], v[194:197], v[218:221], v[18:21]
	v_mfma_f32_16x16x32_bf16 v[6:9], v[176:179], v[226:229], v[6:9]
	v_mfma_f32_16x16x32_bf16 v[2:5], v[194:197], v[226:229], v[2:5]
	s_setprio 0
	s_barrier
	s_add_i32 s66, 0, 0x18000
	s_add_i32 s67, 0, 0x1c000
	v_add_u32_e32 v142, s66, v159
	v_add_u32_e32 v154, s67, v159
	ds_read_b128 v[130:133], v142
	ds_read_b128 v[134:137], v142 offset:1024
	ds_read_b128 v[138:141], v142 offset:2048
	ds_read_b128 v[142:145], v142 offset:3072
	ds_read_b128 v[172:175], v154
	ds_read_b128 v[176:179], v154 offset:1024
	ds_read_b128 v[190:193], v154 offset:2048
	ds_read_b128 v[194:197], v154 offset:3072
	s_add_u32 s22, vcc_lo, 0x40000
	s_addc_u32 s23, vcc_hi, 0
	s_mov_b32 m0, s61
	v_lshl_add_u64 v[236:237], s[22:23], 0, v[146:147]
	ds_read_b128 v[198:201], v186 offset:32768
	ds_read_b128 v[202:205], v186 offset:33792
	ds_read_b128 v[206:209], v186 offset:34816
	ds_read_b128 v[210:213], v186 offset:35840
	ds_read_b128 v[214:217], v186 offset:36864
	ds_read_b128 v[218:221], v186 offset:37888
	ds_read_b128 v[222:225], v186 offset:38912
	ds_read_b128 v[226:229], v186 offset:39936
	global_load_lds_dwordx4 v[236:237], off
	v_lshl_add_u64 v[236:237], s[22:23], 0, v[150:151]
	s_mov_b32 m0, s86
	s_nop 0
	global_load_lds_dwordx4 v[236:237], off
	s_waitcnt vmcnt(8)
	s_waitcnt lgkmcnt(0)
	s_barrier
	s_setprio 1
	s_waitcnt lgkmcnt(0)
	v_mfma_f32_16x16x32_bf16 v[126:129], v[130:133], v[198:201], v[126:129]
	v_mfma_f32_16x16x32_bf16 v[122:125], v[138:141], v[198:201], v[122:125]
	v_mfma_f32_16x16x32_bf16 v[110:113], v[130:133], v[206:209], v[110:113]
	v_mfma_f32_16x16x32_bf16 v[106:109], v[138:141], v[206:209], v[106:109]
	v_mfma_f32_16x16x32_bf16 v[94:97], v[130:133], v[214:217], v[94:97]
	v_mfma_f32_16x16x32_bf16 v[90:93], v[138:141], v[214:217], v[90:93]
	v_mfma_f32_16x16x32_bf16 v[78:81], v[130:133], v[222:225], v[78:81]
	v_mfma_f32_16x16x32_bf16 v[74:77], v[138:141], v[222:225], v[74:77]
	v_mfma_f32_16x16x32_bf16 v[126:129], v[134:137], v[202:205], v[126:129]
	v_mfma_f32_16x16x32_bf16 v[122:125], v[142:145], v[202:205], v[122:125]
	v_mfma_f32_16x16x32_bf16 v[110:113], v[134:137], v[210:213], v[110:113]
	v_mfma_f32_16x16x32_bf16 v[106:109], v[142:145], v[210:213], v[106:109]
	v_mfma_f32_16x16x32_bf16 v[94:97], v[134:137], v[218:221], v[94:97]
	v_mfma_f32_16x16x32_bf16 v[90:93], v[142:145], v[218:221], v[90:93]
	v_mfma_f32_16x16x32_bf16 v[78:81], v[134:137], v[226:229], v[78:81]
	v_mfma_f32_16x16x32_bf16 v[74:77], v[142:145], v[226:229], v[74:77]
	s_setprio 0
	s_setprio 1
	v_mfma_f32_16x16x32_bf16 v[118:121], v[172:175], v[198:201], v[118:121]
	v_mfma_f32_16x16x32_bf16 v[114:117], v[190:193], v[198:201], v[114:117]
	v_mfma_f32_16x16x32_bf16 v[102:105], v[172:175], v[206:209], v[102:105]
	v_mfma_f32_16x16x32_bf16 v[98:101], v[190:193], v[206:209], v[98:101]
	v_mfma_f32_16x16x32_bf16 v[86:89], v[172:175], v[214:217], v[86:89]
	v_mfma_f32_16x16x32_bf16 v[82:85], v[190:193], v[214:217], v[82:85]
	v_mfma_f32_16x16x32_bf16 v[70:73], v[172:175], v[222:225], v[70:73]
	v_mfma_f32_16x16x32_bf16 v[66:69], v[190:193], v[222:225], v[66:69]
	v_mfma_f32_16x16x32_bf16 v[118:121], v[176:179], v[202:205], v[118:121]
	v_mfma_f32_16x16x32_bf16 v[114:117], v[194:197], v[202:205], v[114:117]
	v_mfma_f32_16x16x32_bf16 v[102:105], v[176:179], v[210:213], v[102:105]
	v_mfma_f32_16x16x32_bf16 v[98:101], v[194:197], v[210:213], v[98:101]
	v_mfma_f32_16x16x32_bf16 v[86:89], v[176:179], v[218:221], v[86:89]
	v_mfma_f32_16x16x32_bf16 v[82:85], v[194:197], v[218:221], v[82:85]
	v_mfma_f32_16x16x32_bf16 v[70:73], v[176:179], v[226:229], v[70:73]
	v_mfma_f32_16x16x32_bf16 v[66:69], v[194:197], v[226:229], v[66:69]
	s_setprio 0
	s_barrier
	s_add_i32 s22, s66, s35
	v_lshl_add_u64 v[180:181], v[180:181], 0, s[14:15]
	s_mov_b32 m0, s22
	ds_read_b128 v[198:201], v186 offset:49152
	ds_read_b128 v[202:205], v186 offset:50176
	ds_read_b128 v[206:209], v186 offset:51200
	ds_read_b128 v[210:213], v186 offset:52224
	ds_read_b128 v[214:217], v186 offset:53248
	ds_read_b128 v[218:221], v186 offset:54272
	ds_read_b128 v[222:225], v186 offset:55296
	ds_read_b128 v[226:229], v186 offset:56320
	global_load_lds_dwordx4 v[180:181], off
	s_add_i32 m0, s22, 0x2000
	s_add_u32 s22, s96, 0x40080
	v_lshl_add_u64 v[180:181], v[230:231], 0, s[14:15]
	s_addc_u32 s23, s97, 0
	s_add_i32 s66, s67, s35
	global_load_lds_dwordx4 v[180:181], off
	v_lshl_add_u64 v[180:181], s[22:23], 0, v[148:149]
	s_mov_b32 m0, s66
	s_nop 0
	global_load_lds_dwordx4 v[180:181], off
	v_lshl_add_u64 v[180:181], s[22:23], 0, v[152:153]
	s_add_i32 m0, s66, 0x2000
	s_nop 0
	global_load_lds_dwordx4 v[180:181], off
	v_lshl_add_u64 v[180:181], v[232:233], 0, s[14:15]
	s_mov_b32 m0, s53
	s_nop 0
	global_load_lds_dwordx4 v[180:181], off
	v_lshl_add_u64 v[180:181], v[234:235], 0, s[14:15]
	s_mov_b32 m0, s54
	s_nop 0
	global_load_lds_dwordx4 v[180:181], off
	s_waitcnt vmcnt(8)
	s_waitcnt lgkmcnt(0)
	s_barrier
	s_setprio 1
	s_waitcnt lgkmcnt(0)
	v_mfma_f32_16x16x32_bf16 v[62:65], v[130:133], v[198:201], v[62:65]
	v_mfma_f32_16x16x32_bf16 v[58:61], v[138:141], v[198:201], v[58:61]
	v_mfma_f32_16x16x32_bf16 v[46:49], v[130:133], v[206:209], v[46:49]
	v_mfma_f32_16x16x32_bf16 v[42:45], v[138:141], v[206:209], v[42:45]
	v_mfma_f32_16x16x32_bf16 v[30:33], v[130:133], v[214:217], v[30:33]
	v_mfma_f32_16x16x32_bf16 v[26:29], v[138:141], v[214:217], v[26:29]
	v_mfma_f32_16x16x32_bf16 v[14:17], v[130:133], v[222:225], v[14:17]
	v_mfma_f32_16x16x32_bf16 v[10:13], v[138:141], v[222:225], v[10:13]
	v_mfma_f32_16x16x32_bf16 v[62:65], v[134:137], v[202:205], v[62:65]
	v_mfma_f32_16x16x32_bf16 v[58:61], v[142:145], v[202:205], v[58:61]
	v_mfma_f32_16x16x32_bf16 v[46:49], v[134:137], v[210:213], v[46:49]
	v_mfma_f32_16x16x32_bf16 v[42:45], v[142:145], v[210:213], v[42:45]
	v_mfma_f32_16x16x32_bf16 v[30:33], v[134:137], v[218:221], v[30:33]
	v_mfma_f32_16x16x32_bf16 v[26:29], v[142:145], v[218:221], v[26:29]
	v_mfma_f32_16x16x32_bf16 v[14:17], v[134:137], v[226:229], v[14:17]
	v_mfma_f32_16x16x32_bf16 v[10:13], v[142:145], v[226:229], v[10:13]
	s_setprio 0
	s_setprio 1
	v_mfma_f32_16x16x32_bf16 v[54:57], v[172:175], v[198:201], v[54:57]
	v_mfma_f32_16x16x32_bf16 v[50:53], v[190:193], v[198:201], v[50:53]
	v_mfma_f32_16x16x32_bf16 v[38:41], v[172:175], v[206:209], v[38:41]
	v_mfma_f32_16x16x32_bf16 v[34:37], v[190:193], v[206:209], v[34:37]
	v_mfma_f32_16x16x32_bf16 v[22:25], v[172:175], v[214:217], v[22:25]
	v_mfma_f32_16x16x32_bf16 v[18:21], v[190:193], v[214:217], v[18:21]
	v_mfma_f32_16x16x32_bf16 v[6:9], v[172:175], v[222:225], v[6:9]
	v_mfma_f32_16x16x32_bf16 v[2:5], v[190:193], v[222:225], v[2:5]
	v_mfma_f32_16x16x32_bf16 v[54:57], v[176:179], v[202:205], v[54:57]
	v_mfma_f32_16x16x32_bf16 v[50:53], v[194:197], v[202:205], v[50:53]
	v_mfma_f32_16x16x32_bf16 v[38:41], v[176:179], v[210:213], v[38:41]
	v_mfma_f32_16x16x32_bf16 v[34:37], v[194:197], v[210:213], v[34:37]
	v_mfma_f32_16x16x32_bf16 v[22:25], v[176:179], v[218:221], v[22:25]
	v_mfma_f32_16x16x32_bf16 v[18:21], v[194:197], v[218:221], v[18:21]
	v_mfma_f32_16x16x32_bf16 v[6:9], v[176:179], v[226:229], v[6:9]
	v_mfma_f32_16x16x32_bf16 v[2:5], v[194:197], v[226:229], v[2:5]
	s_setprio 0
	s_add_i32 s84, s84, 2
	s_add_u32 s8, s8, 0x100
	s_addc_u32 s9, s9, 0
	s_add_u32 s63, s63, 0x100
	s_addc_u32 s69, s69, 0
	s_cmp_gt_u32 s84, 13
	s_barrier
	s_cbranch_scc0 .LBB0_1159
	s_and_b64 vcc, exec, s[16:17]
	s_cbranch_vccnz .LBB0_1164
	s_cmp_gt_i32 s92, 11
	s_mov_b64 s[8:9], -1
	s_cbranch_scc1 .LBB0_1165

.LBB0_1379:
	s_waitcnt lgkmcnt(0)
	s_cmpk_lg_u32 s60, 0x800
	s_cbranch_scc1 .Lp4_orig
	s_cmpk_gt_i32 s3, 0x7ff
	s_cbranch_scc1 .LBB0_1779
	s_cmp_lt_u32 s61, 4
	s_cbranch_scc1 .Lp4_a
	s_cmp_eq_u32 s61, 4
	s_cbranch_scc0 .LBB0_1779
	s_cmpk_ge_u32 s2, 0x40
	s_cbranch_scc1 .LBB0_1779
	s_add_i32 s3, s2, 0xc00
	s_branch .LBB0_1380
.Lp4_a:
	s_lshl_b32 s0, s2, 2
	s_add_i32 s0, s0, s61
	s_add_i32 s3, s0, 0x800
	s_branch .LBB0_1380
.Lp4_orig:
	s_add_i32 s3, s3, s60
	s_cmpk_lt_i32 s3, 0xc40
	s_cbranch_scc0 .LBB0_1779
.LBB0_1380:
	s_cmpk_gt_i32 s3, 0x7ff
	s_mov_b64 s[4:5], -1
	s_cbranch_scc0 .LBB0_1382
	s_add_i32 s0, s3, 0xfffff800
	s_lshr_b32 s0, s0, 3
	s_mulk_i32 s0, 0x108
	s_and_b32 s1, s3, 7
	s_or_b32 s0, s0, s1
	s_cmpk_lt_u32 s3, 0x840
	s_cselect_b32 s0, s0, s3
	s_mov_b64 s[4:5], 0

.LBB0_2600:
	s_or_b64 exec, exec, s[10:11]
	v_cvt_f32_u32_e32 v5, v3
	s_waitcnt vmcnt(0)
	v_readfirstlane_b32 s3, v4
	v_sub_u32_e32 v4, 0, v3
	v_rcp_iflag_f32_e32 v5, v5
	v_add_u32_e32 v6, s3, v2
	v_mul_f32_e32 v5, 0x4f7ffffe, v5
	v_cvt_u32_f32_e32 v5, v5
	v_mul_lo_u32 v2, v4, v5
	v_mul_hi_u32 v2, v5, v2
	v_add_u32_e32 v2, v5, v2
	v_mul_hi_u32 v2, v6, v2
	v_mul_lo_u32 v4, v2, v3
	v_sub_u32_e32 v4, v6, v4
	v_add_u32_e32 v5, 1, v2
	v_cmp_ge_u32_e32 vcc, v4, v3
	s_nop 1
	v_cndmask_b32_e32 v2, v2, v5, vcc
	v_sub_u32_e32 v5, v4, v3
	v_cndmask_b32_e32 v4, v4, v5, vcc
	v_add_u32_e32 v5, 1, v2
	v_cmp_ge_u32_e32 vcc, v4, v3
	v_add_u32_e32 v4, 1, v6
	s_nop 0
	v_cndmask_b32_e32 v2, v2, v5, vcc
	v_mul_lo_u32 v5, v3, v2
	v_add_u32_e32 v3, v5, v3
	v_cmp_ne_u32_e32 vcc, v4, v3
	s_and_saveexec_b64 s[8:9], vcc
	s_xor_b64 s[8:9], exec, s[8:9]
	s_cbranch_execz .LBB0_2614
	s_waitcnt lgkmcnt(0)
	s_add_u32 s16, s28, 0xf190900
	s_addc_u32 s17, s29, 0
	v_mov_b32_e32 v1, 0
	global_load_dword v1, v1, s[16:17] sc1
	s_waitcnt vmcnt(0)
	v_cmp_eq_u32_e32 vcc, v1, v2
	s_and_saveexec_b64 s[10:11], vcc
	s_cbranch_execz .LBB0_2613
	s_add_u32 s12, s28, 0xf18d600
	s_addc_u32 s13, s29, 0
	s_mov_b32 s3, 1
	s_mov_b64 s[18:19], 0
	v_mov_b32_e32 v1, 0
	s_branch .LBB0_2604

.LBB0_2648:
	ds_read_b128 v[150:153], v167
	ds_read_b128 v[154:157], v167 offset:1024
	ds_read_b128 v[158:161], v167 offset:2048
	ds_read_b128 v[172:175], v167 offset:3072
	ds_read_b128 v[176:179], v168
	ds_read_b128 v[180:183], v168 offset:1024
	ds_read_b128 v[184:187], v168 offset:2048
	ds_read_b128 v[188:191], v168 offset:3072
	s_add_u32 s50, s48, 0xfffc0080
	s_addc_u32 s51, s49, -1
	s_cmp_eq_u32 s81, 12
	s_cselect_b32 s53, s7, s51
	s_cselect_b32 s52, s9, s50
	s_cselect_b32 s51, s41, s80
	s_cselect_b32 s50, s43, s79
	v_lshl_add_u64 v[162:163], s[48:49], 0, v[142:143]
	s_add_i32 m0, s54, 0xc000
	ds_read_b128 v[192:195], v169
	ds_read_b128 v[196:199], v169 offset:1024
	ds_read_b128 v[200:203], v169 offset:2048
	ds_read_b128 v[204:207], v169 offset:3072
	ds_read_b128 v[208:211], v169 offset:4096
	ds_read_b128 v[212:215], v169 offset:5120
	ds_read_b128 v[216:219], v169 offset:6144
	ds_read_b128 v[220:223], v169 offset:7168
	global_load_lds_dwordx4 v[162:163], off
	v_lshl_add_u64 v[162:163], s[48:49], 0, v[144:145]
	s_add_i32 m0, s54, 0xe000
	s_nop 0
	global_load_lds_dwordx4 v[162:163], off
	s_waitcnt vmcnt(8)
	s_waitcnt lgkmcnt(0)
	s_barrier
	s_setprio 1
	s_waitcnt lgkmcnt(0)
	v_mfma_f32_16x16x32_bf16 v[126:129], v[150:153], v[192:195], v[126:129]
	v_mfma_f32_16x16x32_bf16 v[122:125], v[158:161], v[192:195], v[122:125]
	v_mfma_f32_16x16x32_bf16 v[110:113], v[150:153], v[200:203], v[110:113]
	v_mfma_f32_16x16x32_bf16 v[106:109], v[158:161], v[200:203], v[106:109]
	v_mfma_f32_16x16x32_bf16 v[94:97], v[150:153], v[208:211], v[94:97]
	v_mfma_f32_16x16x32_bf16 v[90:93], v[158:161], v[208:211], v[90:93]
	v_mfma_f32_16x16x32_bf16 v[78:81], v[150:153], v[216:219], v[78:81]
	v_mfma_f32_16x16x32_bf16 v[74:77], v[158:161], v[216:219], v[74:77]
	v_mfma_f32_16x16x32_bf16 v[126:129], v[154:157], v[196:199], v[126:129]
	v_mfma_f32_16x16x32_bf16 v[122:125], v[172:175], v[196:199], v[122:125]
	v_mfma_f32_16x16x32_bf16 v[110:113], v[154:157], v[204:207], v[110:113]
	v_mfma_f32_16x16x32_bf16 v[106:109], v[172:175], v[204:207], v[106:109]
	v_mfma_f32_16x16x32_bf16 v[94:97], v[154:157], v[212:215], v[94:97]
	v_mfma_f32_16x16x32_bf16 v[90:93], v[172:175], v[212:215], v[90:93]
	v_mfma_f32_16x16x32_bf16 v[78:81], v[154:157], v[220:223], v[78:81]
	v_mfma_f32_16x16x32_bf16 v[74:77], v[172:175], v[220:223], v[74:77]
	s_setprio 0
	s_setprio 1
	v_mfma_f32_16x16x32_bf16 v[118:121], v[176:179], v[192:195], v[118:121]
	v_mfma_f32_16x16x32_bf16 v[114:117], v[184:187], v[192:195], v[114:117]
	v_mfma_f32_16x16x32_bf16 v[102:105], v[176:179], v[200:203], v[102:105]
	v_mfma_f32_16x16x32_bf16 v[98:101], v[184:187], v[200:203], v[98:101]
	v_mfma_f32_16x16x32_bf16 v[86:89], v[176:179], v[208:211], v[86:89]
	v_mfma_f32_16x16x32_bf16 v[82:85], v[184:187], v[208:211], v[82:85]
	v_mfma_f32_16x16x32_bf16 v[70:73], v[176:179], v[216:219], v[70:73]
	v_mfma_f32_16x16x32_bf16 v[66:69], v[184:187], v[216:219], v[66:69]
	v_mfma_f32_16x16x32_bf16 v[118:121], v[180:183], v[196:199], v[118:121]
	v_mfma_f32_16x16x32_bf16 v[114:117], v[188:191], v[196:199], v[114:117]
	v_mfma_f32_16x16x32_bf16 v[102:105], v[180:183], v[204:207], v[102:105]
	v_mfma_f32_16x16x32_bf16 v[98:101], v[188:191], v[204:207], v[98:101]
	v_mfma_f32_16x16x32_bf16 v[86:89], v[180:183], v[212:215], v[86:89]
	v_mfma_f32_16x16x32_bf16 v[82:85], v[188:191], v[212:215], v[82:85]
	v_mfma_f32_16x16x32_bf16 v[70:73], v[180:183], v[220:223], v[70:73]
	v_mfma_f32_16x16x32_bf16 v[66:69], v[188:191], v[220:223], v[66:69]
	s_setprio 0
	s_barrier
	s_add_i32 s66, s72, s35
	v_lshl_add_u64 v[162:163], s[50:51], 0, v[132:133]
	s_mov_b32 m0, s66
	ds_read_b128 v[192:195], v169 offset:16384
	ds_read_b128 v[196:199], v169 offset:17408
	ds_read_b128 v[200:203], v169 offset:18432
	ds_read_b128 v[204:207], v169 offset:19456
	ds_read_b128 v[208:211], v169 offset:20480
	ds_read_b128 v[212:215], v169 offset:21504
	ds_read_b128 v[216:219], v169 offset:22528
	ds_read_b128 v[220:223], v169 offset:23552
	global_load_lds_dwordx4 v[162:163], off
	s_add_i32 m0, s66, 0x2000
	s_add_u32 s66, s50, 0x40000
	v_lshl_add_u64 v[224:225], s[50:51], 0, v[136:137]
	s_addc_u32 s67, s51, 0
	s_add_i32 s82, s73, s35
	global_load_lds_dwordx4 v[224:225], off
	v_lshl_add_u64 v[226:227], s[66:67], 0, v[132:133]
	s_mov_b32 m0, s82
	v_lshl_add_u64 v[228:229], s[52:53], 0, v[134:135]
	global_load_lds_dwordx4 v[226:227], off
	v_lshl_add_u64 v[226:227], s[66:67], 0, v[136:137]
	s_add_i32 m0, s82, 0x2000
	s_nop 0
	global_load_lds_dwordx4 v[226:227], off
	v_lshl_add_u64 v[226:227], s[52:53], 0, v[130:131]
	s_mov_b32 m0, s54
	s_nop 0
	global_load_lds_dwordx4 v[226:227], off
	s_mov_b32 m0, s55
	s_nop 0
	global_load_lds_dwordx4 v[228:229], off
	s_waitcnt vmcnt(8)
	s_waitcnt lgkmcnt(0)
	s_barrier
	s_setprio 1
	s_waitcnt lgkmcnt(0)
	v_mfma_f32_16x16x32_bf16 v[62:65], v[150:153], v[192:195], v[62:65]
	v_mfma_f32_16x16x32_bf16 v[58:61], v[158:161], v[192:195], v[58:61]
	v_mfma_f32_16x16x32_bf16 v[46:49], v[150:153], v[200:203], v[46:49]
	v_mfma_f32_16x16x32_bf16 v[42:45], v[158:161], v[200:203], v[42:45]
	v_mfma_f32_16x16x32_bf16 v[30:33], v[150:153], v[208:211], v[30:33]
	v_mfma_f32_16x16x32_bf16 v[26:29], v[158:161], v[208:211], v[26:29]
	v_mfma_f32_16x16x32_bf16 v[14:17], v[150:153], v[216:219], v[14:17]
	v_mfma_f32_16x16x32_bf16 v[10:13], v[158:161], v[216:219], v[10:13]
	v_mfma_f32_16x16x32_bf16 v[62:65], v[154:157], v[196:199], v[62:65]
	v_mfma_f32_16x16x32_bf16 v[58:61], v[172:175], v[196:199], v[58:61]
	v_mfma_f32_16x16x32_bf16 v[46:49], v[154:157], v[204:207], v[46:49]
	v_mfma_f32_16x16x32_bf16 v[42:45], v[172:175], v[204:207], v[42:45]
	v_mfma_f32_16x16x32_bf16 v[30:33], v[154:157], v[212:215], v[30:33]
	v_mfma_f32_16x16x32_bf16 v[26:29], v[172:175], v[212:215], v[26:29]
	v_mfma_f32_16x16x32_bf16 v[14:17], v[154:157], v[220:223], v[14:17]
	v_mfma_f32_16x16x32_bf16 v[10:13], v[172:175], v[220:223], v[10:13]
	s_setprio 0
	s_setprio 1
	v_mfma_f32_16x16x32_bf16 v[54:57], v[176:179], v[192:195], v[54:57]
	v_mfma_f32_16x16x32_bf16 v[50:53], v[184:187], v[192:195], v[50:53]
	v_mfma_f32_16x16x32_bf16 v[38:41], v[176:179], v[200:203], v[38:41]
	v_mfma_f32_16x16x32_bf16 v[34:37], v[184:187], v[200:203], v[34:37]
	v_mfma_f32_16x16x32_bf16 v[22:25], v[176:179], v[208:211], v[22:25]
	v_mfma_f32_16x16x32_bf16 v[18:21], v[184:187], v[208:211], v[18:21]
	v_mfma_f32_16x16x32_bf16 v[6:9], v[176:179], v[216:219], v[6:9]
	v_mfma_f32_16x16x32_bf16 v[2:5], v[184:187], v[216:219], v[2:5]
	v_mfma_f32_16x16x32_bf16 v[54:57], v[180:183], v[196:199], v[54:57]
	v_mfma_f32_16x16x32_bf16 v[50:53], v[188:191], v[196:199], v[50:53]
	v_mfma_f32_16x16x32_bf16 v[38:41], v[180:183], v[204:207], v[38:41]
	v_mfma_f32_16x16x32_bf16 v[34:37], v[188:191], v[204:207], v[34:37]
	v_mfma_f32_16x16x32_bf16 v[22:25], v[180:183], v[212:215], v[22:25]
	v_mfma_f32_16x16x32_bf16 v[18:21], v[188:191], v[212:215], v[18:21]
	v_mfma_f32_16x16x32_bf16 v[6:9], v[180:183], v[220:223], v[6:9]
	v_mfma_f32_16x16x32_bf16 v[2:5], v[188:191], v[220:223], v[2:5]
	s_setprio 0
	s_barrier
	s_add_i32 s66, 0, 0x18000
	v_add_u32_e32 v138, s66, v164
	s_add_i32 s67, 0, 0x1c000
	ds_read_b128 v[150:153], v138
	ds_read_b128 v[154:157], v138 offset:1024
	ds_read_b128 v[158:161], v138 offset:2048
	ds_read_b128 v[172:175], v138 offset:3072
	v_add_u32_e32 v138, s67, v164
	ds_read_b128 v[176:179], v138
	ds_read_b128 v[180:183], v138 offset:1024
	ds_read_b128 v[184:187], v138 offset:2048
	ds_read_b128 v[188:191], v138 offset:3072
	s_add_u32 s52, s52, 0x40000
	s_addc_u32 s53, s53, 0
	s_mov_b32 m0, s56
	v_lshl_add_u64 v[230:231], s[52:53], 0, v[130:131]
	ds_read_b128 v[192:195], v169 offset:32768
	ds_read_b128 v[196:199], v169 offset:33792
	ds_read_b128 v[200:203], v169 offset:34816
	ds_read_b128 v[204:207], v169 offset:35840
	ds_read_b128 v[208:211], v169 offset:36864
	ds_read_b128 v[212:215], v169 offset:37888
	ds_read_b128 v[216:219], v169 offset:38912
	ds_read_b128 v[220:223], v169 offset:39936
	global_load_lds_dwordx4 v[230:231], off
	v_lshl_add_u64 v[230:231], s[52:53], 0, v[134:135]
	s_mov_b32 m0, s57
	s_nop 0
	global_load_lds_dwordx4 v[230:231], off
	s_waitcnt vmcnt(8)
	s_waitcnt lgkmcnt(0)
	s_barrier
	s_setprio 1
	s_waitcnt lgkmcnt(0)
	v_mfma_f32_16x16x32_bf16 v[126:129], v[150:153], v[192:195], v[126:129]
	v_mfma_f32_16x16x32_bf16 v[122:125], v[158:161], v[192:195], v[122:125]
	v_mfma_f32_16x16x32_bf16 v[110:113], v[150:153], v[200:203], v[110:113]
	v_mfma_f32_16x16x32_bf16 v[106:109], v[158:161], v[200:203], v[106:109]
	v_mfma_f32_16x16x32_bf16 v[94:97], v[150:153], v[208:211], v[94:97]
	v_mfma_f32_16x16x32_bf16 v[90:93], v[158:161], v[208:211], v[90:93]
	v_mfma_f32_16x16x32_bf16 v[78:81], v[150:153], v[216:219], v[78:81]
	v_mfma_f32_16x16x32_bf16 v[74:77], v[158:161], v[216:219], v[74:77]
	v_mfma_f32_16x16x32_bf16 v[126:129], v[154:157], v[196:199], v[126:129]
	v_mfma_f32_16x16x32_bf16 v[122:125], v[172:175], v[196:199], v[122:125]
	v_mfma_f32_16x16x32_bf16 v[110:113], v[154:157], v[204:207], v[110:113]
	v_mfma_f32_16x16x32_bf16 v[106:109], v[172:175], v[204:207], v[106:109]
	v_mfma_f32_16x16x32_bf16 v[94:97], v[154:157], v[212:215], v[94:97]
	v_mfma_f32_16x16x32_bf16 v[90:93], v[172:175], v[212:215], v[90:93]
	v_mfma_f32_16x16x32_bf16 v[78:81], v[154:157], v[220:223], v[78:81]
	v_mfma_f32_16x16x32_bf16 v[74:77], v[172:175], v[220:223], v[74:77]
	s_setprio 0
	s_setprio 1
	v_mfma_f32_16x16x32_bf16 v[118:121], v[176:179], v[192:195], v[118:121]
	v_mfma_f32_16x16x32_bf16 v[114:117], v[184:187], v[192:195], v[114:117]
	v_mfma_f32_16x16x32_bf16 v[102:105], v[176:179], v[200:203], v[102:105]
	v_mfma_f32_16x16x32_bf16 v[98:101], v[184:187], v[200:203], v[98:101]
	v_mfma_f32_16x16x32_bf16 v[86:89], v[176:179], v[208:211], v[86:89]
	v_mfma_f32_16x16x32_bf16 v[82:85], v[184:187], v[208:211], v[82:85]
	v_mfma_f32_16x16x32_bf16 v[70:73], v[176:179], v[216:219], v[70:73]
	v_mfma_f32_16x16x32_bf16 v[66:69], v[184:187], v[216:219], v[66:69]
	v_mfma_f32_16x16x32_bf16 v[118:121], v[180:183], v[196:199], v[118:121]
	v_mfma_f32_16x16x32_bf16 v[114:117], v[188:191], v[196:199], v[114:117]
	v_mfma_f32_16x16x32_bf16 v[102:105], v[180:183], v[204:207], v[102:105]
	v_mfma_f32_16x16x32_bf16 v[98:101], v[188:191], v[204:207], v[98:101]
	v_mfma_f32_16x16x32_bf16 v[86:89], v[180:183], v[212:215], v[86:89]
	v_mfma_f32_16x16x32_bf16 v[82:85], v[188:191], v[212:215], v[82:85]
	v_mfma_f32_16x16x32_bf16 v[70:73], v[180:183], v[220:223], v[70:73]
	v_mfma_f32_16x16x32_bf16 v[66:69], v[188:191], v[220:223], v[66:69]
	s_setprio 0
	s_barrier
	s_add_i32 s52, s66, s35
	v_lshl_add_u64 v[162:163], v[162:163], 0, s[16:17]
	s_mov_b32 m0, s52
	ds_read_b128 v[192:195], v169 offset:49152
	ds_read_b128 v[196:199], v169 offset:50176
	ds_read_b128 v[200:203], v169 offset:51200
	ds_read_b128 v[204:207], v169 offset:52224
	ds_read_b128 v[208:211], v169 offset:53248
	ds_read_b128 v[212:215], v169 offset:54272
	ds_read_b128 v[216:219], v169 offset:55296
	ds_read_b128 v[220:223], v169 offset:56320
	global_load_lds_dwordx4 v[162:163], off
	s_add_i32 m0, s52, 0x2000
	s_add_u32 s50, s50, 0x40080
	v_lshl_add_u64 v[162:163], v[224:225], 0, s[16:17]
	s_addc_u32 s51, s51, 0
	s_add_i32 s52, s67, s35
	global_load_lds_dwordx4 v[162:163], off
	v_lshl_add_u64 v[162:163], s[50:51], 0, v[132:133]
	s_mov_b32 m0, s52
	s_nop 0
	global_load_lds_dwordx4 v[162:163], off
	v_lshl_add_u64 v[162:163], s[50:51], 0, v[136:137]
	s_add_i32 m0, s52, 0x2000
	s_nop 0
	global_load_lds_dwordx4 v[162:163], off
	v_lshl_add_u64 v[162:163], v[226:227], 0, s[16:17]
	s_mov_b32 m0, s61
	s_nop 0
	global_load_lds_dwordx4 v[162:163], off
	v_lshl_add_u64 v[162:163], v[228:229], 0, s[16:17]
	s_mov_b32 m0, s68
	s_nop 0
	global_load_lds_dwordx4 v[162:163], off
	s_waitcnt vmcnt(8)
	s_waitcnt lgkmcnt(0)
	s_barrier
	s_setprio 1
	s_waitcnt lgkmcnt(0)
	v_mfma_f32_16x16x32_bf16 v[62:65], v[150:153], v[192:195], v[62:65]
	v_mfma_f32_16x16x32_bf16 v[58:61], v[158:161], v[192:195], v[58:61]
	v_mfma_f32_16x16x32_bf16 v[46:49], v[150:153], v[200:203], v[46:49]
	v_mfma_f32_16x16x32_bf16 v[42:45], v[158:161], v[200:203], v[42:45]
	v_mfma_f32_16x16x32_bf16 v[30:33], v[150:153], v[208:211], v[30:33]
	v_mfma_f32_16x16x32_bf16 v[26:29], v[158:161], v[208:211], v[26:29]
	v_mfma_f32_16x16x32_bf16 v[14:17], v[150:153], v[216:219], v[14:17]
	v_mfma_f32_16x16x32_bf16 v[10:13], v[158:161], v[216:219], v[10:13]
	v_mfma_f32_16x16x32_bf16 v[62:65], v[154:157], v[196:199], v[62:65]
	v_mfma_f32_16x16x32_bf16 v[58:61], v[172:175], v[196:199], v[58:61]
	v_mfma_f32_16x16x32_bf16 v[46:49], v[154:157], v[204:207], v[46:49]
	v_mfma_f32_16x16x32_bf16 v[42:45], v[172:175], v[204:207], v[42:45]
	v_mfma_f32_16x16x32_bf16 v[30:33], v[154:157], v[212:215], v[30:33]
	v_mfma_f32_16x16x32_bf16 v[26:29], v[172:175], v[212:215], v[26:29]
	v_mfma_f32_16x16x32_bf16 v[14:17], v[154:157], v[220:223], v[14:17]
	v_mfma_f32_16x16x32_bf16 v[10:13], v[172:175], v[220:223], v[10:13]
	s_setprio 0
	s_setprio 1
	v_mfma_f32_16x16x32_bf16 v[54:57], v[176:179], v[192:195], v[54:57]
	v_mfma_f32_16x16x32_bf16 v[50:53], v[184:187], v[192:195], v[50:53]
	v_mfma_f32_16x16x32_bf16 v[38:41], v[176:179], v[200:203], v[38:41]
	v_mfma_f32_16x16x32_bf16 v[34:37], v[184:187], v[200:203], v[34:37]
	v_mfma_f32_16x16x32_bf16 v[22:25], v[176:179], v[208:211], v[22:25]
	v_mfma_f32_16x16x32_bf16 v[18:21], v[184:187], v[208:211], v[18:21]
	v_mfma_f32_16x16x32_bf16 v[6:9], v[176:179], v[216:219], v[6:9]
	v_mfma_f32_16x16x32_bf16 v[2:5], v[184:187], v[216:219], v[2:5]
	v_mfma_f32_16x16x32_bf16 v[54:57], v[180:183], v[196:199], v[54:57]
	v_mfma_f32_16x16x32_bf16 v[50:53], v[188:191], v[196:199], v[50:53]
	v_mfma_f32_16x16x32_bf16 v[38:41], v[180:183], v[204:207], v[38:41]
	v_mfma_f32_16x16x32_bf16 v[34:37], v[188:191], v[204:207], v[34:37]
	v_mfma_f32_16x16x32_bf16 v[22:25], v[180:183], v[212:215], v[22:25]
	v_mfma_f32_16x16x32_bf16 v[18:21], v[188:191], v[212:215], v[18:21]
	v_mfma_f32_16x16x32_bf16 v[6:9], v[180:183], v[220:223], v[6:9]
	v_mfma_f32_16x16x32_bf16 v[2:5], v[188:191], v[220:223], v[2:5]
	s_setprio 0
	s_add_i32 s81, s81, 2
	s_add_u32 s48, s48, 0x100
	s_addc_u32 s49, s49, 0
	s_add_u32 s79, s79, 0x100
	s_addc_u32 s80, s80, 0
	s_cmp_gt_u32 s81, 13
	s_barrier
	s_cbranch_scc0 .LBB0_2648
	s_and_b64 vcc, exec, s[18:19]
	s_cbranch_vccz .LBB0_2651
	s_barrier

.LBB0_2870:
	ds_read_b128 v[130:133], v172
	ds_read_b128 v[134:137], v172 offset:1024
	ds_read_b128 v[138:141], v172 offset:2048
	ds_read_b128 v[158:161], v172 offset:3072
	ds_read_b128 v[162:165], v173
	ds_read_b128 v[176:179], v173 offset:1024
	ds_read_b128 v[180:183], v173 offset:2048
	ds_read_b128 v[184:187], v173 offset:3072
	s_add_u32 s44, s42, 0xfffc0080
	s_addc_u32 s45, s43, -1
	s_cmp_eq_u32 s61, 12
	s_cselect_b32 s47, s19, s45
	s_cselect_b32 s46, s57, s44
	s_cselect_b32 s45, s17, s60
	s_cselect_b32 s44, s58, s59
	v_lshl_add_u64 v[166:167], s[42:43], 0, v[150:151]
	s_add_i32 m0, s35, 0xc000
	ds_read_b128 v[188:191], v174
	ds_read_b128 v[192:195], v174 offset:1024
	ds_read_b128 v[196:199], v174 offset:2048
	ds_read_b128 v[200:203], v174 offset:3072
	ds_read_b128 v[204:207], v174 offset:4096
	ds_read_b128 v[208:211], v174 offset:5120
	ds_read_b128 v[212:215], v174 offset:6144
	ds_read_b128 v[216:219], v174 offset:7168
	global_load_lds_dwordx4 v[166:167], off
	v_lshl_add_u64 v[166:167], s[42:43], 0, v[152:153]
	s_add_i32 m0, s35, 0xe000
	s_nop 0
	global_load_lds_dwordx4 v[166:167], off
	s_waitcnt vmcnt(8)
	s_waitcnt lgkmcnt(0)
	s_barrier
	s_setprio 1
	s_waitcnt lgkmcnt(0)
	v_mfma_f32_16x16x32_bf16 v[126:129], v[130:133], v[188:191], v[126:129]
	v_mfma_f32_16x16x32_bf16 v[122:125], v[138:141], v[188:191], v[122:125]
	v_mfma_f32_16x16x32_bf16 v[114:117], v[130:133], v[196:199], v[114:117]
	v_mfma_f32_16x16x32_bf16 v[106:109], v[138:141], v[196:199], v[106:109]
	v_mfma_f32_16x16x32_bf16 v[94:97], v[130:133], v[204:207], v[94:97]
	v_mfma_f32_16x16x32_bf16 v[90:93], v[138:141], v[204:207], v[90:93]
	v_mfma_f32_16x16x32_bf16 v[78:81], v[130:133], v[212:215], v[78:81]
	v_mfma_f32_16x16x32_bf16 v[74:77], v[138:141], v[212:215], v[74:77]
	v_mfma_f32_16x16x32_bf16 v[126:129], v[134:137], v[192:195], v[126:129]
	v_mfma_f32_16x16x32_bf16 v[122:125], v[158:161], v[192:195], v[122:125]
	v_mfma_f32_16x16x32_bf16 v[114:117], v[134:137], v[200:203], v[114:117]
	v_mfma_f32_16x16x32_bf16 v[106:109], v[158:161], v[200:203], v[106:109]
	v_mfma_f32_16x16x32_bf16 v[94:97], v[134:137], v[208:211], v[94:97]
	v_mfma_f32_16x16x32_bf16 v[90:93], v[158:161], v[208:211], v[90:93]
	v_mfma_f32_16x16x32_bf16 v[78:81], v[134:137], v[216:219], v[78:81]
	v_mfma_f32_16x16x32_bf16 v[74:77], v[158:161], v[216:219], v[74:77]
	s_setprio 0
	s_setprio 1
	v_mfma_f32_16x16x32_bf16 v[118:121], v[162:165], v[188:191], v[118:121]
	v_mfma_f32_16x16x32_bf16 v[110:113], v[180:183], v[188:191], v[110:113]
	v_mfma_f32_16x16x32_bf16 v[102:105], v[162:165], v[196:199], v[102:105]
	v_mfma_f32_16x16x32_bf16 v[98:101], v[180:183], v[196:199], v[98:101]
	v_mfma_f32_16x16x32_bf16 v[86:89], v[162:165], v[204:207], v[86:89]
	v_mfma_f32_16x16x32_bf16 v[82:85], v[180:183], v[204:207], v[82:85]
	v_mfma_f32_16x16x32_bf16 v[70:73], v[162:165], v[212:215], v[70:73]
	v_mfma_f32_16x16x32_bf16 v[66:69], v[180:183], v[212:215], v[66:69]
	v_mfma_f32_16x16x32_bf16 v[118:121], v[176:179], v[192:195], v[118:121]
	v_mfma_f32_16x16x32_bf16 v[110:113], v[184:187], v[192:195], v[110:113]
	v_mfma_f32_16x16x32_bf16 v[102:105], v[176:179], v[200:203], v[102:105]
	v_mfma_f32_16x16x32_bf16 v[98:101], v[184:187], v[200:203], v[98:101]
	v_mfma_f32_16x16x32_bf16 v[86:89], v[176:179], v[208:211], v[86:89]
	v_mfma_f32_16x16x32_bf16 v[82:85], v[184:187], v[208:211], v[82:85]
	v_mfma_f32_16x16x32_bf16 v[70:73], v[176:179], v[216:219], v[70:73]
	v_mfma_f32_16x16x32_bf16 v[66:69], v[184:187], v[216:219], v[66:69]
	s_setprio 0
	s_barrier
	s_add_i32 s66, s54, s33
	v_lshl_add_u64 v[166:167], s[44:45], 0, v[144:145]
	s_mov_b32 m0, s66
	ds_read_b128 v[188:191], v174 offset:16384
	ds_read_b128 v[192:195], v174 offset:17408
	ds_read_b128 v[196:199], v174 offset:18432
	ds_read_b128 v[200:203], v174 offset:19456
	ds_read_b128 v[204:207], v174 offset:20480
	ds_read_b128 v[208:211], v174 offset:21504
	ds_read_b128 v[212:215], v174 offset:22528
	ds_read_b128 v[216:219], v174 offset:23552
	global_load_lds_dwordx4 v[166:167], off
	s_add_i32 m0, s66, 0x2000
	s_add_u32 s66, s44, 0x40000
	v_lshl_add_u64 v[220:221], s[44:45], 0, v[148:149]
	s_addc_u32 s67, s45, 0
	s_add_i32 s68, s55, s33
	global_load_lds_dwordx4 v[220:221], off
	v_lshl_add_u64 v[222:223], s[66:67], 0, v[144:145]
	s_mov_b32 m0, s68
	v_lshl_add_u64 v[224:225], s[46:47], 0, v[146:147]
	global_load_lds_dwordx4 v[222:223], off
	v_lshl_add_u64 v[222:223], s[66:67], 0, v[148:149]
	s_add_i32 m0, s68, 0x2000
	s_nop 0
	global_load_lds_dwordx4 v[222:223], off
	v_lshl_add_u64 v[222:223], s[46:47], 0, v[142:143]
	s_mov_b32 m0, s35
	s_nop 0
	global_load_lds_dwordx4 v[222:223], off
	s_mov_b32 m0, s41
	s_nop 0
	global_load_lds_dwordx4 v[224:225], off
	s_waitcnt vmcnt(8)
	s_waitcnt lgkmcnt(0)
	s_barrier
	s_setprio 1
	s_waitcnt lgkmcnt(0)
	v_mfma_f32_16x16x32_bf16 v[62:65], v[130:133], v[188:191], v[62:65]
	v_mfma_f32_16x16x32_bf16 v[58:61], v[138:141], v[188:191], v[58:61]
	v_mfma_f32_16x16x32_bf16 v[50:53], v[130:133], v[196:199], v[50:53]
	v_mfma_f32_16x16x32_bf16 v[42:45], v[138:141], v[196:199], v[42:45]
	v_mfma_f32_16x16x32_bf16 v[38:41], v[130:133], v[204:207], v[38:41]
	v_mfma_f32_16x16x32_bf16 v[30:33], v[138:141], v[204:207], v[30:33]
	v_mfma_f32_16x16x32_bf16 v[22:25], v[130:133], v[212:215], v[22:25]
	v_mfma_f32_16x16x32_bf16 v[14:17], v[138:141], v[212:215], v[14:17]
	v_mfma_f32_16x16x32_bf16 v[62:65], v[134:137], v[192:195], v[62:65]
	v_mfma_f32_16x16x32_bf16 v[58:61], v[158:161], v[192:195], v[58:61]
	v_mfma_f32_16x16x32_bf16 v[50:53], v[134:137], v[200:203], v[50:53]
	v_mfma_f32_16x16x32_bf16 v[42:45], v[158:161], v[200:203], v[42:45]
	v_mfma_f32_16x16x32_bf16 v[38:41], v[134:137], v[208:211], v[38:41]
	v_mfma_f32_16x16x32_bf16 v[30:33], v[158:161], v[208:211], v[30:33]
	v_mfma_f32_16x16x32_bf16 v[22:25], v[134:137], v[216:219], v[22:25]
	v_mfma_f32_16x16x32_bf16 v[14:17], v[158:161], v[216:219], v[14:17]
	s_setprio 0
	s_setprio 1
	v_mfma_f32_16x16x32_bf16 v[54:57], v[162:165], v[188:191], v[54:57]
	v_mfma_f32_16x16x32_bf16 v[46:49], v[180:183], v[188:191], v[46:49]
	v_mfma_f32_16x16x32_bf16 v[34:37], v[162:165], v[196:199], v[34:37]
	v_mfma_f32_16x16x32_bf16 v[26:29], v[180:183], v[196:199], v[26:29]
	v_mfma_f32_16x16x32_bf16 v[18:21], v[162:165], v[204:207], v[18:21]
	v_mfma_f32_16x16x32_bf16 v[10:13], v[180:183], v[204:207], v[10:13]
	v_mfma_f32_16x16x32_bf16 v[6:9], v[162:165], v[212:215], v[6:9]
	v_mfma_f32_16x16x32_bf16 v[2:5], v[180:183], v[212:215], v[2:5]
	v_mfma_f32_16x16x32_bf16 v[54:57], v[176:179], v[192:195], v[54:57]
	v_mfma_f32_16x16x32_bf16 v[46:49], v[184:187], v[192:195], v[46:49]
	v_mfma_f32_16x16x32_bf16 v[34:37], v[176:179], v[200:203], v[34:37]
	v_mfma_f32_16x16x32_bf16 v[26:29], v[184:187], v[200:203], v[26:29]
	v_mfma_f32_16x16x32_bf16 v[18:21], v[176:179], v[208:211], v[18:21]
	v_mfma_f32_16x16x32_bf16 v[10:13], v[184:187], v[208:211], v[10:13]
	v_mfma_f32_16x16x32_bf16 v[6:9], v[176:179], v[216:219], v[6:9]
	v_mfma_f32_16x16x32_bf16 v[2:5], v[184:187], v[216:219], v[2:5]
	s_setprio 0
	s_barrier
	s_add_i32 s66, 0, 0x18000
	s_add_i32 s67, 0, 0x1c000
	v_add_u32_e32 v158, s66, v170
	v_add_u32_e32 v175, s67, v170
	ds_read_b128 v[130:133], v158
	ds_read_b128 v[134:137], v158 offset:1024
	ds_read_b128 v[138:141], v158 offset:2048
	ds_read_b128 v[158:161], v158 offset:3072
	ds_read_b128 v[162:165], v175
	ds_read_b128 v[176:179], v175 offset:1024
	ds_read_b128 v[180:183], v175 offset:2048
	ds_read_b128 v[184:187], v175 offset:3072
	s_add_u32 s46, s46, 0x40000
	s_addc_u32 s47, s47, 0
	s_mov_b32 m0, s48
	v_lshl_add_u64 v[226:227], s[46:47], 0, v[142:143]
	ds_read_b128 v[188:191], v174 offset:32768
	ds_read_b128 v[192:195], v174 offset:33792
	ds_read_b128 v[196:199], v174 offset:34816
	ds_read_b128 v[200:203], v174 offset:35840
	ds_read_b128 v[204:207], v174 offset:36864
	ds_read_b128 v[208:211], v174 offset:37888
	ds_read_b128 v[212:215], v174 offset:38912
	ds_read_b128 v[216:219], v174 offset:39936
	global_load_lds_dwordx4 v[226:227], off
	v_lshl_add_u64 v[226:227], s[46:47], 0, v[146:147]
	s_mov_b32 m0, s49
	s_nop 0
	global_load_lds_dwordx4 v[226:227], off
	s_waitcnt vmcnt(8)
	s_waitcnt lgkmcnt(0)
	s_barrier
	s_setprio 1
	s_waitcnt lgkmcnt(0)
	v_mfma_f32_16x16x32_bf16 v[126:129], v[130:133], v[188:191], v[126:129]
	v_mfma_f32_16x16x32_bf16 v[122:125], v[138:141], v[188:191], v[122:125]
	v_mfma_f32_16x16x32_bf16 v[114:117], v[130:133], v[196:199], v[114:117]
	v_mfma_f32_16x16x32_bf16 v[106:109], v[138:141], v[196:199], v[106:109]
	v_mfma_f32_16x16x32_bf16 v[94:97], v[130:133], v[204:207], v[94:97]
	v_mfma_f32_16x16x32_bf16 v[90:93], v[138:141], v[204:207], v[90:93]
	v_mfma_f32_16x16x32_bf16 v[78:81], v[130:133], v[212:215], v[78:81]
	v_mfma_f32_16x16x32_bf16 v[74:77], v[138:141], v[212:215], v[74:77]
	v_mfma_f32_16x16x32_bf16 v[126:129], v[134:137], v[192:195], v[126:129]
	v_mfma_f32_16x16x32_bf16 v[122:125], v[158:161], v[192:195], v[122:125]
	v_mfma_f32_16x16x32_bf16 v[114:117], v[134:137], v[200:203], v[114:117]
	v_mfma_f32_16x16x32_bf16 v[106:109], v[158:161], v[200:203], v[106:109]
	v_mfma_f32_16x16x32_bf16 v[94:97], v[134:137], v[208:211], v[94:97]
	v_mfma_f32_16x16x32_bf16 v[90:93], v[158:161], v[208:211], v[90:93]
	v_mfma_f32_16x16x32_bf16 v[78:81], v[134:137], v[216:219], v[78:81]
	v_mfma_f32_16x16x32_bf16 v[74:77], v[158:161], v[216:219], v[74:77]
	s_setprio 0
	s_setprio 1
	v_mfma_f32_16x16x32_bf16 v[118:121], v[162:165], v[188:191], v[118:121]
	v_mfma_f32_16x16x32_bf16 v[110:113], v[180:183], v[188:191], v[110:113]
	v_mfma_f32_16x16x32_bf16 v[102:105], v[162:165], v[196:199], v[102:105]
	v_mfma_f32_16x16x32_bf16 v[98:101], v[180:183], v[196:199], v[98:101]
	v_mfma_f32_16x16x32_bf16 v[86:89], v[162:165], v[204:207], v[86:89]
	v_mfma_f32_16x16x32_bf16 v[82:85], v[180:183], v[204:207], v[82:85]
	v_mfma_f32_16x16x32_bf16 v[70:73], v[162:165], v[212:215], v[70:73]
	v_mfma_f32_16x16x32_bf16 v[66:69], v[180:183], v[212:215], v[66:69]
	v_mfma_f32_16x16x32_bf16 v[118:121], v[176:179], v[192:195], v[118:121]
	v_mfma_f32_16x16x32_bf16 v[110:113], v[184:187], v[192:195], v[110:113]
	v_mfma_f32_16x16x32_bf16 v[102:105], v[176:179], v[200:203], v[102:105]
	v_mfma_f32_16x16x32_bf16 v[98:101], v[184:187], v[200:203], v[98:101]
	v_mfma_f32_16x16x32_bf16 v[86:89], v[176:179], v[208:211], v[86:89]
	v_mfma_f32_16x16x32_bf16 v[82:85], v[184:187], v[208:211], v[82:85]
	v_mfma_f32_16x16x32_bf16 v[70:73], v[176:179], v[216:219], v[70:73]
	v_mfma_f32_16x16x32_bf16 v[66:69], v[184:187], v[216:219], v[66:69]
	s_setprio 0
	s_barrier
	s_add_i32 s46, s66, s33
	v_lshl_add_u64 v[166:167], v[166:167], 0, s[10:11]
	s_mov_b32 m0, s46
	ds_read_b128 v[188:191], v174 offset:49152
	ds_read_b128 v[192:195], v174 offset:50176
	ds_read_b128 v[196:199], v174 offset:51200
	ds_read_b128 v[200:203], v174 offset:52224
	ds_read_b128 v[204:207], v174 offset:53248
	ds_read_b128 v[208:211], v174 offset:54272
	ds_read_b128 v[212:215], v174 offset:55296
	ds_read_b128 v[216:219], v174 offset:56320
	global_load_lds_dwordx4 v[166:167], off
	s_add_i32 m0, s46, 0x2000
	s_add_u32 s44, s44, 0x40080
	v_lshl_add_u64 v[166:167], v[220:221], 0, s[10:11]
	s_addc_u32 s45, s45, 0
	s_add_i32 s46, s67, s33
	global_load_lds_dwordx4 v[166:167], off
	v_lshl_add_u64 v[166:167], s[44:45], 0, v[144:145]
	s_mov_b32 m0, s46
	s_nop 0
	global_load_lds_dwordx4 v[166:167], off
	v_lshl_add_u64 v[166:167], s[44:45], 0, v[148:149]
	s_add_i32 m0, s46, 0x2000
	s_nop 0
	global_load_lds_dwordx4 v[166:167], off
	v_lshl_add_u64 v[166:167], v[222:223], 0, s[10:11]
	s_mov_b32 m0, s51
	s_nop 0
	global_load_lds_dwordx4 v[166:167], off
	v_lshl_add_u64 v[166:167], v[224:225], 0, s[10:11]
	s_mov_b32 m0, s52
	s_nop 0
	global_load_lds_dwordx4 v[166:167], off
	s_waitcnt vmcnt(8)
	s_waitcnt lgkmcnt(0)
	s_barrier
	s_setprio 1
	s_waitcnt lgkmcnt(0)
	v_mfma_f32_16x16x32_bf16 v[62:65], v[130:133], v[188:191], v[62:65]
	v_mfma_f32_16x16x32_bf16 v[58:61], v[138:141], v[188:191], v[58:61]
	v_mfma_f32_16x16x32_bf16 v[50:53], v[130:133], v[196:199], v[50:53]
	v_mfma_f32_16x16x32_bf16 v[42:45], v[138:141], v[196:199], v[42:45]
	v_mfma_f32_16x16x32_bf16 v[38:41], v[130:133], v[204:207], v[38:41]
	v_mfma_f32_16x16x32_bf16 v[30:33], v[138:141], v[204:207], v[30:33]
	v_mfma_f32_16x16x32_bf16 v[22:25], v[130:133], v[212:215], v[22:25]
	v_mfma_f32_16x16x32_bf16 v[14:17], v[138:141], v[212:215], v[14:17]
	v_mfma_f32_16x16x32_bf16 v[62:65], v[134:137], v[192:195], v[62:65]
	v_mfma_f32_16x16x32_bf16 v[58:61], v[158:161], v[192:195], v[58:61]
	v_mfma_f32_16x16x32_bf16 v[50:53], v[134:137], v[200:203], v[50:53]
	v_mfma_f32_16x16x32_bf16 v[42:45], v[158:161], v[200:203], v[42:45]
	v_mfma_f32_16x16x32_bf16 v[38:41], v[134:137], v[208:211], v[38:41]
	v_mfma_f32_16x16x32_bf16 v[30:33], v[158:161], v[208:211], v[30:33]
	v_mfma_f32_16x16x32_bf16 v[22:25], v[134:137], v[216:219], v[22:25]
	v_mfma_f32_16x16x32_bf16 v[14:17], v[158:161], v[216:219], v[14:17]
	s_setprio 0
	s_setprio 1
	v_mfma_f32_16x16x32_bf16 v[54:57], v[162:165], v[188:191], v[54:57]
	v_mfma_f32_16x16x32_bf16 v[46:49], v[180:183], v[188:191], v[46:49]
	v_mfma_f32_16x16x32_bf16 v[34:37], v[162:165], v[196:199], v[34:37]
	v_mfma_f32_16x16x32_bf16 v[26:29], v[180:183], v[196:199], v[26:29]
	v_mfma_f32_16x16x32_bf16 v[18:21], v[162:165], v[204:207], v[18:21]
	v_mfma_f32_16x16x32_bf16 v[10:13], v[180:183], v[204:207], v[10:13]
	v_mfma_f32_16x16x32_bf16 v[6:9], v[162:165], v[212:215], v[6:9]
	v_mfma_f32_16x16x32_bf16 v[2:5], v[180:183], v[212:215], v[2:5]
	v_mfma_f32_16x16x32_bf16 v[54:57], v[176:179], v[192:195], v[54:57]
	v_mfma_f32_16x16x32_bf16 v[46:49], v[184:187], v[192:195], v[46:49]
	v_mfma_f32_16x16x32_bf16 v[34:37], v[176:179], v[200:203], v[34:37]
	v_mfma_f32_16x16x32_bf16 v[26:29], v[184:187], v[200:203], v[26:29]
	v_mfma_f32_16x16x32_bf16 v[18:21], v[176:179], v[208:211], v[18:21]
	v_mfma_f32_16x16x32_bf16 v[10:13], v[184:187], v[208:211], v[10:13]
	v_mfma_f32_16x16x32_bf16 v[6:9], v[176:179], v[216:219], v[6:9]
	v_mfma_f32_16x16x32_bf16 v[2:5], v[184:187], v[216:219], v[2:5]
	s_setprio 0
	s_add_i32 s61, s61, 2
	s_add_u32 s42, s42, 0x100
	s_addc_u32 s43, s43, 0
	s_add_u32 s59, s59, 0x100
	s_addc_u32 s60, s60, 0
	s_cmp_gt_u32 s61, 13
	s_barrier
	s_cbranch_scc0 .LBB0_2870
	s_and_b64 vcc, exec, s[12:13]
	s_cbranch_vccz .LBB0_2873
	s_barrier

.LBB0_2916:
	ds_read_b128 v[150:153], v166
	ds_read_b128 v[154:157], v166 offset:1024
	ds_read_b128 v[170:173], v166 offset:2048
	ds_read_b128 v[174:177], v166 offset:3072
	ds_read_b128 v[178:181], v167
	ds_read_b128 v[182:185], v167 offset:1024
	ds_read_b128 v[186:189], v167 offset:2048
	ds_read_b128 v[190:193], v167 offset:3072
	s_add_u32 s46, s44, 0xfffc0080
	s_addc_u32 s47, s45, -1
	s_cmp_eq_u32 s71, 12
	s_cselect_b32 s49, s39, s47
	s_cselect_b32 s48, s61, s46
	s_cselect_b32 s47, s23, s70
	s_cselect_b32 s46, s68, s69
	v_lshl_add_u64 v[158:159], s[44:45], 0, v[142:143]
	s_add_i32 m0, s33, 0xc000
	ds_read_b128 v[194:197], v168
	ds_read_b128 v[198:201], v168 offset:1024
	ds_read_b128 v[202:205], v168 offset:2048
	ds_read_b128 v[206:209], v168 offset:3072
	ds_read_b128 v[210:213], v168 offset:4096
	ds_read_b128 v[214:217], v168 offset:5120
	ds_read_b128 v[218:221], v168 offset:6144
	ds_read_b128 v[222:225], v168 offset:7168
	global_load_lds_dwordx4 v[158:159], off
	v_lshl_add_u64 v[158:159], s[44:45], 0, v[144:145]
	s_add_i32 m0, s33, 0xe000
	s_nop 0
	global_load_lds_dwordx4 v[158:159], off
	s_waitcnt vmcnt(8)
	s_waitcnt lgkmcnt(0)
	s_barrier
	s_setprio 1
	s_waitcnt lgkmcnt(0)
	v_mfma_f32_16x16x32_bf16 v[126:129], v[150:153], v[194:197], v[126:129]
	v_mfma_f32_16x16x32_bf16 v[122:125], v[170:173], v[194:197], v[122:125]
	v_mfma_f32_16x16x32_bf16 v[110:113], v[150:153], v[202:205], v[110:113]
	v_mfma_f32_16x16x32_bf16 v[106:109], v[170:173], v[202:205], v[106:109]
	v_mfma_f32_16x16x32_bf16 v[94:97], v[150:153], v[210:213], v[94:97]
	v_mfma_f32_16x16x32_bf16 v[90:93], v[170:173], v[210:213], v[90:93]
	v_mfma_f32_16x16x32_bf16 v[78:81], v[150:153], v[218:221], v[78:81]
	v_mfma_f32_16x16x32_bf16 v[74:77], v[170:173], v[218:221], v[74:77]
	v_mfma_f32_16x16x32_bf16 v[126:129], v[154:157], v[198:201], v[126:129]
	v_mfma_f32_16x16x32_bf16 v[122:125], v[174:177], v[198:201], v[122:125]
	v_mfma_f32_16x16x32_bf16 v[110:113], v[154:157], v[206:209], v[110:113]
	v_mfma_f32_16x16x32_bf16 v[106:109], v[174:177], v[206:209], v[106:109]
	v_mfma_f32_16x16x32_bf16 v[94:97], v[154:157], v[214:217], v[94:97]
	v_mfma_f32_16x16x32_bf16 v[90:93], v[174:177], v[214:217], v[90:93]
	v_mfma_f32_16x16x32_bf16 v[78:81], v[154:157], v[222:225], v[78:81]
	v_mfma_f32_16x16x32_bf16 v[74:77], v[174:177], v[222:225], v[74:77]
	s_setprio 0
	s_setprio 1
	v_mfma_f32_16x16x32_bf16 v[118:121], v[178:181], v[194:197], v[118:121]
	v_mfma_f32_16x16x32_bf16 v[114:117], v[186:189], v[194:197], v[114:117]
	v_mfma_f32_16x16x32_bf16 v[102:105], v[178:181], v[202:205], v[102:105]
	v_mfma_f32_16x16x32_bf16 v[98:101], v[186:189], v[202:205], v[98:101]
	v_mfma_f32_16x16x32_bf16 v[86:89], v[178:181], v[210:213], v[86:89]
	v_mfma_f32_16x16x32_bf16 v[82:85], v[186:189], v[210:213], v[82:85]
	v_mfma_f32_16x16x32_bf16 v[70:73], v[178:181], v[218:221], v[70:73]
	v_mfma_f32_16x16x32_bf16 v[66:69], v[186:189], v[218:221], v[66:69]
	v_mfma_f32_16x16x32_bf16 v[118:121], v[182:185], v[198:201], v[118:121]
	v_mfma_f32_16x16x32_bf16 v[114:117], v[190:193], v[198:201], v[114:117]
	v_mfma_f32_16x16x32_bf16 v[102:105], v[182:185], v[206:209], v[102:105]
	v_mfma_f32_16x16x32_bf16 v[98:101], v[190:193], v[206:209], v[98:101]
	v_mfma_f32_16x16x32_bf16 v[86:89], v[182:185], v[214:217], v[86:89]
	v_mfma_f32_16x16x32_bf16 v[82:85], v[190:193], v[214:217], v[82:85]
	v_mfma_f32_16x16x32_bf16 v[70:73], v[182:185], v[222:225], v[70:73]
	v_mfma_f32_16x16x32_bf16 v[66:69], v[190:193], v[222:225], v[66:69]
	s_setprio 0
	s_barrier
	s_add_i32 s66, s58, s21
	v_lshl_add_u64 v[158:159], s[46:47], 0, v[132:133]
	s_mov_b32 m0, s66
	ds_read_b128 v[194:197], v168 offset:16384
	ds_read_b128 v[198:201], v168 offset:17408
	ds_read_b128 v[202:205], v168 offset:18432
	ds_read_b128 v[206:209], v168 offset:19456
	ds_read_b128 v[210:213], v168 offset:20480
	ds_read_b128 v[214:217], v168 offset:21504
	ds_read_b128 v[218:221], v168 offset:22528
	ds_read_b128 v[222:225], v168 offset:23552
	global_load_lds_dwordx4 v[158:159], off
	s_add_i32 m0, s66, 0x2000
	s_add_u32 s66, s46, 0x40000
	v_lshl_add_u64 v[226:227], s[46:47], 0, v[136:137]
	s_addc_u32 s67, s47, 0
	s_add_i32 s72, s59, s21
	global_load_lds_dwordx4 v[226:227], off
	v_lshl_add_u64 v[228:229], s[66:67], 0, v[132:133]
	s_mov_b32 m0, s72
	v_lshl_add_u64 v[230:231], s[48:49], 0, v[134:135]
	global_load_lds_dwordx4 v[228:229], off
	v_lshl_add_u64 v[228:229], s[66:67], 0, v[136:137]
	s_add_i32 m0, s72, 0x2000
	s_nop 0
	global_load_lds_dwordx4 v[228:229], off
	v_lshl_add_u64 v[228:229], s[48:49], 0, v[130:131]
	s_mov_b32 m0, s33
	s_nop 0
	global_load_lds_dwordx4 v[228:229], off
	s_mov_b32 m0, s35
	s_nop 0
	global_load_lds_dwordx4 v[230:231], off
	s_waitcnt vmcnt(8)
	s_waitcnt lgkmcnt(0)
	s_barrier
	s_setprio 1
	s_waitcnt lgkmcnt(0)
	v_mfma_f32_16x16x32_bf16 v[62:65], v[150:153], v[194:197], v[62:65]
	v_mfma_f32_16x16x32_bf16 v[58:61], v[170:173], v[194:197], v[58:61]
	v_mfma_f32_16x16x32_bf16 v[46:49], v[150:153], v[202:205], v[46:49]
	v_mfma_f32_16x16x32_bf16 v[42:45], v[170:173], v[202:205], v[42:45]
	v_mfma_f32_16x16x32_bf16 v[30:33], v[150:153], v[210:213], v[30:33]
	v_mfma_f32_16x16x32_bf16 v[26:29], v[170:173], v[210:213], v[26:29]
	v_mfma_f32_16x16x32_bf16 v[14:17], v[150:153], v[218:221], v[14:17]
	v_mfma_f32_16x16x32_bf16 v[10:13], v[170:173], v[218:221], v[10:13]
	v_mfma_f32_16x16x32_bf16 v[62:65], v[154:157], v[198:201], v[62:65]
	v_mfma_f32_16x16x32_bf16 v[58:61], v[174:177], v[198:201], v[58:61]
	v_mfma_f32_16x16x32_bf16 v[46:49], v[154:157], v[206:209], v[46:49]
	v_mfma_f32_16x16x32_bf16 v[42:45], v[174:177], v[206:209], v[42:45]
	v_mfma_f32_16x16x32_bf16 v[30:33], v[154:157], v[214:217], v[30:33]
	v_mfma_f32_16x16x32_bf16 v[26:29], v[174:177], v[214:217], v[26:29]
	v_mfma_f32_16x16x32_bf16 v[14:17], v[154:157], v[222:225], v[14:17]
	v_mfma_f32_16x16x32_bf16 v[10:13], v[174:177], v[222:225], v[10:13]
	s_setprio 0
	s_setprio 1
	v_mfma_f32_16x16x32_bf16 v[54:57], v[178:181], v[194:197], v[54:57]
	v_mfma_f32_16x16x32_bf16 v[50:53], v[186:189], v[194:197], v[50:53]
	v_mfma_f32_16x16x32_bf16 v[38:41], v[178:181], v[202:205], v[38:41]
	v_mfma_f32_16x16x32_bf16 v[34:37], v[186:189], v[202:205], v[34:37]
	v_mfma_f32_16x16x32_bf16 v[22:25], v[178:181], v[210:213], v[22:25]
	v_mfma_f32_16x16x32_bf16 v[18:21], v[186:189], v[210:213], v[18:21]
	v_mfma_f32_16x16x32_bf16 v[6:9], v[178:181], v[218:221], v[6:9]
	v_mfma_f32_16x16x32_bf16 v[2:5], v[186:189], v[218:221], v[2:5]
	v_mfma_f32_16x16x32_bf16 v[54:57], v[182:185], v[198:201], v[54:57]
	v_mfma_f32_16x16x32_bf16 v[50:53], v[190:193], v[198:201], v[50:53]
	v_mfma_f32_16x16x32_bf16 v[38:41], v[182:185], v[206:209], v[38:41]
	v_mfma_f32_16x16x32_bf16 v[34:37], v[190:193], v[206:209], v[34:37]
	v_mfma_f32_16x16x32_bf16 v[22:25], v[182:185], v[214:217], v[22:25]
	v_mfma_f32_16x16x32_bf16 v[18:21], v[190:193], v[214:217], v[18:21]
	v_mfma_f32_16x16x32_bf16 v[6:9], v[182:185], v[222:225], v[6:9]
	v_mfma_f32_16x16x32_bf16 v[2:5], v[190:193], v[222:225], v[2:5]
	s_setprio 0
	s_barrier
	s_add_i32 s66, 0, 0x18000
	s_add_i32 s67, 0, 0x1c000
	v_add_u32_e32 v174, s66, v164
	v_add_u32_e32 v190, s67, v164
	ds_read_b128 v[150:153], v174
	ds_read_b128 v[154:157], v174 offset:1024
	ds_read_b128 v[170:173], v174 offset:2048
	ds_read_b128 v[174:177], v174 offset:3072
	ds_read_b128 v[178:181], v190
	ds_read_b128 v[182:185], v190 offset:1024
	ds_read_b128 v[186:189], v190 offset:2048
	ds_read_b128 v[190:193], v190 offset:3072
	s_add_u32 s48, s48, 0x40000
	s_addc_u32 s49, s49, 0
	s_mov_b32 m0, s50
	v_lshl_add_u64 v[232:233], s[48:49], 0, v[130:131]
	ds_read_b128 v[194:197], v168 offset:32768
	ds_read_b128 v[198:201], v168 offset:33792
	ds_read_b128 v[202:205], v168 offset:34816
	ds_read_b128 v[206:209], v168 offset:35840
	ds_read_b128 v[210:213], v168 offset:36864
	ds_read_b128 v[214:217], v168 offset:37888
	ds_read_b128 v[218:221], v168 offset:38912
	ds_read_b128 v[222:225], v168 offset:39936
	global_load_lds_dwordx4 v[232:233], off
	v_lshl_add_u64 v[232:233], s[48:49], 0, v[134:135]
	s_mov_b32 m0, s51
	s_nop 0
	global_load_lds_dwordx4 v[232:233], off
	s_waitcnt vmcnt(8)
	s_waitcnt lgkmcnt(0)
	s_barrier
	s_setprio 1
	s_waitcnt lgkmcnt(0)
	v_mfma_f32_16x16x32_bf16 v[126:129], v[150:153], v[194:197], v[126:129]
	v_mfma_f32_16x16x32_bf16 v[122:125], v[170:173], v[194:197], v[122:125]
	v_mfma_f32_16x16x32_bf16 v[110:113], v[150:153], v[202:205], v[110:113]
	v_mfma_f32_16x16x32_bf16 v[106:109], v[170:173], v[202:205], v[106:109]
	v_mfma_f32_16x16x32_bf16 v[94:97], v[150:153], v[210:213], v[94:97]
	v_mfma_f32_16x16x32_bf16 v[90:93], v[170:173], v[210:213], v[90:93]
	v_mfma_f32_16x16x32_bf16 v[78:81], v[150:153], v[218:221], v[78:81]
	v_mfma_f32_16x16x32_bf16 v[74:77], v[170:173], v[218:221], v[74:77]
	v_mfma_f32_16x16x32_bf16 v[126:129], v[154:157], v[198:201], v[126:129]
	v_mfma_f32_16x16x32_bf16 v[122:125], v[174:177], v[198:201], v[122:125]
	v_mfma_f32_16x16x32_bf16 v[110:113], v[154:157], v[206:209], v[110:113]
	v_mfma_f32_16x16x32_bf16 v[106:109], v[174:177], v[206:209], v[106:109]
	v_mfma_f32_16x16x32_bf16 v[94:97], v[154:157], v[214:217], v[94:97]
	v_mfma_f32_16x16x32_bf16 v[90:93], v[174:177], v[214:217], v[90:93]
	v_mfma_f32_16x16x32_bf16 v[78:81], v[154:157], v[222:225], v[78:81]
	v_mfma_f32_16x16x32_bf16 v[74:77], v[174:177], v[222:225], v[74:77]
	s_setprio 0
	s_setprio 1
	v_mfma_f32_16x16x32_bf16 v[118:121], v[178:181], v[194:197], v[118:121]
	v_mfma_f32_16x16x32_bf16 v[114:117], v[186:189], v[194:197], v[114:117]
	v_mfma_f32_16x16x32_bf16 v[102:105], v[178:181], v[202:205], v[102:105]
	v_mfma_f32_16x16x32_bf16 v[98:101], v[186:189], v[202:205], v[98:101]
	v_mfma_f32_16x16x32_bf16 v[86:89], v[178:181], v[210:213], v[86:89]
	v_mfma_f32_16x16x32_bf16 v[82:85], v[186:189], v[210:213], v[82:85]
	v_mfma_f32_16x16x32_bf16 v[70:73], v[178:181], v[218:221], v[70:73]
	v_mfma_f32_16x16x32_bf16 v[66:69], v[186:189], v[218:221], v[66:69]
	v_mfma_f32_16x16x32_bf16 v[118:121], v[182:185], v[198:201], v[118:121]
	v_mfma_f32_16x16x32_bf16 v[114:117], v[190:193], v[198:201], v[114:117]
	v_mfma_f32_16x16x32_bf16 v[102:105], v[182:185], v[206:209], v[102:105]
	v_mfma_f32_16x16x32_bf16 v[98:101], v[190:193], v[206:209], v[98:101]
	v_mfma_f32_16x16x32_bf16 v[86:89], v[182:185], v[214:217], v[86:89]
	v_mfma_f32_16x16x32_bf16 v[82:85], v[190:193], v[214:217], v[82:85]
	v_mfma_f32_16x16x32_bf16 v[70:73], v[182:185], v[222:225], v[70:73]
	v_mfma_f32_16x16x32_bf16 v[66:69], v[190:193], v[222:225], v[66:69]
	s_setprio 0
	s_barrier
	s_add_i32 s48, s66, s21
	v_lshl_add_u64 v[158:159], v[158:159], 0, s[10:11]
	s_mov_b32 m0, s48
	ds_read_b128 v[194:197], v168 offset:49152
	ds_read_b128 v[198:201], v168 offset:50176
	ds_read_b128 v[202:205], v168 offset:51200
	ds_read_b128 v[206:209], v168 offset:52224
	ds_read_b128 v[210:213], v168 offset:53248
	ds_read_b128 v[214:217], v168 offset:54272
	ds_read_b128 v[218:221], v168 offset:55296
	ds_read_b128 v[222:225], v168 offset:56320
	global_load_lds_dwordx4 v[158:159], off
	s_add_i32 m0, s48, 0x2000
	s_add_u32 s46, s46, 0x40080
	v_lshl_add_u64 v[158:159], v[226:227], 0, s[10:11]
	s_addc_u32 s47, s47, 0
	s_add_i32 s48, s67, s21
	global_load_lds_dwordx4 v[158:159], off
	v_lshl_add_u64 v[158:159], s[46:47], 0, v[132:133]
	s_mov_b32 m0, s48
	s_nop 0
	global_load_lds_dwordx4 v[158:159], off
	v_lshl_add_u64 v[158:159], s[46:47], 0, v[136:137]
	s_add_i32 m0, s48, 0x2000
	s_nop 0
	global_load_lds_dwordx4 v[158:159], off
	v_lshl_add_u64 v[158:159], v[228:229], 0, s[10:11]
	s_mov_b32 m0, s53
	s_nop 0
	global_load_lds_dwordx4 v[158:159], off
	v_lshl_add_u64 v[158:159], v[230:231], 0, s[10:11]
	s_mov_b32 m0, s54
	s_nop 0
	global_load_lds_dwordx4 v[158:159], off
	s_waitcnt vmcnt(8)
	s_waitcnt lgkmcnt(0)
	s_barrier
	s_setprio 1
	s_waitcnt lgkmcnt(0)
	v_mfma_f32_16x16x32_bf16 v[62:65], v[150:153], v[194:197], v[62:65]
	v_mfma_f32_16x16x32_bf16 v[58:61], v[170:173], v[194:197], v[58:61]
	v_mfma_f32_16x16x32_bf16 v[46:49], v[150:153], v[202:205], v[46:49]
	v_mfma_f32_16x16x32_bf16 v[42:45], v[170:173], v[202:205], v[42:45]
	v_mfma_f32_16x16x32_bf16 v[30:33], v[150:153], v[210:213], v[30:33]
	v_mfma_f32_16x16x32_bf16 v[26:29], v[170:173], v[210:213], v[26:29]
	v_mfma_f32_16x16x32_bf16 v[14:17], v[150:153], v[218:221], v[14:17]
	v_mfma_f32_16x16x32_bf16 v[10:13], v[170:173], v[218:221], v[10:13]
	v_mfma_f32_16x16x32_bf16 v[62:65], v[154:157], v[198:201], v[62:65]
	v_mfma_f32_16x16x32_bf16 v[58:61], v[174:177], v[198:201], v[58:61]
	v_mfma_f32_16x16x32_bf16 v[46:49], v[154:157], v[206:209], v[46:49]
	v_mfma_f32_16x16x32_bf16 v[42:45], v[174:177], v[206:209], v[42:45]
	v_mfma_f32_16x16x32_bf16 v[30:33], v[154:157], v[214:217], v[30:33]
	v_mfma_f32_16x16x32_bf16 v[26:29], v[174:177], v[214:217], v[26:29]
	v_mfma_f32_16x16x32_bf16 v[14:17], v[154:157], v[222:225], v[14:17]
	v_mfma_f32_16x16x32_bf16 v[10:13], v[174:177], v[222:225], v[10:13]
	s_setprio 0
	s_setprio 1
	v_mfma_f32_16x16x32_bf16 v[54:57], v[178:181], v[194:197], v[54:57]
	v_mfma_f32_16x16x32_bf16 v[50:53], v[186:189], v[194:197], v[50:53]
	v_mfma_f32_16x16x32_bf16 v[38:41], v[178:181], v[202:205], v[38:41]
	v_mfma_f32_16x16x32_bf16 v[34:37], v[186:189], v[202:205], v[34:37]
	v_mfma_f32_16x16x32_bf16 v[22:25], v[178:181], v[210:213], v[22:25]
	v_mfma_f32_16x16x32_bf16 v[18:21], v[186:189], v[210:213], v[18:21]
	v_mfma_f32_16x16x32_bf16 v[6:9], v[178:181], v[218:221], v[6:9]
	v_mfma_f32_16x16x32_bf16 v[2:5], v[186:189], v[218:221], v[2:5]
	v_mfma_f32_16x16x32_bf16 v[54:57], v[182:185], v[198:201], v[54:57]
	v_mfma_f32_16x16x32_bf16 v[50:53], v[190:193], v[198:201], v[50:53]
	v_mfma_f32_16x16x32_bf16 v[38:41], v[182:185], v[206:209], v[38:41]
	v_mfma_f32_16x16x32_bf16 v[34:37], v[190:193], v[206:209], v[34:37]
	v_mfma_f32_16x16x32_bf16 v[22:25], v[182:185], v[214:217], v[22:25]
	v_mfma_f32_16x16x32_bf16 v[18:21], v[190:193], v[214:217], v[18:21]
	v_mfma_f32_16x16x32_bf16 v[6:9], v[182:185], v[222:225], v[6:9]
	v_mfma_f32_16x16x32_bf16 v[2:5], v[190:193], v[222:225], v[2:5]
	s_setprio 0
	s_add_i32 s71, s71, 2
	s_add_u32 s44, s44, 0x100
	s_addc_u32 s45, s45, 0
	s_add_u32 s69, s69, 0x100
	s_addc_u32 s70, s70, 0
	s_cmp_gt_u32 s71, 13
	s_barrier
	s_cbranch_scc0 .LBB0_2916
	s_and_b64 vcc, exec, s[16:17]
	s_cbranch_vccz .LBB0_2919
	s_barrier

.LBB0_2976:
	s_or_b64 exec, exec, s[10:11]
	v_cvt_f32_u32_e32 v6, v4
	s_waitcnt vmcnt(0)
	v_readfirstlane_b32 s3, v5
	v_sub_u32_e32 v5, 0, v4
	v_rcp_iflag_f32_e32 v6, v6
	v_add_u32_e32 v7, s3, v3
	v_mul_f32_e32 v6, 0x4f7ffffe, v6
	v_cvt_u32_f32_e32 v6, v6
	v_mul_lo_u32 v3, v5, v6
	v_mul_hi_u32 v3, v6, v3
	v_add_u32_e32 v3, v6, v3
	v_mul_hi_u32 v3, v7, v3
	v_mul_lo_u32 v5, v3, v4
	v_sub_u32_e32 v5, v7, v5
	v_add_u32_e32 v6, 1, v3
	v_cmp_ge_u32_e32 vcc, v5, v4
	s_nop 1
	v_cndmask_b32_e32 v3, v3, v6, vcc
	v_sub_u32_e32 v6, v5, v4
	v_cndmask_b32_e32 v5, v5, v6, vcc
	v_add_u32_e32 v6, 1, v3
	v_cmp_ge_u32_e32 vcc, v5, v4
	v_add_u32_e32 v5, 1, v7
	s_nop 0
	v_cndmask_b32_e32 v3, v3, v6, vcc
	v_mul_lo_u32 v6, v4, v3
	v_add_u32_e32 v4, v6, v4
	v_cmp_ne_u32_e32 vcc, v5, v4
	s_and_saveexec_b64 s[8:9], vcc
	s_xor_b64 s[8:9], exec, s[8:9]
	s_cbranch_execz .LBB0_2990
	s_waitcnt lgkmcnt(0)
	s_add_u32 s16, s28, 0xf190900
	s_addc_u32 s17, s29, 0
	v_mov_b32_e32 v2, 0
	global_load_dword v2, v2, s[16:17] sc1
	s_waitcnt vmcnt(0)
	v_cmp_eq_u32_e32 vcc, v2, v3
	s_and_saveexec_b64 s[10:11], vcc
	s_cbranch_execz .LBB0_2989
	s_add_u32 s12, s28, 0xf18d600
	s_addc_u32 s13, s29, 0
	s_mov_b32 s3, 1
	s_mov_b64 s[18:19], 0
	v_mov_b32_e32 v2, 0
	s_branch .LBB0_2980

.LBB0_3029:
	ds_read_b128 v[130:133], v168
	ds_read_b128 v[134:137], v168 offset:1024
	ds_read_b128 v[154:157], v168 offset:2048
	ds_read_b128 v[158:161], v168 offset:3072
	ds_read_b128 v[172:175], v169
	ds_read_b128 v[176:179], v169 offset:1024
	ds_read_b128 v[180:183], v169 offset:2048
	ds_read_b128 v[184:187], v169 offset:3072
	s_add_u32 s42, s40, 0xfffc0080
	s_addc_u32 s43, s41, -1
	s_cmp_eq_u32 s59, 12
	s_cselect_b32 s45, s21, s43
	s_cselect_b32 s44, s55, s42
	s_cselect_b32 s43, s19, s58
	s_cselect_b32 s42, s56, s57
	v_lshl_add_u64 v[162:163], s[40:41], 0, v[146:147]
	s_add_i32 m0, s35, 0xc000
	ds_read_b128 v[188:191], v170
	ds_read_b128 v[192:195], v170 offset:1024
	ds_read_b128 v[196:199], v170 offset:2048
	ds_read_b128 v[200:203], v170 offset:3072
	ds_read_b128 v[204:207], v170 offset:4096
	ds_read_b128 v[208:211], v170 offset:5120
	ds_read_b128 v[212:215], v170 offset:6144
	ds_read_b128 v[216:219], v170 offset:7168
	global_load_lds_dwordx4 v[162:163], off
	v_lshl_add_u64 v[162:163], s[40:41], 0, v[148:149]
	s_add_i32 m0, s35, 0xe000
	s_nop 0
	global_load_lds_dwordx4 v[162:163], off
	s_waitcnt vmcnt(8)
	s_waitcnt lgkmcnt(0)
	s_barrier
	s_setprio 1
	s_waitcnt lgkmcnt(0)
	v_mfma_f32_16x16x32_bf16 v[126:129], v[130:133], v[188:191], v[126:129]
	v_mfma_f32_16x16x32_bf16 v[122:125], v[154:157], v[188:191], v[122:125]
	v_mfma_f32_16x16x32_bf16 v[110:113], v[130:133], v[196:199], v[110:113]
	v_mfma_f32_16x16x32_bf16 v[106:109], v[154:157], v[196:199], v[106:109]
	v_mfma_f32_16x16x32_bf16 v[94:97], v[130:133], v[204:207], v[94:97]
	v_mfma_f32_16x16x32_bf16 v[90:93], v[154:157], v[204:207], v[90:93]
	v_mfma_f32_16x16x32_bf16 v[82:85], v[130:133], v[212:215], v[82:85]
	v_mfma_f32_16x16x32_bf16 v[74:77], v[154:157], v[212:215], v[74:77]
	v_mfma_f32_16x16x32_bf16 v[126:129], v[134:137], v[192:195], v[126:129]
	v_mfma_f32_16x16x32_bf16 v[122:125], v[158:161], v[192:195], v[122:125]
	v_mfma_f32_16x16x32_bf16 v[110:113], v[134:137], v[200:203], v[110:113]
	v_mfma_f32_16x16x32_bf16 v[106:109], v[158:161], v[200:203], v[106:109]
	v_mfma_f32_16x16x32_bf16 v[94:97], v[134:137], v[208:211], v[94:97]
	v_mfma_f32_16x16x32_bf16 v[90:93], v[158:161], v[208:211], v[90:93]
	v_mfma_f32_16x16x32_bf16 v[82:85], v[134:137], v[216:219], v[82:85]
	v_mfma_f32_16x16x32_bf16 v[74:77], v[158:161], v[216:219], v[74:77]
	s_setprio 0
	s_setprio 1
	v_mfma_f32_16x16x32_bf16 v[118:121], v[172:175], v[188:191], v[118:121]
	v_mfma_f32_16x16x32_bf16 v[114:117], v[180:183], v[188:191], v[114:117]
	v_mfma_f32_16x16x32_bf16 v[102:105], v[172:175], v[196:199], v[102:105]
	v_mfma_f32_16x16x32_bf16 v[98:101], v[180:183], v[196:199], v[98:101]
	v_mfma_f32_16x16x32_bf16 v[86:89], v[172:175], v[204:207], v[86:89]
	v_mfma_f32_16x16x32_bf16 v[78:81], v[180:183], v[204:207], v[78:81]
	v_mfma_f32_16x16x32_bf16 v[70:73], v[172:175], v[212:215], v[70:73]
	v_mfma_f32_16x16x32_bf16 v[66:69], v[180:183], v[212:215], v[66:69]
	v_mfma_f32_16x16x32_bf16 v[118:121], v[176:179], v[192:195], v[118:121]
	v_mfma_f32_16x16x32_bf16 v[114:117], v[184:187], v[192:195], v[114:117]
	v_mfma_f32_16x16x32_bf16 v[102:105], v[176:179], v[200:203], v[102:105]
	v_mfma_f32_16x16x32_bf16 v[98:101], v[184:187], v[200:203], v[98:101]
	v_mfma_f32_16x16x32_bf16 v[86:89], v[176:179], v[208:211], v[86:89]
	v_mfma_f32_16x16x32_bf16 v[78:81], v[184:187], v[208:211], v[78:81]
	v_mfma_f32_16x16x32_bf16 v[70:73], v[176:179], v[216:219], v[70:73]
	v_mfma_f32_16x16x32_bf16 v[66:69], v[184:187], v[216:219], v[66:69]
	s_setprio 0
	s_barrier
	s_add_i32 s60, s52, s33
	v_lshl_add_u64 v[162:163], s[42:43], 0, v[140:141]
	s_mov_b32 m0, s60
	ds_read_b128 v[188:191], v170 offset:16384
	ds_read_b128 v[192:195], v170 offset:17408
	ds_read_b128 v[196:199], v170 offset:18432
	ds_read_b128 v[200:203], v170 offset:19456
	ds_read_b128 v[204:207], v170 offset:20480
	ds_read_b128 v[208:211], v170 offset:21504
	ds_read_b128 v[212:215], v170 offset:22528
	ds_read_b128 v[216:219], v170 offset:23552
	global_load_lds_dwordx4 v[162:163], off
	s_add_i32 m0, s60, 0x2000
	s_add_u32 s60, s42, 0x40000
	v_lshl_add_u64 v[220:221], s[42:43], 0, v[144:145]
	s_addc_u32 s61, s43, 0
	s_add_i32 s66, s53, s33
	global_load_lds_dwordx4 v[220:221], off
	v_lshl_add_u64 v[222:223], s[60:61], 0, v[140:141]
	s_mov_b32 m0, s66
	v_lshl_add_u64 v[224:225], s[44:45], 0, v[142:143]
	global_load_lds_dwordx4 v[222:223], off
	v_lshl_add_u64 v[222:223], s[60:61], 0, v[144:145]
	s_add_i32 m0, s66, 0x2000
	s_nop 0
	global_load_lds_dwordx4 v[222:223], off
	v_lshl_add_u64 v[222:223], s[44:45], 0, v[138:139]
	s_mov_b32 m0, s35
	s_nop 0
	global_load_lds_dwordx4 v[222:223], off
	s_mov_b32 m0, s39
	s_nop 0
	global_load_lds_dwordx4 v[224:225], off
	s_waitcnt vmcnt(8)
	s_waitcnt lgkmcnt(0)
	s_barrier
	s_setprio 1
	s_waitcnt lgkmcnt(0)
	v_mfma_f32_16x16x32_bf16 v[62:65], v[130:133], v[188:191], v[62:65]
	v_mfma_f32_16x16x32_bf16 v[58:61], v[154:157], v[188:191], v[58:61]
	v_mfma_f32_16x16x32_bf16 v[46:49], v[130:133], v[196:199], v[46:49]
	v_mfma_f32_16x16x32_bf16 v[42:45], v[154:157], v[196:199], v[42:45]
	v_mfma_f32_16x16x32_bf16 v[30:33], v[130:133], v[204:207], v[30:33]
	v_mfma_f32_16x16x32_bf16 v[26:29], v[154:157], v[204:207], v[26:29]
	v_mfma_f32_16x16x32_bf16 v[14:17], v[130:133], v[212:215], v[14:17]
	v_mfma_f32_16x16x32_bf16 v[10:13], v[154:157], v[212:215], v[10:13]
	v_mfma_f32_16x16x32_bf16 v[62:65], v[134:137], v[192:195], v[62:65]
	v_mfma_f32_16x16x32_bf16 v[58:61], v[158:161], v[192:195], v[58:61]
	v_mfma_f32_16x16x32_bf16 v[46:49], v[134:137], v[200:203], v[46:49]
	v_mfma_f32_16x16x32_bf16 v[42:45], v[158:161], v[200:203], v[42:45]
	v_mfma_f32_16x16x32_bf16 v[30:33], v[134:137], v[208:211], v[30:33]
	v_mfma_f32_16x16x32_bf16 v[26:29], v[158:161], v[208:211], v[26:29]
	v_mfma_f32_16x16x32_bf16 v[14:17], v[134:137], v[216:219], v[14:17]
	v_mfma_f32_16x16x32_bf16 v[10:13], v[158:161], v[216:219], v[10:13]
	s_setprio 0
	s_setprio 1
	v_mfma_f32_16x16x32_bf16 v[54:57], v[172:175], v[188:191], v[54:57]
	v_mfma_f32_16x16x32_bf16 v[50:53], v[180:183], v[188:191], v[50:53]
	v_mfma_f32_16x16x32_bf16 v[38:41], v[172:175], v[196:199], v[38:41]
	v_mfma_f32_16x16x32_bf16 v[34:37], v[180:183], v[196:199], v[34:37]
	v_mfma_f32_16x16x32_bf16 v[22:25], v[172:175], v[204:207], v[22:25]
	v_mfma_f32_16x16x32_bf16 v[18:21], v[180:183], v[204:207], v[18:21]
	v_mfma_f32_16x16x32_bf16 v[6:9], v[172:175], v[212:215], v[6:9]
	v_mfma_f32_16x16x32_bf16 v[2:5], v[180:183], v[212:215], v[2:5]
	v_mfma_f32_16x16x32_bf16 v[54:57], v[176:179], v[192:195], v[54:57]
	v_mfma_f32_16x16x32_bf16 v[50:53], v[184:187], v[192:195], v[50:53]
	v_mfma_f32_16x16x32_bf16 v[38:41], v[176:179], v[200:203], v[38:41]
	v_mfma_f32_16x16x32_bf16 v[34:37], v[184:187], v[200:203], v[34:37]
	v_mfma_f32_16x16x32_bf16 v[22:25], v[176:179], v[208:211], v[22:25]
	v_mfma_f32_16x16x32_bf16 v[18:21], v[184:187], v[208:211], v[18:21]
	v_mfma_f32_16x16x32_bf16 v[6:9], v[176:179], v[216:219], v[6:9]
	v_mfma_f32_16x16x32_bf16 v[2:5], v[184:187], v[216:219], v[2:5]
	s_setprio 0
	s_barrier
	s_add_i32 s60, 0, 0x18000
	s_add_i32 s61, 0, 0x1c000
	v_add_u32_e32 v158, s60, v166
	v_add_u32_e32 v171, s61, v166
	ds_read_b128 v[130:133], v158
	ds_read_b128 v[134:137], v158 offset:1024
	ds_read_b128 v[154:157], v158 offset:2048
	ds_read_b128 v[158:161], v158 offset:3072
	ds_read_b128 v[172:175], v171
	ds_read_b128 v[176:179], v171 offset:1024
	ds_read_b128 v[180:183], v171 offset:2048
	ds_read_b128 v[184:187], v171 offset:3072
	s_add_u32 s44, s44, 0x40000
	s_addc_u32 s45, s45, 0
	s_mov_b32 m0, s46
	v_lshl_add_u64 v[226:227], s[44:45], 0, v[138:139]
	ds_read_b128 v[188:191], v170 offset:32768
	ds_read_b128 v[192:195], v170 offset:33792
	ds_read_b128 v[196:199], v170 offset:34816
	ds_read_b128 v[200:203], v170 offset:35840
	ds_read_b128 v[204:207], v170 offset:36864
	ds_read_b128 v[208:211], v170 offset:37888
	ds_read_b128 v[212:215], v170 offset:38912
	ds_read_b128 v[216:219], v170 offset:39936
	global_load_lds_dwordx4 v[226:227], off
	v_lshl_add_u64 v[226:227], s[44:45], 0, v[142:143]
	s_mov_b32 m0, s47
	s_nop 0
	global_load_lds_dwordx4 v[226:227], off
	s_waitcnt vmcnt(8)
	s_waitcnt lgkmcnt(0)
	s_barrier
	s_setprio 1
	s_waitcnt lgkmcnt(0)
	v_mfma_f32_16x16x32_bf16 v[126:129], v[130:133], v[188:191], v[126:129]
	v_mfma_f32_16x16x32_bf16 v[122:125], v[154:157], v[188:191], v[122:125]
	v_mfma_f32_16x16x32_bf16 v[110:113], v[130:133], v[196:199], v[110:113]
	v_mfma_f32_16x16x32_bf16 v[106:109], v[154:157], v[196:199], v[106:109]
	v_mfma_f32_16x16x32_bf16 v[94:97], v[130:133], v[204:207], v[94:97]
	v_mfma_f32_16x16x32_bf16 v[90:93], v[154:157], v[204:207], v[90:93]
	v_mfma_f32_16x16x32_bf16 v[82:85], v[130:133], v[212:215], v[82:85]
	v_mfma_f32_16x16x32_bf16 v[74:77], v[154:157], v[212:215], v[74:77]
	v_mfma_f32_16x16x32_bf16 v[126:129], v[134:137], v[192:195], v[126:129]
	v_mfma_f32_16x16x32_bf16 v[122:125], v[158:161], v[192:195], v[122:125]
	v_mfma_f32_16x16x32_bf16 v[110:113], v[134:137], v[200:203], v[110:113]
	v_mfma_f32_16x16x32_bf16 v[106:109], v[158:161], v[200:203], v[106:109]
	v_mfma_f32_16x16x32_bf16 v[94:97], v[134:137], v[208:211], v[94:97]
	v_mfma_f32_16x16x32_bf16 v[90:93], v[158:161], v[208:211], v[90:93]
	v_mfma_f32_16x16x32_bf16 v[82:85], v[134:137], v[216:219], v[82:85]
	v_mfma_f32_16x16x32_bf16 v[74:77], v[158:161], v[216:219], v[74:77]
	s_setprio 0
	s_setprio 1
	v_mfma_f32_16x16x32_bf16 v[118:121], v[172:175], v[188:191], v[118:121]
	v_mfma_f32_16x16x32_bf16 v[114:117], v[180:183], v[188:191], v[114:117]
	v_mfma_f32_16x16x32_bf16 v[102:105], v[172:175], v[196:199], v[102:105]
	v_mfma_f32_16x16x32_bf16 v[98:101], v[180:183], v[196:199], v[98:101]
	v_mfma_f32_16x16x32_bf16 v[86:89], v[172:175], v[204:207], v[86:89]
	v_mfma_f32_16x16x32_bf16 v[78:81], v[180:183], v[204:207], v[78:81]
	v_mfma_f32_16x16x32_bf16 v[70:73], v[172:175], v[212:215], v[70:73]
	v_mfma_f32_16x16x32_bf16 v[66:69], v[180:183], v[212:215], v[66:69]
	v_mfma_f32_16x16x32_bf16 v[118:121], v[176:179], v[192:195], v[118:121]
	v_mfma_f32_16x16x32_bf16 v[114:117], v[184:187], v[192:195], v[114:117]
	v_mfma_f32_16x16x32_bf16 v[102:105], v[176:179], v[200:203], v[102:105]
	v_mfma_f32_16x16x32_bf16 v[98:101], v[184:187], v[200:203], v[98:101]
	v_mfma_f32_16x16x32_bf16 v[86:89], v[176:179], v[208:211], v[86:89]
	v_mfma_f32_16x16x32_bf16 v[78:81], v[184:187], v[208:211], v[78:81]
	v_mfma_f32_16x16x32_bf16 v[70:73], v[176:179], v[216:219], v[70:73]
	v_mfma_f32_16x16x32_bf16 v[66:69], v[184:187], v[216:219], v[66:69]
	s_setprio 0
	s_barrier
	s_add_i32 s44, s60, s33
	v_lshl_add_u64 v[162:163], v[162:163], 0, s[12:13]
	s_mov_b32 m0, s44
	ds_read_b128 v[188:191], v170 offset:49152
	ds_read_b128 v[192:195], v170 offset:50176
	ds_read_b128 v[196:199], v170 offset:51200
	ds_read_b128 v[200:203], v170 offset:52224
	ds_read_b128 v[204:207], v170 offset:53248
	ds_read_b128 v[208:211], v170 offset:54272
	ds_read_b128 v[212:215], v170 offset:55296
	ds_read_b128 v[216:219], v170 offset:56320
	global_load_lds_dwordx4 v[162:163], off
	s_add_i32 m0, s44, 0x2000
	s_add_u32 s42, s42, 0x40080
	v_lshl_add_u64 v[162:163], v[220:221], 0, s[12:13]
	s_addc_u32 s43, s43, 0
	s_add_i32 s44, s61, s33
	global_load_lds_dwordx4 v[162:163], off
	v_lshl_add_u64 v[162:163], s[42:43], 0, v[140:141]
	s_mov_b32 m0, s44
	s_nop 0
	global_load_lds_dwordx4 v[162:163], off
	v_lshl_add_u64 v[162:163], s[42:43], 0, v[144:145]
	s_add_i32 m0, s44, 0x2000
	s_nop 0
	global_load_lds_dwordx4 v[162:163], off
	v_lshl_add_u64 v[162:163], v[222:223], 0, s[12:13]
	s_mov_b32 m0, s49
	s_nop 0
	global_load_lds_dwordx4 v[162:163], off
	v_lshl_add_u64 v[162:163], v[224:225], 0, s[12:13]
	s_mov_b32 m0, s50
	s_nop 0
	global_load_lds_dwordx4 v[162:163], off
	s_waitcnt vmcnt(8)
	s_waitcnt lgkmcnt(0)
	s_barrier
	s_setprio 1
	s_waitcnt lgkmcnt(0)
	v_mfma_f32_16x16x32_bf16 v[62:65], v[130:133], v[188:191], v[62:65]
	v_mfma_f32_16x16x32_bf16 v[58:61], v[154:157], v[188:191], v[58:61]
	v_mfma_f32_16x16x32_bf16 v[46:49], v[130:133], v[196:199], v[46:49]
	v_mfma_f32_16x16x32_bf16 v[42:45], v[154:157], v[196:199], v[42:45]
	v_mfma_f32_16x16x32_bf16 v[30:33], v[130:133], v[204:207], v[30:33]
	v_mfma_f32_16x16x32_bf16 v[26:29], v[154:157], v[204:207], v[26:29]
	v_mfma_f32_16x16x32_bf16 v[14:17], v[130:133], v[212:215], v[14:17]
	v_mfma_f32_16x16x32_bf16 v[10:13], v[154:157], v[212:215], v[10:13]
	v_mfma_f32_16x16x32_bf16 v[62:65], v[134:137], v[192:195], v[62:65]
	v_mfma_f32_16x16x32_bf16 v[58:61], v[158:161], v[192:195], v[58:61]
	v_mfma_f32_16x16x32_bf16 v[46:49], v[134:137], v[200:203], v[46:49]
	v_mfma_f32_16x16x32_bf16 v[42:45], v[158:161], v[200:203], v[42:45]
	v_mfma_f32_16x16x32_bf16 v[30:33], v[134:137], v[208:211], v[30:33]
	v_mfma_f32_16x16x32_bf16 v[26:29], v[158:161], v[208:211], v[26:29]
	v_mfma_f32_16x16x32_bf16 v[14:17], v[134:137], v[216:219], v[14:17]
	v_mfma_f32_16x16x32_bf16 v[10:13], v[158:161], v[216:219], v[10:13]
	s_setprio 0
	s_setprio 1
	v_mfma_f32_16x16x32_bf16 v[54:57], v[172:175], v[188:191], v[54:57]
	v_mfma_f32_16x16x32_bf16 v[50:53], v[180:183], v[188:191], v[50:53]
	v_mfma_f32_16x16x32_bf16 v[38:41], v[172:175], v[196:199], v[38:41]
	v_mfma_f32_16x16x32_bf16 v[34:37], v[180:183], v[196:199], v[34:37]
	v_mfma_f32_16x16x32_bf16 v[22:25], v[172:175], v[204:207], v[22:25]
	v_mfma_f32_16x16x32_bf16 v[18:21], v[180:183], v[204:207], v[18:21]
	v_mfma_f32_16x16x32_bf16 v[6:9], v[172:175], v[212:215], v[6:9]
	v_mfma_f32_16x16x32_bf16 v[2:5], v[180:183], v[212:215], v[2:5]
	v_mfma_f32_16x16x32_bf16 v[54:57], v[176:179], v[192:195], v[54:57]
	v_mfma_f32_16x16x32_bf16 v[50:53], v[184:187], v[192:195], v[50:53]
	v_mfma_f32_16x16x32_bf16 v[38:41], v[176:179], v[200:203], v[38:41]
	v_mfma_f32_16x16x32_bf16 v[34:37], v[184:187], v[200:203], v[34:37]
	v_mfma_f32_16x16x32_bf16 v[22:25], v[176:179], v[208:211], v[22:25]
	v_mfma_f32_16x16x32_bf16 v[18:21], v[184:187], v[208:211], v[18:21]
	v_mfma_f32_16x16x32_bf16 v[6:9], v[176:179], v[216:219], v[6:9]
	v_mfma_f32_16x16x32_bf16 v[2:5], v[184:187], v[216:219], v[2:5]
	s_setprio 0
	s_add_i32 s59, s59, 2
	s_add_u32 s40, s40, 0x100
	s_addc_u32 s41, s41, 0
	s_add_u32 s57, s57, 0x100
	s_addc_u32 s58, s58, 0
	s_cmp_gt_u32 s59, 13
	s_barrier
	s_cbranch_scc0 .LBB0_3029
	s_and_b64 vcc, exec, s[16:17]
	s_cbranch_vccz .LBB0_3032
	s_barrier

.LBB0_3131:
	ds_read_b128 v[130:133], v172
	ds_read_b128 v[134:137], v172 offset:1024
	ds_read_b128 v[156:159], v172 offset:2048
	ds_read_b128 v[176:179], v172 offset:3072
	ds_read_b128 v[180:183], v173
	ds_read_b128 v[184:187], v173 offset:1024
	ds_read_b128 v[188:191], v173 offset:2048
	ds_read_b128 v[192:195], v173 offset:3072
	s_add_u32 s46, s44, 0xfffc0080
	s_addc_u32 s47, s45, -1
	s_cmp_eq_u32 s71, 12
	s_cselect_b32 s49, s37, s47
	s_cselect_b32 s48, s43, s46
	s_cselect_b32 s47, s23, s70
	s_cselect_b32 s46, s68, s69
	v_lshl_add_u64 v[138:139], s[44:45], 0, v[148:149]
	s_add_i32 m0, s33, 0xc000
	ds_read_b128 v[196:199], v174
	ds_read_b128 v[200:203], v174 offset:1024
	ds_read_b128 v[204:207], v174 offset:2048
	ds_read_b128 v[208:211], v174 offset:3072
	ds_read_b128 v[212:215], v174 offset:4096
	ds_read_b128 v[216:219], v174 offset:5120
	ds_read_b128 v[220:223], v174 offset:6144
	ds_read_b128 v[224:227], v174 offset:7168
	global_load_lds_dwordx4 v[138:139], off
	v_lshl_add_u64 v[138:139], s[44:45], 0, v[150:151]
	s_add_i32 m0, s33, 0xe000
	s_nop 0
	global_load_lds_dwordx4 v[138:139], off
	s_waitcnt vmcnt(8)
	s_waitcnt lgkmcnt(0)
	s_barrier
	s_setprio 1
	s_waitcnt lgkmcnt(0)
	v_mfma_f32_16x16x32_bf16 v[126:129], v[130:133], v[196:199], v[126:129]
	v_mfma_f32_16x16x32_bf16 v[122:125], v[156:159], v[196:199], v[122:125]
	v_mfma_f32_16x16x32_bf16 v[110:113], v[130:133], v[204:207], v[110:113]
	v_mfma_f32_16x16x32_bf16 v[106:109], v[156:159], v[204:207], v[106:109]
	v_mfma_f32_16x16x32_bf16 v[94:97], v[130:133], v[212:215], v[94:97]
	v_mfma_f32_16x16x32_bf16 v[90:93], v[156:159], v[212:215], v[90:93]
	v_mfma_f32_16x16x32_bf16 v[78:81], v[130:133], v[220:223], v[78:81]
	v_mfma_f32_16x16x32_bf16 v[74:77], v[156:159], v[220:223], v[74:77]
	v_mfma_f32_16x16x32_bf16 v[126:129], v[134:137], v[200:203], v[126:129]
	v_mfma_f32_16x16x32_bf16 v[122:125], v[176:179], v[200:203], v[122:125]
	v_mfma_f32_16x16x32_bf16 v[110:113], v[134:137], v[208:211], v[110:113]
	v_mfma_f32_16x16x32_bf16 v[106:109], v[176:179], v[208:211], v[106:109]
	v_mfma_f32_16x16x32_bf16 v[94:97], v[134:137], v[216:219], v[94:97]
	v_mfma_f32_16x16x32_bf16 v[90:93], v[176:179], v[216:219], v[90:93]
	v_mfma_f32_16x16x32_bf16 v[78:81], v[134:137], v[224:227], v[78:81]
	v_mfma_f32_16x16x32_bf16 v[74:77], v[176:179], v[224:227], v[74:77]
	s_setprio 0
	s_setprio 1
	v_mfma_f32_16x16x32_bf16 v[118:121], v[180:183], v[196:199], v[118:121]
	v_mfma_f32_16x16x32_bf16 v[114:117], v[188:191], v[196:199], v[114:117]
	v_mfma_f32_16x16x32_bf16 v[102:105], v[180:183], v[204:207], v[102:105]
	v_mfma_f32_16x16x32_bf16 v[98:101], v[188:191], v[204:207], v[98:101]
	v_mfma_f32_16x16x32_bf16 v[86:89], v[180:183], v[212:215], v[86:89]
	v_mfma_f32_16x16x32_bf16 v[82:85], v[188:191], v[212:215], v[82:85]
	v_mfma_f32_16x16x32_bf16 v[70:73], v[180:183], v[220:223], v[70:73]
	v_mfma_f32_16x16x32_bf16 v[66:69], v[188:191], v[220:223], v[66:69]
	v_mfma_f32_16x16x32_bf16 v[118:121], v[184:187], v[200:203], v[118:121]
	v_mfma_f32_16x16x32_bf16 v[114:117], v[192:195], v[200:203], v[114:117]
	v_mfma_f32_16x16x32_bf16 v[102:105], v[184:187], v[208:211], v[102:105]
	v_mfma_f32_16x16x32_bf16 v[98:101], v[192:195], v[208:211], v[98:101]
	v_mfma_f32_16x16x32_bf16 v[86:89], v[184:187], v[216:219], v[86:89]
	v_mfma_f32_16x16x32_bf16 v[82:85], v[192:195], v[216:219], v[82:85]
	v_mfma_f32_16x16x32_bf16 v[70:73], v[184:187], v[224:227], v[70:73]
	v_mfma_f32_16x16x32_bf16 v[66:69], v[192:195], v[224:227], v[66:69]
	s_setprio 0
	s_barrier
	s_add_i32 s72, s60, s3
	v_lshl_add_u64 v[138:139], s[46:47], 0, v[142:143]
	s_mov_b32 m0, s72
	ds_read_b128 v[196:199], v174 offset:16384
	ds_read_b128 v[200:203], v174 offset:17408
	ds_read_b128 v[204:207], v174 offset:18432
	ds_read_b128 v[208:211], v174 offset:19456
	ds_read_b128 v[212:215], v174 offset:20480
	ds_read_b128 v[216:219], v174 offset:21504
	ds_read_b128 v[220:223], v174 offset:22528
	ds_read_b128 v[224:227], v174 offset:23552
	global_load_lds_dwordx4 v[138:139], off
	s_add_i32 m0, s72, 0x2000
	s_add_u32 s72, s46, 0x40000
	v_lshl_add_u64 v[160:161], s[46:47], 0, v[146:147]
	s_addc_u32 s73, s47, 0
	s_add_i32 s74, s61, s3
	global_load_lds_dwordx4 v[160:161], off
	v_lshl_add_u64 v[228:229], s[72:73], 0, v[142:143]
	s_mov_b32 m0, s74
	v_lshl_add_u64 v[230:231], s[48:49], 0, v[144:145]
	global_load_lds_dwordx4 v[228:229], off
	v_lshl_add_u64 v[228:229], s[72:73], 0, v[146:147]
	s_add_i32 m0, s74, 0x2000
	s_nop 0
	global_load_lds_dwordx4 v[228:229], off
	v_lshl_add_u64 v[228:229], s[48:49], 0, v[140:141]
	s_mov_b32 m0, s33
	s_nop 0
	global_load_lds_dwordx4 v[228:229], off
	s_mov_b32 m0, s35
	s_nop 0
	global_load_lds_dwordx4 v[230:231], off
	s_waitcnt vmcnt(8)
	s_waitcnt lgkmcnt(0)
	s_barrier
	s_setprio 1
	s_waitcnt lgkmcnt(0)
	v_mfma_f32_16x16x32_bf16 v[62:65], v[130:133], v[196:199], v[62:65]
	v_mfma_f32_16x16x32_bf16 v[58:61], v[156:159], v[196:199], v[58:61]
	v_mfma_f32_16x16x32_bf16 v[46:49], v[130:133], v[204:207], v[46:49]
	v_mfma_f32_16x16x32_bf16 v[42:45], v[156:159], v[204:207], v[42:45]
	v_mfma_f32_16x16x32_bf16 v[30:33], v[130:133], v[212:215], v[30:33]
	v_mfma_f32_16x16x32_bf16 v[26:29], v[156:159], v[212:215], v[26:29]
	v_mfma_f32_16x16x32_bf16 v[14:17], v[130:133], v[220:223], v[14:17]
	v_mfma_f32_16x16x32_bf16 v[10:13], v[156:159], v[220:223], v[10:13]
	v_mfma_f32_16x16x32_bf16 v[62:65], v[134:137], v[200:203], v[62:65]
	v_mfma_f32_16x16x32_bf16 v[58:61], v[176:179], v[200:203], v[58:61]
	v_mfma_f32_16x16x32_bf16 v[46:49], v[134:137], v[208:211], v[46:49]
	v_mfma_f32_16x16x32_bf16 v[42:45], v[176:179], v[208:211], v[42:45]
	v_mfma_f32_16x16x32_bf16 v[30:33], v[134:137], v[216:219], v[30:33]
	v_mfma_f32_16x16x32_bf16 v[26:29], v[176:179], v[216:219], v[26:29]
	v_mfma_f32_16x16x32_bf16 v[14:17], v[134:137], v[224:227], v[14:17]
	v_mfma_f32_16x16x32_bf16 v[10:13], v[176:179], v[224:227], v[10:13]
	s_setprio 0
	s_setprio 1
	v_mfma_f32_16x16x32_bf16 v[54:57], v[180:183], v[196:199], v[54:57]
	v_mfma_f32_16x16x32_bf16 v[50:53], v[188:191], v[196:199], v[50:53]
	v_mfma_f32_16x16x32_bf16 v[38:41], v[180:183], v[204:207], v[38:41]
	v_mfma_f32_16x16x32_bf16 v[34:37], v[188:191], v[204:207], v[34:37]
	v_mfma_f32_16x16x32_bf16 v[22:25], v[180:183], v[212:215], v[22:25]
	v_mfma_f32_16x16x32_bf16 v[18:21], v[188:191], v[212:215], v[18:21]
	v_mfma_f32_16x16x32_bf16 v[6:9], v[180:183], v[220:223], v[6:9]
	v_mfma_f32_16x16x32_bf16 v[2:5], v[188:191], v[220:223], v[2:5]
	v_mfma_f32_16x16x32_bf16 v[54:57], v[184:187], v[200:203], v[54:57]
	v_mfma_f32_16x16x32_bf16 v[50:53], v[192:195], v[200:203], v[50:53]
	v_mfma_f32_16x16x32_bf16 v[38:41], v[184:187], v[208:211], v[38:41]
	v_mfma_f32_16x16x32_bf16 v[34:37], v[192:195], v[208:211], v[34:37]
	v_mfma_f32_16x16x32_bf16 v[22:25], v[184:187], v[216:219], v[22:25]
	v_mfma_f32_16x16x32_bf16 v[18:21], v[192:195], v[216:219], v[18:21]
	v_mfma_f32_16x16x32_bf16 v[6:9], v[184:187], v[224:227], v[6:9]
	v_mfma_f32_16x16x32_bf16 v[2:5], v[192:195], v[224:227], v[2:5]
	s_setprio 0
	s_barrier
	s_add_i32 s72, 0, 0x18000
	s_add_i32 s73, 0, 0x1c000
	v_add_u32_e32 v176, s72, v166
	v_add_u32_e32 v192, s73, v166
	ds_read_b128 v[130:133], v176
	ds_read_b128 v[134:137], v176 offset:1024
	ds_read_b128 v[156:159], v176 offset:2048
	ds_read_b128 v[176:179], v176 offset:3072
	ds_read_b128 v[180:183], v192
	ds_read_b128 v[184:187], v192 offset:1024
	ds_read_b128 v[188:191], v192 offset:2048
	ds_read_b128 v[192:195], v192 offset:3072
	s_add_u32 s48, s48, 0x40000
	s_addc_u32 s49, s49, 0
	s_mov_b32 m0, s50
	v_lshl_add_u64 v[232:233], s[48:49], 0, v[140:141]
	ds_read_b128 v[196:199], v174 offset:32768
	ds_read_b128 v[200:203], v174 offset:33792
	ds_read_b128 v[204:207], v174 offset:34816
	ds_read_b128 v[208:211], v174 offset:35840
	ds_read_b128 v[212:215], v174 offset:36864
	ds_read_b128 v[216:219], v174 offset:37888
	ds_read_b128 v[220:223], v174 offset:38912
	ds_read_b128 v[224:227], v174 offset:39936
	global_load_lds_dwordx4 v[232:233], off
	v_lshl_add_u64 v[232:233], s[48:49], 0, v[144:145]
	s_mov_b32 m0, s51
	s_nop 0
	global_load_lds_dwordx4 v[232:233], off
	s_waitcnt vmcnt(8)
	s_waitcnt lgkmcnt(0)
	s_barrier
	s_setprio 1
	s_waitcnt lgkmcnt(0)
	v_mfma_f32_16x16x32_bf16 v[126:129], v[130:133], v[196:199], v[126:129]
	v_mfma_f32_16x16x32_bf16 v[122:125], v[156:159], v[196:199], v[122:125]
	v_mfma_f32_16x16x32_bf16 v[110:113], v[130:133], v[204:207], v[110:113]
	v_mfma_f32_16x16x32_bf16 v[106:109], v[156:159], v[204:207], v[106:109]
	v_mfma_f32_16x16x32_bf16 v[94:97], v[130:133], v[212:215], v[94:97]
	v_mfma_f32_16x16x32_bf16 v[90:93], v[156:159], v[212:215], v[90:93]
	v_mfma_f32_16x16x32_bf16 v[78:81], v[130:133], v[220:223], v[78:81]
	v_mfma_f32_16x16x32_bf16 v[74:77], v[156:159], v[220:223], v[74:77]
	v_mfma_f32_16x16x32_bf16 v[126:129], v[134:137], v[200:203], v[126:129]
	v_mfma_f32_16x16x32_bf16 v[122:125], v[176:179], v[200:203], v[122:125]
	v_mfma_f32_16x16x32_bf16 v[110:113], v[134:137], v[208:211], v[110:113]
	v_mfma_f32_16x16x32_bf16 v[106:109], v[176:179], v[208:211], v[106:109]
	v_mfma_f32_16x16x32_bf16 v[94:97], v[134:137], v[216:219], v[94:97]
	v_mfma_f32_16x16x32_bf16 v[90:93], v[176:179], v[216:219], v[90:93]
	v_mfma_f32_16x16x32_bf16 v[78:81], v[134:137], v[224:227], v[78:81]
	v_mfma_f32_16x16x32_bf16 v[74:77], v[176:179], v[224:227], v[74:77]
	s_setprio 0
	s_setprio 1
	v_mfma_f32_16x16x32_bf16 v[118:121], v[180:183], v[196:199], v[118:121]
	v_mfma_f32_16x16x32_bf16 v[114:117], v[188:191], v[196:199], v[114:117]
	v_mfma_f32_16x16x32_bf16 v[102:105], v[180:183], v[204:207], v[102:105]
	v_mfma_f32_16x16x32_bf16 v[98:101], v[188:191], v[204:207], v[98:101]
	v_mfma_f32_16x16x32_bf16 v[86:89], v[180:183], v[212:215], v[86:89]
	v_mfma_f32_16x16x32_bf16 v[82:85], v[188:191], v[212:215], v[82:85]
	v_mfma_f32_16x16x32_bf16 v[70:73], v[180:183], v[220:223], v[70:73]
	v_mfma_f32_16x16x32_bf16 v[66:69], v[188:191], v[220:223], v[66:69]
	v_mfma_f32_16x16x32_bf16 v[118:121], v[184:187], v[200:203], v[118:121]
	v_mfma_f32_16x16x32_bf16 v[114:117], v[192:195], v[200:203], v[114:117]
	v_mfma_f32_16x16x32_bf16 v[102:105], v[184:187], v[208:211], v[102:105]
	v_mfma_f32_16x16x32_bf16 v[98:101], v[192:195], v[208:211], v[98:101]
	v_mfma_f32_16x16x32_bf16 v[86:89], v[184:187], v[216:219], v[86:89]
	v_mfma_f32_16x16x32_bf16 v[82:85], v[192:195], v[216:219], v[82:85]
	v_mfma_f32_16x16x32_bf16 v[70:73], v[184:187], v[224:227], v[70:73]
	v_mfma_f32_16x16x32_bf16 v[66:69], v[192:195], v[224:227], v[66:69]
	s_setprio 0
	s_barrier
	s_add_i32 s48, s72, s3
	v_lshl_add_u64 v[138:139], v[138:139], 0, s[18:19]
	s_mov_b32 m0, s48
	ds_read_b128 v[196:199], v174 offset:49152
	ds_read_b128 v[200:203], v174 offset:50176
	ds_read_b128 v[204:207], v174 offset:51200
	ds_read_b128 v[208:211], v174 offset:52224
	ds_read_b128 v[212:215], v174 offset:53248
	ds_read_b128 v[216:219], v174 offset:54272
	ds_read_b128 v[220:223], v174 offset:55296
	ds_read_b128 v[224:227], v174 offset:56320
	global_load_lds_dwordx4 v[138:139], off
	s_add_i32 m0, s48, 0x2000
	s_add_u32 s46, s46, 0x40080
	v_lshl_add_u64 v[138:139], v[160:161], 0, s[18:19]
	s_addc_u32 s47, s47, 0
	s_add_i32 s48, s73, s3
	global_load_lds_dwordx4 v[138:139], off
	v_lshl_add_u64 v[138:139], s[46:47], 0, v[142:143]
	s_mov_b32 m0, s48
	s_nop 0
	global_load_lds_dwordx4 v[138:139], off
	v_lshl_add_u64 v[138:139], s[46:47], 0, v[146:147]
	s_add_i32 m0, s48, 0x2000
	s_nop 0
	global_load_lds_dwordx4 v[138:139], off
	v_lshl_add_u64 v[138:139], v[228:229], 0, s[18:19]
	s_mov_b32 m0, s54
	s_nop 0
	global_load_lds_dwordx4 v[138:139], off
	v_lshl_add_u64 v[138:139], v[230:231], 0, s[18:19]
	s_mov_b32 m0, s55
	s_nop 0
	global_load_lds_dwordx4 v[138:139], off
	s_waitcnt vmcnt(8)
	s_waitcnt lgkmcnt(0)
	s_barrier
	s_setprio 1
	s_waitcnt lgkmcnt(0)
	v_mfma_f32_16x16x32_bf16 v[62:65], v[130:133], v[196:199], v[62:65]
	v_mfma_f32_16x16x32_bf16 v[58:61], v[156:159], v[196:199], v[58:61]
	v_mfma_f32_16x16x32_bf16 v[46:49], v[130:133], v[204:207], v[46:49]
	v_mfma_f32_16x16x32_bf16 v[42:45], v[156:159], v[204:207], v[42:45]
	v_mfma_f32_16x16x32_bf16 v[30:33], v[130:133], v[212:215], v[30:33]
	v_mfma_f32_16x16x32_bf16 v[26:29], v[156:159], v[212:215], v[26:29]
	v_mfma_f32_16x16x32_bf16 v[14:17], v[130:133], v[220:223], v[14:17]
	v_mfma_f32_16x16x32_bf16 v[10:13], v[156:159], v[220:223], v[10:13]
	v_mfma_f32_16x16x32_bf16 v[62:65], v[134:137], v[200:203], v[62:65]
	v_mfma_f32_16x16x32_bf16 v[58:61], v[176:179], v[200:203], v[58:61]
	v_mfma_f32_16x16x32_bf16 v[46:49], v[134:137], v[208:211], v[46:49]
	v_mfma_f32_16x16x32_bf16 v[42:45], v[176:179], v[208:211], v[42:45]
	v_mfma_f32_16x16x32_bf16 v[30:33], v[134:137], v[216:219], v[30:33]
	v_mfma_f32_16x16x32_bf16 v[26:29], v[176:179], v[216:219], v[26:29]
	v_mfma_f32_16x16x32_bf16 v[14:17], v[134:137], v[224:227], v[14:17]
	v_mfma_f32_16x16x32_bf16 v[10:13], v[176:179], v[224:227], v[10:13]
	s_setprio 0
	s_setprio 1
	v_mfma_f32_16x16x32_bf16 v[54:57], v[180:183], v[196:199], v[54:57]
	v_mfma_f32_16x16x32_bf16 v[50:53], v[188:191], v[196:199], v[50:53]
	v_mfma_f32_16x16x32_bf16 v[38:41], v[180:183], v[204:207], v[38:41]
	v_mfma_f32_16x16x32_bf16 v[34:37], v[188:191], v[204:207], v[34:37]
	v_mfma_f32_16x16x32_bf16 v[22:25], v[180:183], v[212:215], v[22:25]
	v_mfma_f32_16x16x32_bf16 v[18:21], v[188:191], v[212:215], v[18:21]
	v_mfma_f32_16x16x32_bf16 v[6:9], v[180:183], v[220:223], v[6:9]
	v_mfma_f32_16x16x32_bf16 v[2:5], v[188:191], v[220:223], v[2:5]
	v_mfma_f32_16x16x32_bf16 v[54:57], v[184:187], v[200:203], v[54:57]
	v_mfma_f32_16x16x32_bf16 v[50:53], v[192:195], v[200:203], v[50:53]
	v_mfma_f32_16x16x32_bf16 v[38:41], v[184:187], v[208:211], v[38:41]
	v_mfma_f32_16x16x32_bf16 v[34:37], v[192:195], v[208:211], v[34:37]
	v_mfma_f32_16x16x32_bf16 v[22:25], v[184:187], v[216:219], v[22:25]
	v_mfma_f32_16x16x32_bf16 v[18:21], v[192:195], v[216:219], v[18:21]
	v_mfma_f32_16x16x32_bf16 v[6:9], v[184:187], v[224:227], v[6:9]
	v_mfma_f32_16x16x32_bf16 v[2:5], v[192:195], v[224:227], v[2:5]
	s_setprio 0
	s_add_i32 s71, s71, 2
	s_add_u32 s44, s44, 0x100
	s_addc_u32 s45, s45, 0
	s_add_u32 s69, s69, 0x100
	s_addc_u32 s70, s70, 0
	s_cmp_gt_u32 s71, 13
	s_barrier
	s_cbranch_scc0 .LBB0_3131
	s_and_b64 vcc, exec, s[20:21]
	s_cbranch_vccz .LBB0_3134
	s_barrier

.LBB0_3240:
	s_or_b64 exec, exec, s[10:11]
	v_cvt_f32_u32_e32 v5, v3
	s_waitcnt vmcnt(0)
	v_readfirstlane_b32 s3, v4
	v_sub_u32_e32 v4, 0, v3
	v_rcp_iflag_f32_e32 v5, v5
	v_add_u32_e32 v6, s3, v2
	v_mul_f32_e32 v5, 0x4f7ffffe, v5
	v_cvt_u32_f32_e32 v5, v5
	v_mul_lo_u32 v2, v4, v5
	v_mul_hi_u32 v2, v5, v2
	v_add_u32_e32 v2, v5, v2
	v_mul_hi_u32 v2, v6, v2
	v_mul_lo_u32 v4, v2, v3
	v_sub_u32_e32 v4, v6, v4
	v_add_u32_e32 v5, 1, v2
	v_cmp_ge_u32_e32 vcc, v4, v3
	s_nop 1
	v_cndmask_b32_e32 v2, v2, v5, vcc
	v_sub_u32_e32 v5, v4, v3
	v_cndmask_b32_e32 v4, v4, v5, vcc
	v_add_u32_e32 v5, 1, v2
	v_cmp_ge_u32_e32 vcc, v4, v3
	v_add_u32_e32 v4, 1, v6
	s_nop 0
	v_cndmask_b32_e32 v2, v2, v5, vcc
	v_mul_lo_u32 v5, v3, v2
	v_add_u32_e32 v3, v5, v3
	v_cmp_ne_u32_e32 vcc, v4, v3
	s_and_saveexec_b64 s[8:9], vcc
	s_xor_b64 s[8:9], exec, s[8:9]
	s_cbranch_execz .LBB0_3254
	s_waitcnt lgkmcnt(0)
	s_add_u32 s16, s28, 0xf190900
	s_addc_u32 s17, s29, 0
	v_mov_b32_e32 v1, 0
	global_load_dword v1, v1, s[16:17] sc1
	s_waitcnt vmcnt(0)
	v_cmp_eq_u32_e32 vcc, v1, v2
	s_and_saveexec_b64 s[10:11], vcc
	s_cbranch_execz .LBB0_3253
	s_add_u32 s14, s28, 0xf18d600
	s_addc_u32 s15, s29, 0
	s_mov_b32 s3, 1
	s_mov_b64 s[18:19], 0
	v_mov_b32_e32 v1, 0
	s_branch .LBB0_3244

.LBB0_3293:
	ds_read_b128 v[148:151], v156
	ds_read_b128 v[162:165], v156 offset:1024
	ds_read_b128 v[166:169], v156 offset:2048
	ds_read_b128 v[170:173], v156 offset:3072
	ds_read_b128 v[174:177], v157
	ds_read_b128 v[178:181], v157 offset:1024
	ds_read_b128 v[182:185], v157 offset:2048
	ds_read_b128 v[186:189], v157 offset:3072
	s_add_u32 s36, s22, 0xfffc0080
	s_addc_u32 s37, s23, -1
	s_cmp_eq_u32 s57, 12
	s_cselect_b32 s39, s17, s37
	s_cselect_b32 s38, s53, s36
	s_cselect_b32 s37, s13, s56
	s_cselect_b32 s36, s54, s55
	v_lshl_add_u64 v[152:153], s[22:23], 0, v[140:141]
	s_add_i32 m0, s41, 0xc000
	ds_read_b128 v[190:193], v158
	ds_read_b128 v[194:197], v158 offset:1024
	ds_read_b128 v[198:201], v158 offset:2048
	ds_read_b128 v[202:205], v158 offset:3072
	ds_read_b128 v[206:209], v158 offset:4096
	ds_read_b128 v[210:213], v158 offset:5120
	ds_read_b128 v[214:217], v158 offset:6144
	ds_read_b128 v[218:221], v158 offset:7168
	global_load_lds_dwordx4 v[152:153], off
	v_lshl_add_u64 v[152:153], s[22:23], 0, v[142:143]
	s_add_i32 m0, s41, 0xe000
	s_nop 0
	global_load_lds_dwordx4 v[152:153], off
	s_waitcnt vmcnt(8)
	s_waitcnt lgkmcnt(0)
	s_barrier
	s_setprio 1
	s_waitcnt lgkmcnt(0)
	v_mfma_f32_16x16x32_bf16 v[126:129], v[148:151], v[190:193], v[126:129]
	v_mfma_f32_16x16x32_bf16 v[122:125], v[166:169], v[190:193], v[122:125]
	v_mfma_f32_16x16x32_bf16 v[110:113], v[148:151], v[198:201], v[110:113]
	v_mfma_f32_16x16x32_bf16 v[106:109], v[166:169], v[198:201], v[106:109]
	v_mfma_f32_16x16x32_bf16 v[94:97], v[148:151], v[206:209], v[94:97]
	v_mfma_f32_16x16x32_bf16 v[90:93], v[166:169], v[206:209], v[90:93]
	v_mfma_f32_16x16x32_bf16 v[78:81], v[148:151], v[214:217], v[78:81]
	v_mfma_f32_16x16x32_bf16 v[74:77], v[166:169], v[214:217], v[74:77]
	v_mfma_f32_16x16x32_bf16 v[126:129], v[162:165], v[194:197], v[126:129]
	v_mfma_f32_16x16x32_bf16 v[122:125], v[170:173], v[194:197], v[122:125]
	v_mfma_f32_16x16x32_bf16 v[110:113], v[162:165], v[202:205], v[110:113]
	v_mfma_f32_16x16x32_bf16 v[106:109], v[170:173], v[202:205], v[106:109]
	v_mfma_f32_16x16x32_bf16 v[94:97], v[162:165], v[210:213], v[94:97]
	v_mfma_f32_16x16x32_bf16 v[90:93], v[170:173], v[210:213], v[90:93]
	v_mfma_f32_16x16x32_bf16 v[78:81], v[162:165], v[218:221], v[78:81]
	v_mfma_f32_16x16x32_bf16 v[74:77], v[170:173], v[218:221], v[74:77]
	s_setprio 0
	s_setprio 1
	v_mfma_f32_16x16x32_bf16 v[118:121], v[174:177], v[190:193], v[118:121]
	v_mfma_f32_16x16x32_bf16 v[114:117], v[182:185], v[190:193], v[114:117]
	v_mfma_f32_16x16x32_bf16 v[102:105], v[174:177], v[198:201], v[102:105]
	v_mfma_f32_16x16x32_bf16 v[98:101], v[182:185], v[198:201], v[98:101]
	v_mfma_f32_16x16x32_bf16 v[86:89], v[174:177], v[206:209], v[86:89]
	v_mfma_f32_16x16x32_bf16 v[82:85], v[182:185], v[206:209], v[82:85]
	v_mfma_f32_16x16x32_bf16 v[70:73], v[174:177], v[214:217], v[70:73]
	v_mfma_f32_16x16x32_bf16 v[66:69], v[182:185], v[214:217], v[66:69]
	v_mfma_f32_16x16x32_bf16 v[118:121], v[178:181], v[194:197], v[118:121]
	v_mfma_f32_16x16x32_bf16 v[114:117], v[186:189], v[194:197], v[114:117]
	v_mfma_f32_16x16x32_bf16 v[102:105], v[178:181], v[202:205], v[102:105]
	v_mfma_f32_16x16x32_bf16 v[98:101], v[186:189], v[202:205], v[98:101]
	v_mfma_f32_16x16x32_bf16 v[86:89], v[178:181], v[210:213], v[86:89]
	v_mfma_f32_16x16x32_bf16 v[82:85], v[186:189], v[210:213], v[82:85]
	v_mfma_f32_16x16x32_bf16 v[70:73], v[178:181], v[218:221], v[70:73]
	v_mfma_f32_16x16x32_bf16 v[66:69], v[186:189], v[218:221], v[66:69]
	s_setprio 0
	s_barrier
	s_add_i32 s58, s49, s40
	v_lshl_add_u64 v[152:153], s[36:37], 0, v[132:133]
	s_mov_b32 m0, s58
	ds_read_b128 v[190:193], v158 offset:16384
	ds_read_b128 v[194:197], v158 offset:17408
	ds_read_b128 v[198:201], v158 offset:18432
	ds_read_b128 v[202:205], v158 offset:19456
	ds_read_b128 v[206:209], v158 offset:20480
	ds_read_b128 v[210:213], v158 offset:21504
	ds_read_b128 v[214:217], v158 offset:22528
	ds_read_b128 v[218:221], v158 offset:23552
	global_load_lds_dwordx4 v[152:153], off
	s_add_i32 m0, s58, 0x2000
	s_add_u32 s58, s36, 0x40000
	v_lshl_add_u64 v[222:223], s[36:37], 0, v[136:137]
	s_addc_u32 s59, s37, 0
	s_add_i32 s60, s50, s40
	global_load_lds_dwordx4 v[222:223], off
	v_lshl_add_u64 v[224:225], s[58:59], 0, v[132:133]
	s_mov_b32 m0, s60
	v_lshl_add_u64 v[226:227], s[38:39], 0, v[134:135]
	global_load_lds_dwordx4 v[224:225], off
	v_lshl_add_u64 v[224:225], s[58:59], 0, v[136:137]
	s_add_i32 m0, s60, 0x2000
	s_nop 0
	global_load_lds_dwordx4 v[224:225], off
	v_lshl_add_u64 v[224:225], s[38:39], 0, v[130:131]
	s_mov_b32 m0, s41
	s_nop 0
	global_load_lds_dwordx4 v[224:225], off
	s_mov_b32 m0, s42
	s_nop 0
	global_load_lds_dwordx4 v[226:227], off
	s_waitcnt vmcnt(8)
	s_waitcnt lgkmcnt(0)
	s_barrier
	s_setprio 1
	s_waitcnt lgkmcnt(0)
	v_mfma_f32_16x16x32_bf16 v[62:65], v[148:151], v[190:193], v[62:65]
	v_mfma_f32_16x16x32_bf16 v[58:61], v[166:169], v[190:193], v[58:61]
	v_mfma_f32_16x16x32_bf16 v[46:49], v[148:151], v[198:201], v[46:49]
	v_mfma_f32_16x16x32_bf16 v[42:45], v[166:169], v[198:201], v[42:45]
	v_mfma_f32_16x16x32_bf16 v[30:33], v[148:151], v[206:209], v[30:33]
	v_mfma_f32_16x16x32_bf16 v[26:29], v[166:169], v[206:209], v[26:29]
	v_mfma_f32_16x16x32_bf16 v[14:17], v[148:151], v[214:217], v[14:17]
	v_mfma_f32_16x16x32_bf16 v[10:13], v[166:169], v[214:217], v[10:13]
	v_mfma_f32_16x16x32_bf16 v[62:65], v[162:165], v[194:197], v[62:65]
	v_mfma_f32_16x16x32_bf16 v[58:61], v[170:173], v[194:197], v[58:61]
	v_mfma_f32_16x16x32_bf16 v[46:49], v[162:165], v[202:205], v[46:49]
	v_mfma_f32_16x16x32_bf16 v[42:45], v[170:173], v[202:205], v[42:45]
	v_mfma_f32_16x16x32_bf16 v[30:33], v[162:165], v[210:213], v[30:33]
	v_mfma_f32_16x16x32_bf16 v[26:29], v[170:173], v[210:213], v[26:29]
	v_mfma_f32_16x16x32_bf16 v[14:17], v[162:165], v[218:221], v[14:17]
	v_mfma_f32_16x16x32_bf16 v[10:13], v[170:173], v[218:221], v[10:13]
	s_setprio 0
	s_setprio 1
	v_mfma_f32_16x16x32_bf16 v[54:57], v[174:177], v[190:193], v[54:57]
	v_mfma_f32_16x16x32_bf16 v[50:53], v[182:185], v[190:193], v[50:53]
	v_mfma_f32_16x16x32_bf16 v[38:41], v[174:177], v[198:201], v[38:41]
	v_mfma_f32_16x16x32_bf16 v[34:37], v[182:185], v[198:201], v[34:37]
	v_mfma_f32_16x16x32_bf16 v[22:25], v[174:177], v[206:209], v[22:25]
	v_mfma_f32_16x16x32_bf16 v[18:21], v[182:185], v[206:209], v[18:21]
	v_mfma_f32_16x16x32_bf16 v[6:9], v[174:177], v[214:217], v[6:9]
	v_mfma_f32_16x16x32_bf16 v[2:5], v[182:185], v[214:217], v[2:5]
	v_mfma_f32_16x16x32_bf16 v[54:57], v[178:181], v[194:197], v[54:57]
	v_mfma_f32_16x16x32_bf16 v[50:53], v[186:189], v[194:197], v[50:53]
	v_mfma_f32_16x16x32_bf16 v[38:41], v[178:181], v[202:205], v[38:41]
	v_mfma_f32_16x16x32_bf16 v[34:37], v[186:189], v[202:205], v[34:37]
	v_mfma_f32_16x16x32_bf16 v[22:25], v[178:181], v[210:213], v[22:25]
	v_mfma_f32_16x16x32_bf16 v[18:21], v[186:189], v[210:213], v[18:21]
	v_mfma_f32_16x16x32_bf16 v[6:9], v[178:181], v[218:221], v[6:9]
	v_mfma_f32_16x16x32_bf16 v[2:5], v[186:189], v[218:221], v[2:5]
	s_setprio 0
	s_barrier
	s_add_i32 s58, 0, 0x18000
	v_add_u32_e32 v161, s58, v154
	s_add_i32 s59, 0, 0x1c000
	ds_read_b128 v[148:151], v161
	ds_read_b128 v[162:165], v161 offset:1024
	ds_read_b128 v[166:169], v161 offset:2048
	ds_read_b128 v[170:173], v161 offset:3072
	v_add_u32_e32 v161, s59, v154
	ds_read_b128 v[174:177], v161
	ds_read_b128 v[178:181], v161 offset:1024
	ds_read_b128 v[182:185], v161 offset:2048
	ds_read_b128 v[186:189], v161 offset:3072
	s_add_u32 s38, s38, 0x40000
	s_addc_u32 s39, s39, 0
	s_mov_b32 m0, s43
	v_lshl_add_u64 v[228:229], s[38:39], 0, v[130:131]
	ds_read_b128 v[190:193], v158 offset:32768
	ds_read_b128 v[194:197], v158 offset:33792
	ds_read_b128 v[198:201], v158 offset:34816
	ds_read_b128 v[202:205], v158 offset:35840
	ds_read_b128 v[206:209], v158 offset:36864
	ds_read_b128 v[210:213], v158 offset:37888
	ds_read_b128 v[214:217], v158 offset:38912
	ds_read_b128 v[218:221], v158 offset:39936
	global_load_lds_dwordx4 v[228:229], off
	v_lshl_add_u64 v[228:229], s[38:39], 0, v[134:135]
	s_mov_b32 m0, s44
	s_nop 0
	global_load_lds_dwordx4 v[228:229], off
	s_waitcnt vmcnt(8)
	s_waitcnt lgkmcnt(0)
	s_barrier
	s_setprio 1
	s_waitcnt lgkmcnt(0)
	v_mfma_f32_16x16x32_bf16 v[126:129], v[148:151], v[190:193], v[126:129]
	v_mfma_f32_16x16x32_bf16 v[122:125], v[166:169], v[190:193], v[122:125]
	v_mfma_f32_16x16x32_bf16 v[110:113], v[148:151], v[198:201], v[110:113]
	v_mfma_f32_16x16x32_bf16 v[106:109], v[166:169], v[198:201], v[106:109]
	v_mfma_f32_16x16x32_bf16 v[94:97], v[148:151], v[206:209], v[94:97]
	v_mfma_f32_16x16x32_bf16 v[90:93], v[166:169], v[206:209], v[90:93]
	v_mfma_f32_16x16x32_bf16 v[78:81], v[148:151], v[214:217], v[78:81]
	v_mfma_f32_16x16x32_bf16 v[74:77], v[166:169], v[214:217], v[74:77]
	v_mfma_f32_16x16x32_bf16 v[126:129], v[162:165], v[194:197], v[126:129]
	v_mfma_f32_16x16x32_bf16 v[122:125], v[170:173], v[194:197], v[122:125]
	v_mfma_f32_16x16x32_bf16 v[110:113], v[162:165], v[202:205], v[110:113]
	v_mfma_f32_16x16x32_bf16 v[106:109], v[170:173], v[202:205], v[106:109]
	v_mfma_f32_16x16x32_bf16 v[94:97], v[162:165], v[210:213], v[94:97]
	v_mfma_f32_16x16x32_bf16 v[90:93], v[170:173], v[210:213], v[90:93]
	v_mfma_f32_16x16x32_bf16 v[78:81], v[162:165], v[218:221], v[78:81]
	v_mfma_f32_16x16x32_bf16 v[74:77], v[170:173], v[218:221], v[74:77]
	s_setprio 0
	s_setprio 1
	v_mfma_f32_16x16x32_bf16 v[118:121], v[174:177], v[190:193], v[118:121]
	v_mfma_f32_16x16x32_bf16 v[114:117], v[182:185], v[190:193], v[114:117]
	v_mfma_f32_16x16x32_bf16 v[102:105], v[174:177], v[198:201], v[102:105]
	v_mfma_f32_16x16x32_bf16 v[98:101], v[182:185], v[198:201], v[98:101]
	v_mfma_f32_16x16x32_bf16 v[86:89], v[174:177], v[206:209], v[86:89]
	v_mfma_f32_16x16x32_bf16 v[82:85], v[182:185], v[206:209], v[82:85]
	v_mfma_f32_16x16x32_bf16 v[70:73], v[174:177], v[214:217], v[70:73]
	v_mfma_f32_16x16x32_bf16 v[66:69], v[182:185], v[214:217], v[66:69]
	v_mfma_f32_16x16x32_bf16 v[118:121], v[178:181], v[194:197], v[118:121]
	v_mfma_f32_16x16x32_bf16 v[114:117], v[186:189], v[194:197], v[114:117]
	v_mfma_f32_16x16x32_bf16 v[102:105], v[178:181], v[202:205], v[102:105]
	v_mfma_f32_16x16x32_bf16 v[98:101], v[186:189], v[202:205], v[98:101]
	v_mfma_f32_16x16x32_bf16 v[86:89], v[178:181], v[210:213], v[86:89]
	v_mfma_f32_16x16x32_bf16 v[82:85], v[186:189], v[210:213], v[82:85]
	v_mfma_f32_16x16x32_bf16 v[70:73], v[178:181], v[218:221], v[70:73]
	v_mfma_f32_16x16x32_bf16 v[66:69], v[186:189], v[218:221], v[66:69]
	s_setprio 0
	s_barrier
	s_add_i32 s38, s58, s40
	v_lshl_add_u64 v[152:153], v[152:153], 0, s[10:11]
	s_mov_b32 m0, s38
	ds_read_b128 v[190:193], v158 offset:49152
	ds_read_b128 v[194:197], v158 offset:50176
	ds_read_b128 v[198:201], v158 offset:51200
	ds_read_b128 v[202:205], v158 offset:52224
	ds_read_b128 v[206:209], v158 offset:53248
	ds_read_b128 v[210:213], v158 offset:54272
	ds_read_b128 v[214:217], v158 offset:55296
	ds_read_b128 v[218:221], v158 offset:56320
	global_load_lds_dwordx4 v[152:153], off
	s_add_i32 m0, s38, 0x2000
	s_add_u32 s36, s36, 0x40080
	v_lshl_add_u64 v[152:153], v[222:223], 0, s[10:11]
	s_addc_u32 s37, s37, 0
	s_add_i32 s38, s59, s40
	global_load_lds_dwordx4 v[152:153], off
	v_lshl_add_u64 v[152:153], s[36:37], 0, v[132:133]
	s_mov_b32 m0, s38
	s_nop 0
	global_load_lds_dwordx4 v[152:153], off
	v_lshl_add_u64 v[152:153], s[36:37], 0, v[136:137]
	s_add_i32 m0, s38, 0x2000
	s_nop 0
	global_load_lds_dwordx4 v[152:153], off
	v_lshl_add_u64 v[152:153], v[224:225], 0, s[10:11]
	s_mov_b32 m0, s46
	s_nop 0
	global_load_lds_dwordx4 v[152:153], off
	v_lshl_add_u64 v[152:153], v[226:227], 0, s[10:11]
	s_mov_b32 m0, s47
	s_nop 0
	global_load_lds_dwordx4 v[152:153], off
	s_waitcnt vmcnt(8)
	s_waitcnt lgkmcnt(0)
	s_barrier
	s_setprio 1
	s_waitcnt lgkmcnt(0)
	v_mfma_f32_16x16x32_bf16 v[62:65], v[148:151], v[190:193], v[62:65]
	v_mfma_f32_16x16x32_bf16 v[58:61], v[166:169], v[190:193], v[58:61]
	v_mfma_f32_16x16x32_bf16 v[46:49], v[148:151], v[198:201], v[46:49]
	v_mfma_f32_16x16x32_bf16 v[42:45], v[166:169], v[198:201], v[42:45]
	v_mfma_f32_16x16x32_bf16 v[30:33], v[148:151], v[206:209], v[30:33]
	v_mfma_f32_16x16x32_bf16 v[26:29], v[166:169], v[206:209], v[26:29]
	v_mfma_f32_16x16x32_bf16 v[14:17], v[148:151], v[214:217], v[14:17]
	v_mfma_f32_16x16x32_bf16 v[10:13], v[166:169], v[214:217], v[10:13]
	v_mfma_f32_16x16x32_bf16 v[62:65], v[162:165], v[194:197], v[62:65]
	v_mfma_f32_16x16x32_bf16 v[58:61], v[170:173], v[194:197], v[58:61]
	v_mfma_f32_16x16x32_bf16 v[46:49], v[162:165], v[202:205], v[46:49]
	v_mfma_f32_16x16x32_bf16 v[42:45], v[170:173], v[202:205], v[42:45]
	v_mfma_f32_16x16x32_bf16 v[30:33], v[162:165], v[210:213], v[30:33]
	v_mfma_f32_16x16x32_bf16 v[26:29], v[170:173], v[210:213], v[26:29]
	v_mfma_f32_16x16x32_bf16 v[14:17], v[162:165], v[218:221], v[14:17]
	v_mfma_f32_16x16x32_bf16 v[10:13], v[170:173], v[218:221], v[10:13]
	s_setprio 0
	s_setprio 1
	v_mfma_f32_16x16x32_bf16 v[54:57], v[174:177], v[190:193], v[54:57]
	v_mfma_f32_16x16x32_bf16 v[50:53], v[182:185], v[190:193], v[50:53]
	v_mfma_f32_16x16x32_bf16 v[38:41], v[174:177], v[198:201], v[38:41]
	v_mfma_f32_16x16x32_bf16 v[34:37], v[182:185], v[198:201], v[34:37]
	v_mfma_f32_16x16x32_bf16 v[22:25], v[174:177], v[206:209], v[22:25]
	v_mfma_f32_16x16x32_bf16 v[18:21], v[182:185], v[206:209], v[18:21]
	v_mfma_f32_16x16x32_bf16 v[6:9], v[174:177], v[214:217], v[6:9]
	v_mfma_f32_16x16x32_bf16 v[2:5], v[182:185], v[214:217], v[2:5]
	v_mfma_f32_16x16x32_bf16 v[54:57], v[178:181], v[194:197], v[54:57]
	v_mfma_f32_16x16x32_bf16 v[50:53], v[186:189], v[194:197], v[50:53]
	v_mfma_f32_16x16x32_bf16 v[38:41], v[178:181], v[202:205], v[38:41]
	v_mfma_f32_16x16x32_bf16 v[34:37], v[186:189], v[202:205], v[34:37]
	v_mfma_f32_16x16x32_bf16 v[22:25], v[178:181], v[210:213], v[22:25]
	v_mfma_f32_16x16x32_bf16 v[18:21], v[186:189], v[210:213], v[18:21]
	v_mfma_f32_16x16x32_bf16 v[6:9], v[178:181], v[218:221], v[6:9]
	v_mfma_f32_16x16x32_bf16 v[2:5], v[186:189], v[218:221], v[2:5]
	s_setprio 0
	s_add_i32 s57, s57, 2
	s_add_u32 s22, s22, 0x100
	s_addc_u32 s23, s23, 0
	s_add_u32 s55, s55, 0x100
	s_addc_u32 s56, s56, 0
	s_cmp_gt_u32 s57, 13
	s_barrier
	s_cbranch_scc0 .LBB0_3293
	s_and_b64 vcc, exec, s[14:15]
	s_cbranch_vccz .LBB0_3296
	s_barrier

.LBB0_3379:
	ds_read_b128 v[130:133], v169
	ds_read_b128 v[134:137], v169 offset:1024
	ds_read_b128 v[158:161], v169 offset:2048
	ds_read_b128 v[174:177], v169 offset:3072
	ds_read_b128 v[178:181], v170
	ds_read_b128 v[182:185], v170 offset:1024
	ds_read_b128 v[186:189], v170 offset:2048
	ds_read_b128 v[190:193], v170 offset:3072
	s_add_u32 s40, s38, 0xfff50080
	s_addc_u32 s41, s39, -1
	s_cmp_eq_u32 s63, 40
	s_cselect_b32 s43, s7, s41
	s_cselect_b32 s42, s6, s40
	s_cselect_b32 s41, s37, s62
	s_cselect_b32 s40, s36, s61
	v_lshl_add_u64 v[138:139], s[38:39], 0, v[150:151]
	s_add_i32 m0, s33, 0xc000
	ds_read_b128 v[194:197], v171
	ds_read_b128 v[198:201], v171 offset:1024
	ds_read_b128 v[202:205], v171 offset:2048
	ds_read_b128 v[206:209], v171 offset:3072
	ds_read_b128 v[210:213], v171 offset:4096
	ds_read_b128 v[214:217], v171 offset:5120
	ds_read_b128 v[218:221], v171 offset:6144
	ds_read_b128 v[222:225], v171 offset:7168
	global_load_lds_dwordx4 v[138:139], off
	v_lshl_add_u64 v[138:139], s[38:39], 0, v[152:153]
	s_add_i32 m0, s33, 0xe000
	s_nop 0
	global_load_lds_dwordx4 v[138:139], off
	s_waitcnt vmcnt(8)
	s_waitcnt lgkmcnt(0)
	s_barrier
	s_setprio 1
	s_waitcnt lgkmcnt(0)
	v_mfma_f32_16x16x32_bf16 v[126:129], v[130:133], v[194:197], v[126:129]
	v_mfma_f32_16x16x32_bf16 v[122:125], v[158:161], v[194:197], v[122:125]
	v_mfma_f32_16x16x32_bf16 v[110:113], v[130:133], v[202:205], v[110:113]
	v_mfma_f32_16x16x32_bf16 v[106:109], v[158:161], v[202:205], v[106:109]
	v_mfma_f32_16x16x32_bf16 v[94:97], v[130:133], v[210:213], v[94:97]
	v_mfma_f32_16x16x32_bf16 v[90:93], v[158:161], v[210:213], v[90:93]
	v_mfma_f32_16x16x32_bf16 v[78:81], v[130:133], v[218:221], v[78:81]
	v_mfma_f32_16x16x32_bf16 v[74:77], v[158:161], v[218:221], v[74:77]
	v_mfma_f32_16x16x32_bf16 v[126:129], v[134:137], v[198:201], v[126:129]
	v_mfma_f32_16x16x32_bf16 v[122:125], v[174:177], v[198:201], v[122:125]
	v_mfma_f32_16x16x32_bf16 v[110:113], v[134:137], v[206:209], v[110:113]
	v_mfma_f32_16x16x32_bf16 v[106:109], v[174:177], v[206:209], v[106:109]
	v_mfma_f32_16x16x32_bf16 v[94:97], v[134:137], v[214:217], v[94:97]
	v_mfma_f32_16x16x32_bf16 v[90:93], v[174:177], v[214:217], v[90:93]
	v_mfma_f32_16x16x32_bf16 v[78:81], v[134:137], v[222:225], v[78:81]
	v_mfma_f32_16x16x32_bf16 v[74:77], v[174:177], v[222:225], v[74:77]
	s_setprio 0
	s_setprio 1
	v_mfma_f32_16x16x32_bf16 v[118:121], v[178:181], v[194:197], v[118:121]
	v_mfma_f32_16x16x32_bf16 v[114:117], v[186:189], v[194:197], v[114:117]
	v_mfma_f32_16x16x32_bf16 v[102:105], v[178:181], v[202:205], v[102:105]
	v_mfma_f32_16x16x32_bf16 v[98:101], v[186:189], v[202:205], v[98:101]
	v_mfma_f32_16x16x32_bf16 v[86:89], v[178:181], v[210:213], v[86:89]
	v_mfma_f32_16x16x32_bf16 v[82:85], v[186:189], v[210:213], v[82:85]
	v_mfma_f32_16x16x32_bf16 v[70:73], v[178:181], v[218:221], v[70:73]
	v_mfma_f32_16x16x32_bf16 v[66:69], v[186:189], v[218:221], v[66:69]
	v_mfma_f32_16x16x32_bf16 v[118:121], v[182:185], v[198:201], v[118:121]
	v_mfma_f32_16x16x32_bf16 v[114:117], v[190:193], v[198:201], v[114:117]
	v_mfma_f32_16x16x32_bf16 v[102:105], v[182:185], v[206:209], v[102:105]
	v_mfma_f32_16x16x32_bf16 v[98:101], v[190:193], v[206:209], v[98:101]
	v_mfma_f32_16x16x32_bf16 v[86:89], v[182:185], v[214:217], v[86:89]
	v_mfma_f32_16x16x32_bf16 v[82:85], v[190:193], v[214:217], v[82:85]
	v_mfma_f32_16x16x32_bf16 v[70:73], v[182:185], v[222:225], v[70:73]
	v_mfma_f32_16x16x32_bf16 v[66:69], v[190:193], v[222:225], v[66:69]
	s_setprio 0
	s_barrier
	s_add_i32 s66, s54, s3
	v_lshl_add_u64 v[138:139], s[40:41], 0, v[144:145]
	s_mov_b32 m0, s66
	ds_read_b128 v[194:197], v171 offset:16384
	ds_read_b128 v[198:201], v171 offset:17408
	ds_read_b128 v[202:205], v171 offset:18432
	ds_read_b128 v[206:209], v171 offset:19456
	ds_read_b128 v[210:213], v171 offset:20480
	ds_read_b128 v[214:217], v171 offset:21504
	ds_read_b128 v[218:221], v171 offset:22528
	ds_read_b128 v[222:225], v171 offset:23552
	global_load_lds_dwordx4 v[138:139], off
	s_add_i32 m0, s66, 0x2000
	s_add_u32 s66, s40, 0xb0000
	v_lshl_add_u64 v[162:163], s[40:41], 0, v[148:149]
	s_addc_u32 s67, s41, 0
	s_add_i32 s68, s55, s3
	global_load_lds_dwordx4 v[162:163], off
	v_lshl_add_u64 v[226:227], s[66:67], 0, v[144:145]
	s_mov_b32 m0, s68
	v_lshl_add_u64 v[228:229], s[42:43], 0, v[146:147]
	global_load_lds_dwordx4 v[226:227], off
	v_lshl_add_u64 v[226:227], s[66:67], 0, v[148:149]
	s_add_i32 m0, s68, 0x2000
	s_nop 0
	global_load_lds_dwordx4 v[226:227], off
	v_lshl_add_u64 v[226:227], s[42:43], 0, v[142:143]
	s_mov_b32 m0, s33
	s_nop 0
	global_load_lds_dwordx4 v[226:227], off
	s_mov_b32 m0, s35
	s_nop 0
	global_load_lds_dwordx4 v[228:229], off
	s_waitcnt vmcnt(8)
	s_waitcnt lgkmcnt(0)
	s_barrier
	s_setprio 1
	s_waitcnt lgkmcnt(0)
	v_mfma_f32_16x16x32_bf16 v[62:65], v[130:133], v[194:197], v[62:65]
	v_mfma_f32_16x16x32_bf16 v[58:61], v[158:161], v[194:197], v[58:61]
	v_mfma_f32_16x16x32_bf16 v[46:49], v[130:133], v[202:205], v[46:49]
	v_mfma_f32_16x16x32_bf16 v[42:45], v[158:161], v[202:205], v[42:45]
	v_mfma_f32_16x16x32_bf16 v[30:33], v[130:133], v[210:213], v[30:33]
	v_mfma_f32_16x16x32_bf16 v[26:29], v[158:161], v[210:213], v[26:29]
	v_mfma_f32_16x16x32_bf16 v[14:17], v[130:133], v[218:221], v[14:17]
	v_mfma_f32_16x16x32_bf16 v[10:13], v[158:161], v[218:221], v[10:13]
	v_mfma_f32_16x16x32_bf16 v[62:65], v[134:137], v[198:201], v[62:65]
	v_mfma_f32_16x16x32_bf16 v[58:61], v[174:177], v[198:201], v[58:61]
	v_mfma_f32_16x16x32_bf16 v[46:49], v[134:137], v[206:209], v[46:49]
	v_mfma_f32_16x16x32_bf16 v[42:45], v[174:177], v[206:209], v[42:45]
	v_mfma_f32_16x16x32_bf16 v[30:33], v[134:137], v[214:217], v[30:33]
	v_mfma_f32_16x16x32_bf16 v[26:29], v[174:177], v[214:217], v[26:29]
	v_mfma_f32_16x16x32_bf16 v[14:17], v[134:137], v[222:225], v[14:17]
	v_mfma_f32_16x16x32_bf16 v[10:13], v[174:177], v[222:225], v[10:13]
	s_setprio 0
	s_setprio 1
	v_mfma_f32_16x16x32_bf16 v[54:57], v[178:181], v[194:197], v[54:57]
	v_mfma_f32_16x16x32_bf16 v[50:53], v[186:189], v[194:197], v[50:53]
	v_mfma_f32_16x16x32_bf16 v[38:41], v[178:181], v[202:205], v[38:41]
	v_mfma_f32_16x16x32_bf16 v[34:37], v[186:189], v[202:205], v[34:37]
	v_mfma_f32_16x16x32_bf16 v[22:25], v[178:181], v[210:213], v[22:25]
	v_mfma_f32_16x16x32_bf16 v[18:21], v[186:189], v[210:213], v[18:21]
	v_mfma_f32_16x16x32_bf16 v[6:9], v[178:181], v[218:221], v[6:9]
	v_mfma_f32_16x16x32_bf16 v[2:5], v[186:189], v[218:221], v[2:5]
	v_mfma_f32_16x16x32_bf16 v[54:57], v[182:185], v[198:201], v[54:57]
	v_mfma_f32_16x16x32_bf16 v[50:53], v[190:193], v[198:201], v[50:53]
	v_mfma_f32_16x16x32_bf16 v[38:41], v[182:185], v[206:209], v[38:41]
	v_mfma_f32_16x16x32_bf16 v[34:37], v[190:193], v[206:209], v[34:37]
	v_mfma_f32_16x16x32_bf16 v[22:25], v[182:185], v[214:217], v[22:25]
	v_mfma_f32_16x16x32_bf16 v[18:21], v[190:193], v[214:217], v[18:21]
	v_mfma_f32_16x16x32_bf16 v[6:9], v[182:185], v[222:225], v[6:9]
	v_mfma_f32_16x16x32_bf16 v[2:5], v[190:193], v[222:225], v[2:5]
	s_setprio 0
	s_barrier
	s_add_i32 s66, 0, 0x18000
	v_add_u32_e32 v173, s66, v141
	s_add_i32 s67, 0, 0x1c000
	ds_read_b128 v[130:133], v173
	ds_read_b128 v[134:137], v173 offset:1024
	ds_read_b128 v[158:161], v173 offset:2048
	ds_read_b128 v[174:177], v173 offset:3072
	v_add_u32_e32 v173, s67, v141
	ds_read_b128 v[178:181], v173
	ds_read_b128 v[182:185], v173 offset:1024
	ds_read_b128 v[186:189], v173 offset:2048
	ds_read_b128 v[190:193], v173 offset:3072
	s_add_u32 s42, s42, 0xb0000
	s_addc_u32 s43, s43, 0
	s_mov_b32 m0, s44
	v_lshl_add_u64 v[230:231], s[42:43], 0, v[142:143]
	ds_read_b128 v[194:197], v171 offset:32768
	ds_read_b128 v[198:201], v171 offset:33792
	ds_read_b128 v[202:205], v171 offset:34816
	ds_read_b128 v[206:209], v171 offset:35840
	ds_read_b128 v[210:213], v171 offset:36864
	ds_read_b128 v[214:217], v171 offset:37888
	ds_read_b128 v[218:221], v171 offset:38912
	ds_read_b128 v[222:225], v171 offset:39936
	global_load_lds_dwordx4 v[230:231], off
	v_lshl_add_u64 v[230:231], s[42:43], 0, v[146:147]
	s_mov_b32 m0, s45
	s_nop 0
	global_load_lds_dwordx4 v[230:231], off
	s_waitcnt vmcnt(8)
	s_waitcnt lgkmcnt(0)
	s_barrier
	s_setprio 1
	s_waitcnt lgkmcnt(0)
	v_mfma_f32_16x16x32_bf16 v[126:129], v[130:133], v[194:197], v[126:129]
	v_mfma_f32_16x16x32_bf16 v[122:125], v[158:161], v[194:197], v[122:125]
	v_mfma_f32_16x16x32_bf16 v[110:113], v[130:133], v[202:205], v[110:113]
	v_mfma_f32_16x16x32_bf16 v[106:109], v[158:161], v[202:205], v[106:109]
	v_mfma_f32_16x16x32_bf16 v[94:97], v[130:133], v[210:213], v[94:97]
	v_mfma_f32_16x16x32_bf16 v[90:93], v[158:161], v[210:213], v[90:93]
	v_mfma_f32_16x16x32_bf16 v[78:81], v[130:133], v[218:221], v[78:81]
	v_mfma_f32_16x16x32_bf16 v[74:77], v[158:161], v[218:221], v[74:77]
	v_mfma_f32_16x16x32_bf16 v[126:129], v[134:137], v[198:201], v[126:129]
	v_mfma_f32_16x16x32_bf16 v[122:125], v[174:177], v[198:201], v[122:125]
	v_mfma_f32_16x16x32_bf16 v[110:113], v[134:137], v[206:209], v[110:113]
	v_mfma_f32_16x16x32_bf16 v[106:109], v[174:177], v[206:209], v[106:109]
	v_mfma_f32_16x16x32_bf16 v[94:97], v[134:137], v[214:217], v[94:97]
	v_mfma_f32_16x16x32_bf16 v[90:93], v[174:177], v[214:217], v[90:93]
	v_mfma_f32_16x16x32_bf16 v[78:81], v[134:137], v[222:225], v[78:81]
	v_mfma_f32_16x16x32_bf16 v[74:77], v[174:177], v[222:225], v[74:77]
	s_setprio 0
	s_setprio 1
	v_mfma_f32_16x16x32_bf16 v[118:121], v[178:181], v[194:197], v[118:121]
	v_mfma_f32_16x16x32_bf16 v[114:117], v[186:189], v[194:197], v[114:117]
	v_mfma_f32_16x16x32_bf16 v[102:105], v[178:181], v[202:205], v[102:105]
	v_mfma_f32_16x16x32_bf16 v[98:101], v[186:189], v[202:205], v[98:101]
	v_mfma_f32_16x16x32_bf16 v[86:89], v[178:181], v[210:213], v[86:89]
	v_mfma_f32_16x16x32_bf16 v[82:85], v[186:189], v[210:213], v[82:85]
	v_mfma_f32_16x16x32_bf16 v[70:73], v[178:181], v[218:221], v[70:73]
	v_mfma_f32_16x16x32_bf16 v[66:69], v[186:189], v[218:221], v[66:69]
	v_mfma_f32_16x16x32_bf16 v[118:121], v[182:185], v[198:201], v[118:121]
	v_mfma_f32_16x16x32_bf16 v[114:117], v[190:193], v[198:201], v[114:117]
	v_mfma_f32_16x16x32_bf16 v[102:105], v[182:185], v[206:209], v[102:105]
	v_mfma_f32_16x16x32_bf16 v[98:101], v[190:193], v[206:209], v[98:101]
	v_mfma_f32_16x16x32_bf16 v[86:89], v[182:185], v[214:217], v[86:89]
	v_mfma_f32_16x16x32_bf16 v[82:85], v[190:193], v[214:217], v[82:85]
	v_mfma_f32_16x16x32_bf16 v[70:73], v[182:185], v[222:225], v[70:73]
	v_mfma_f32_16x16x32_bf16 v[66:69], v[190:193], v[222:225], v[66:69]
	s_setprio 0
	s_barrier
	s_add_i32 s42, s66, s3
	v_lshl_add_u64 v[138:139], v[138:139], 0, s[20:21]
	s_mov_b32 m0, s42
	ds_read_b128 v[194:197], v171 offset:49152
	ds_read_b128 v[198:201], v171 offset:50176
	ds_read_b128 v[202:205], v171 offset:51200
	ds_read_b128 v[206:209], v171 offset:52224
	ds_read_b128 v[210:213], v171 offset:53248
	ds_read_b128 v[214:217], v171 offset:54272
	ds_read_b128 v[218:221], v171 offset:55296
	ds_read_b128 v[222:225], v171 offset:56320
	global_load_lds_dwordx4 v[138:139], off
	s_add_i32 m0, s42, 0x2000
	s_add_u32 s40, s40, 0xb0080
	v_lshl_add_u64 v[138:139], v[162:163], 0, s[20:21]
	s_addc_u32 s41, s41, 0
	s_add_i32 s42, s67, s3
	global_load_lds_dwordx4 v[138:139], off
	v_lshl_add_u64 v[138:139], s[40:41], 0, v[144:145]
	s_mov_b32 m0, s42
	s_nop 0
	global_load_lds_dwordx4 v[138:139], off
	v_lshl_add_u64 v[138:139], s[40:41], 0, v[148:149]
	s_add_i32 m0, s42, 0x2000
	s_nop 0
	global_load_lds_dwordx4 v[138:139], off
	v_lshl_add_u64 v[138:139], v[226:227], 0, s[20:21]
	s_mov_b32 m0, s48
	s_nop 0
	global_load_lds_dwordx4 v[138:139], off
	v_lshl_add_u64 v[138:139], v[228:229], 0, s[20:21]
	s_mov_b32 m0, s49
	s_nop 0
	global_load_lds_dwordx4 v[138:139], off
	s_waitcnt vmcnt(8)
	s_waitcnt lgkmcnt(0)
	s_barrier
	s_setprio 1
	s_waitcnt lgkmcnt(0)
	v_mfma_f32_16x16x32_bf16 v[62:65], v[130:133], v[194:197], v[62:65]
	v_mfma_f32_16x16x32_bf16 v[58:61], v[158:161], v[194:197], v[58:61]
	v_mfma_f32_16x16x32_bf16 v[46:49], v[130:133], v[202:205], v[46:49]
	v_mfma_f32_16x16x32_bf16 v[42:45], v[158:161], v[202:205], v[42:45]
	v_mfma_f32_16x16x32_bf16 v[30:33], v[130:133], v[210:213], v[30:33]
	v_mfma_f32_16x16x32_bf16 v[26:29], v[158:161], v[210:213], v[26:29]
	v_mfma_f32_16x16x32_bf16 v[14:17], v[130:133], v[218:221], v[14:17]
	v_mfma_f32_16x16x32_bf16 v[10:13], v[158:161], v[218:221], v[10:13]
	v_mfma_f32_16x16x32_bf16 v[62:65], v[134:137], v[198:201], v[62:65]
	v_mfma_f32_16x16x32_bf16 v[58:61], v[174:177], v[198:201], v[58:61]
	v_mfma_f32_16x16x32_bf16 v[46:49], v[134:137], v[206:209], v[46:49]
	v_mfma_f32_16x16x32_bf16 v[42:45], v[174:177], v[206:209], v[42:45]
	v_mfma_f32_16x16x32_bf16 v[30:33], v[134:137], v[214:217], v[30:33]
	v_mfma_f32_16x16x32_bf16 v[26:29], v[174:177], v[214:217], v[26:29]
	v_mfma_f32_16x16x32_bf16 v[14:17], v[134:137], v[222:225], v[14:17]
	v_mfma_f32_16x16x32_bf16 v[10:13], v[174:177], v[222:225], v[10:13]
	s_setprio 0
	s_setprio 1
	v_mfma_f32_16x16x32_bf16 v[54:57], v[178:181], v[194:197], v[54:57]
	v_mfma_f32_16x16x32_bf16 v[50:53], v[186:189], v[194:197], v[50:53]
	v_mfma_f32_16x16x32_bf16 v[38:41], v[178:181], v[202:205], v[38:41]
	v_mfma_f32_16x16x32_bf16 v[34:37], v[186:189], v[202:205], v[34:37]
	v_mfma_f32_16x16x32_bf16 v[22:25], v[178:181], v[210:213], v[22:25]
	v_mfma_f32_16x16x32_bf16 v[18:21], v[186:189], v[210:213], v[18:21]
	v_mfma_f32_16x16x32_bf16 v[6:9], v[178:181], v[218:221], v[6:9]
	v_mfma_f32_16x16x32_bf16 v[2:5], v[186:189], v[218:221], v[2:5]
	v_mfma_f32_16x16x32_bf16 v[54:57], v[182:185], v[198:201], v[54:57]
	v_mfma_f32_16x16x32_bf16 v[50:53], v[190:193], v[198:201], v[50:53]
	v_mfma_f32_16x16x32_bf16 v[38:41], v[182:185], v[206:209], v[38:41]
	v_mfma_f32_16x16x32_bf16 v[34:37], v[190:193], v[206:209], v[34:37]
	v_mfma_f32_16x16x32_bf16 v[22:25], v[182:185], v[214:217], v[22:25]
	v_mfma_f32_16x16x32_bf16 v[18:21], v[190:193], v[214:217], v[18:21]
	v_mfma_f32_16x16x32_bf16 v[6:9], v[182:185], v[222:225], v[6:9]
	v_mfma_f32_16x16x32_bf16 v[2:5], v[190:193], v[222:225], v[2:5]
	s_setprio 0
	s_add_i32 s63, s63, 2
	s_add_u32 s38, s38, 0x100
	s_addc_u32 s39, s39, 0
	s_add_u32 s61, s61, 0x100
	s_addc_u32 s62, s62, 0
	s_cmp_gt_u32 s63, 41
	s_barrier
	s_cbranch_scc0 .LBB0_3379
	s_and_b64 vcc, exec, s[22:23]
	s_cbranch_vccz .LBB0_3382
	s_barrier

.LBB0_3455:
	v_add_u32_e32 v168, s54, v154
	v_add_u32_e32 v184, s55, v154
	s_add_u32 s44, s40, s42
	ds_read_b128 v[156:159], v168
	ds_read_b128 v[160:163], v168 offset:1024
	ds_read_b128 v[164:167], v168 offset:2048
	ds_read_b128 v[168:171], v168 offset:3072
	ds_read_b128 v[172:175], v184
	ds_read_b128 v[176:179], v184 offset:1024
	ds_read_b128 v[180:183], v184 offset:2048
	ds_read_b128 v[184:187], v184 offset:3072
	s_addc_u32 s45, s41, s43
	s_add_u32 s44, s44, 0x100
	s_addc_u32 s45, s45, 0
	s_add_u32 s61, s37, s42
	s_addc_u32 s62, s59, s43
	s_cmpk_eq_i32 s42, 0x1500
	s_cselect_b32 s47, s7, s45
	s_cselect_b32 s46, s6, s44
	s_cselect_b32 s45, s39, s62
	s_cselect_b32 s44, s38, s61
	v_lshl_add_u64 v[220:221], v[148:149], 0, s[42:43]
	s_add_i32 m0, s35, 0xc000
	ds_read_b128 v[188:191], v155
	ds_read_b128 v[192:195], v155 offset:1024
	ds_read_b128 v[196:199], v155 offset:2048
	ds_read_b128 v[200:203], v155 offset:3072
	ds_read_b128 v[204:207], v155 offset:4096
	ds_read_b128 v[208:211], v155 offset:5120
	ds_read_b128 v[212:215], v155 offset:6144
	ds_read_b128 v[216:219], v155 offset:7168
	global_load_lds_dwordx4 v[220:221], off
	v_lshl_add_u64 v[220:221], v[150:151], 0, s[42:43]
	s_add_i32 m0, s35, 0xe000
	s_nop 0
	global_load_lds_dwordx4 v[220:221], off
	s_waitcnt vmcnt(8)
	s_waitcnt lgkmcnt(0)
	s_barrier
	s_setprio 1
	s_waitcnt lgkmcnt(0)
	v_mfma_f32_16x16x32_bf16 v[126:129], v[156:159], v[188:191], v[126:129]
	v_mfma_f32_16x16x32_bf16 v[122:125], v[164:167], v[188:191], v[122:125]
	v_mfma_f32_16x16x32_bf16 v[110:113], v[156:159], v[196:199], v[110:113]
	v_mfma_f32_16x16x32_bf16 v[106:109], v[164:167], v[196:199], v[106:109]
	v_mfma_f32_16x16x32_bf16 v[94:97], v[156:159], v[204:207], v[94:97]
	v_mfma_f32_16x16x32_bf16 v[90:93], v[164:167], v[204:207], v[90:93]
	v_mfma_f32_16x16x32_bf16 v[78:81], v[156:159], v[212:215], v[78:81]
	v_mfma_f32_16x16x32_bf16 v[74:77], v[164:167], v[212:215], v[74:77]
	v_mfma_f32_16x16x32_bf16 v[126:129], v[160:163], v[192:195], v[126:129]
	v_mfma_f32_16x16x32_bf16 v[122:125], v[168:171], v[192:195], v[122:125]
	v_mfma_f32_16x16x32_bf16 v[110:113], v[160:163], v[200:203], v[110:113]
	v_mfma_f32_16x16x32_bf16 v[106:109], v[168:171], v[200:203], v[106:109]
	v_mfma_f32_16x16x32_bf16 v[94:97], v[160:163], v[208:211], v[94:97]
	v_mfma_f32_16x16x32_bf16 v[90:93], v[168:171], v[208:211], v[90:93]
	v_mfma_f32_16x16x32_bf16 v[78:81], v[160:163], v[216:219], v[78:81]
	v_mfma_f32_16x16x32_bf16 v[74:77], v[168:171], v[216:219], v[74:77]
	s_setprio 0
	s_setprio 1
	v_mfma_f32_16x16x32_bf16 v[118:121], v[172:175], v[188:191], v[118:121]
	v_mfma_f32_16x16x32_bf16 v[114:117], v[180:183], v[188:191], v[114:117]
	v_mfma_f32_16x16x32_bf16 v[102:105], v[172:175], v[196:199], v[102:105]
	v_mfma_f32_16x16x32_bf16 v[98:101], v[180:183], v[196:199], v[98:101]
	v_mfma_f32_16x16x32_bf16 v[86:89], v[172:175], v[204:207], v[86:89]
	v_mfma_f32_16x16x32_bf16 v[82:85], v[180:183], v[204:207], v[82:85]
	v_mfma_f32_16x16x32_bf16 v[70:73], v[172:175], v[212:215], v[70:73]
	v_mfma_f32_16x16x32_bf16 v[66:69], v[180:183], v[212:215], v[66:69]
	v_mfma_f32_16x16x32_bf16 v[118:121], v[176:179], v[192:195], v[118:121]
	v_mfma_f32_16x16x32_bf16 v[114:117], v[184:187], v[192:195], v[114:117]
	v_mfma_f32_16x16x32_bf16 v[102:105], v[176:179], v[200:203], v[102:105]
	v_mfma_f32_16x16x32_bf16 v[98:101], v[184:187], v[200:203], v[98:101]
	v_mfma_f32_16x16x32_bf16 v[86:89], v[176:179], v[208:211], v[86:89]
	v_mfma_f32_16x16x32_bf16 v[82:85], v[184:187], v[208:211], v[82:85]
	v_mfma_f32_16x16x32_bf16 v[70:73], v[176:179], v[216:219], v[70:73]
	v_mfma_f32_16x16x32_bf16 v[66:69], v[184:187], v[216:219], v[66:69]
	s_setprio 0
	s_barrier
	s_add_i32 s61, s54, s33
	v_lshl_add_u64 v[220:221], s[44:45], 0, v[132:133]
	s_mov_b32 m0, s61
	ds_read_b128 v[188:191], v155 offset:16384
	ds_read_b128 v[192:195], v155 offset:17408
	ds_read_b128 v[196:199], v155 offset:18432
	ds_read_b128 v[200:203], v155 offset:19456
	ds_read_b128 v[204:207], v155 offset:20480
	ds_read_b128 v[208:211], v155 offset:21504
	ds_read_b128 v[212:215], v155 offset:22528
	ds_read_b128 v[216:219], v155 offset:23552
	global_load_lds_dwordx4 v[220:221], off
	s_add_i32 m0, s61, 0x2000
	s_add_u32 s62, s44, 0xb0000
	v_lshl_add_u64 v[222:223], s[44:45], 0, v[136:137]
	s_addc_u32 s63, s45, 0
	s_add_i32 s61, s55, s33
	global_load_lds_dwordx4 v[222:223], off
	v_lshl_add_u64 v[224:225], s[62:63], 0, v[132:133]
	s_mov_b32 m0, s61
	v_lshl_add_u64 v[226:227], s[46:47], 0, v[134:135]
	global_load_lds_dwordx4 v[224:225], off
	v_lshl_add_u64 v[224:225], s[62:63], 0, v[136:137]
	s_add_i32 m0, s61, 0x2000
	s_nop 0
	global_load_lds_dwordx4 v[224:225], off
	v_lshl_add_u64 v[224:225], s[46:47], 0, v[130:131]
	s_mov_b32 m0, s35
	s_nop 0
	global_load_lds_dwordx4 v[224:225], off
	s_mov_b32 m0, s48
	s_nop 0
	global_load_lds_dwordx4 v[226:227], off
	s_waitcnt vmcnt(8)
	s_waitcnt lgkmcnt(0)
	s_barrier
	s_setprio 1
	s_waitcnt lgkmcnt(0)
	v_mfma_f32_16x16x32_bf16 v[62:65], v[156:159], v[188:191], v[62:65]
	v_mfma_f32_16x16x32_bf16 v[58:61], v[164:167], v[188:191], v[58:61]
	v_mfma_f32_16x16x32_bf16 v[46:49], v[156:159], v[196:199], v[46:49]
	v_mfma_f32_16x16x32_bf16 v[42:45], v[164:167], v[196:199], v[42:45]
	v_mfma_f32_16x16x32_bf16 v[30:33], v[156:159], v[204:207], v[30:33]
	v_mfma_f32_16x16x32_bf16 v[26:29], v[164:167], v[204:207], v[26:29]
	v_mfma_f32_16x16x32_bf16 v[14:17], v[156:159], v[212:215], v[14:17]
	v_mfma_f32_16x16x32_bf16 v[10:13], v[164:167], v[212:215], v[10:13]
	v_mfma_f32_16x16x32_bf16 v[62:65], v[160:163], v[192:195], v[62:65]
	v_mfma_f32_16x16x32_bf16 v[58:61], v[168:171], v[192:195], v[58:61]
	v_mfma_f32_16x16x32_bf16 v[46:49], v[160:163], v[200:203], v[46:49]
	v_mfma_f32_16x16x32_bf16 v[42:45], v[168:171], v[200:203], v[42:45]
	v_mfma_f32_16x16x32_bf16 v[30:33], v[160:163], v[208:211], v[30:33]
	v_mfma_f32_16x16x32_bf16 v[26:29], v[168:171], v[208:211], v[26:29]
	v_mfma_f32_16x16x32_bf16 v[14:17], v[160:163], v[216:219], v[14:17]
	v_mfma_f32_16x16x32_bf16 v[10:13], v[168:171], v[216:219], v[10:13]
	s_setprio 0
	s_setprio 1
	v_mfma_f32_16x16x32_bf16 v[54:57], v[172:175], v[188:191], v[54:57]
	v_mfma_f32_16x16x32_bf16 v[50:53], v[180:183], v[188:191], v[50:53]
	v_mfma_f32_16x16x32_bf16 v[38:41], v[172:175], v[196:199], v[38:41]
	v_mfma_f32_16x16x32_bf16 v[34:37], v[180:183], v[196:199], v[34:37]
	v_mfma_f32_16x16x32_bf16 v[22:25], v[172:175], v[204:207], v[22:25]
	v_mfma_f32_16x16x32_bf16 v[18:21], v[180:183], v[204:207], v[18:21]
	v_mfma_f32_16x16x32_bf16 v[6:9], v[172:175], v[212:215], v[6:9]
	v_mfma_f32_16x16x32_bf16 v[2:5], v[180:183], v[212:215], v[2:5]
	v_mfma_f32_16x16x32_bf16 v[54:57], v[176:179], v[192:195], v[54:57]
	v_mfma_f32_16x16x32_bf16 v[50:53], v[184:187], v[192:195], v[50:53]
	v_mfma_f32_16x16x32_bf16 v[38:41], v[176:179], v[200:203], v[38:41]
	v_mfma_f32_16x16x32_bf16 v[34:37], v[184:187], v[200:203], v[34:37]
	v_mfma_f32_16x16x32_bf16 v[22:25], v[176:179], v[208:211], v[22:25]
	v_mfma_f32_16x16x32_bf16 v[18:21], v[184:187], v[208:211], v[18:21]
	v_mfma_f32_16x16x32_bf16 v[6:9], v[176:179], v[216:219], v[6:9]
	v_mfma_f32_16x16x32_bf16 v[2:5], v[184:187], v[216:219], v[2:5]
	s_setprio 0
	s_barrier
	s_add_i32 s61, 0, 0x18000
	s_add_i32 s62, 0, 0x1c000
	v_add_u32_e32 v168, s61, v154
	v_add_u32_e32 v184, s62, v154
	ds_read_b128 v[156:159], v168
	ds_read_b128 v[160:163], v168 offset:1024
	ds_read_b128 v[164:167], v168 offset:2048
	ds_read_b128 v[168:171], v168 offset:3072
	ds_read_b128 v[172:175], v184
	ds_read_b128 v[176:179], v184 offset:1024
	ds_read_b128 v[180:183], v184 offset:2048
	ds_read_b128 v[184:187], v184 offset:3072
	s_add_u32 s46, s46, 0xb0000
	s_addc_u32 s47, s47, 0
	s_mov_b32 m0, s49
	v_lshl_add_u64 v[228:229], s[46:47], 0, v[130:131]
	ds_read_b128 v[188:191], v155 offset:32768
	ds_read_b128 v[192:195], v155 offset:33792
	ds_read_b128 v[196:199], v155 offset:34816
	ds_read_b128 v[200:203], v155 offset:35840
	ds_read_b128 v[204:207], v155 offset:36864
	ds_read_b128 v[208:211], v155 offset:37888
	ds_read_b128 v[212:215], v155 offset:38912
	ds_read_b128 v[216:219], v155 offset:39936
	global_load_lds_dwordx4 v[228:229], off
	v_lshl_add_u64 v[228:229], s[46:47], 0, v[134:135]
	s_mov_b32 m0, s50
	s_nop 0
	global_load_lds_dwordx4 v[228:229], off
	s_waitcnt vmcnt(8)
	s_waitcnt lgkmcnt(0)
	s_barrier
	s_setprio 1
	s_waitcnt lgkmcnt(0)
	v_mfma_f32_16x16x32_bf16 v[126:129], v[156:159], v[188:191], v[126:129]
	v_mfma_f32_16x16x32_bf16 v[122:125], v[164:167], v[188:191], v[122:125]
	v_mfma_f32_16x16x32_bf16 v[110:113], v[156:159], v[196:199], v[110:113]
	v_mfma_f32_16x16x32_bf16 v[106:109], v[164:167], v[196:199], v[106:109]
	v_mfma_f32_16x16x32_bf16 v[94:97], v[156:159], v[204:207], v[94:97]
	v_mfma_f32_16x16x32_bf16 v[90:93], v[164:167], v[204:207], v[90:93]
	v_mfma_f32_16x16x32_bf16 v[78:81], v[156:159], v[212:215], v[78:81]
	v_mfma_f32_16x16x32_bf16 v[74:77], v[164:167], v[212:215], v[74:77]
	v_mfma_f32_16x16x32_bf16 v[126:129], v[160:163], v[192:195], v[126:129]
	v_mfma_f32_16x16x32_bf16 v[122:125], v[168:171], v[192:195], v[122:125]
	v_mfma_f32_16x16x32_bf16 v[110:113], v[160:163], v[200:203], v[110:113]
	v_mfma_f32_16x16x32_bf16 v[106:109], v[168:171], v[200:203], v[106:109]
	v_mfma_f32_16x16x32_bf16 v[94:97], v[160:163], v[208:211], v[94:97]
	v_mfma_f32_16x16x32_bf16 v[90:93], v[168:171], v[208:211], v[90:93]
	v_mfma_f32_16x16x32_bf16 v[78:81], v[160:163], v[216:219], v[78:81]
	v_mfma_f32_16x16x32_bf16 v[74:77], v[168:171], v[216:219], v[74:77]
	s_setprio 0
	s_setprio 1
	v_mfma_f32_16x16x32_bf16 v[118:121], v[172:175], v[188:191], v[118:121]
	v_mfma_f32_16x16x32_bf16 v[114:117], v[180:183], v[188:191], v[114:117]
	v_mfma_f32_16x16x32_bf16 v[102:105], v[172:175], v[196:199], v[102:105]
	v_mfma_f32_16x16x32_bf16 v[98:101], v[180:183], v[196:199], v[98:101]
	v_mfma_f32_16x16x32_bf16 v[86:89], v[172:175], v[204:207], v[86:89]
	v_mfma_f32_16x16x32_bf16 v[82:85], v[180:183], v[204:207], v[82:85]
	v_mfma_f32_16x16x32_bf16 v[70:73], v[172:175], v[212:215], v[70:73]
	v_mfma_f32_16x16x32_bf16 v[66:69], v[180:183], v[212:215], v[66:69]
	v_mfma_f32_16x16x32_bf16 v[118:121], v[176:179], v[192:195], v[118:121]
	v_mfma_f32_16x16x32_bf16 v[114:117], v[184:187], v[192:195], v[114:117]
	v_mfma_f32_16x16x32_bf16 v[102:105], v[176:179], v[200:203], v[102:105]
	v_mfma_f32_16x16x32_bf16 v[98:101], v[184:187], v[200:203], v[98:101]
	v_mfma_f32_16x16x32_bf16 v[86:89], v[176:179], v[208:211], v[86:89]
	v_mfma_f32_16x16x32_bf16 v[82:85], v[184:187], v[208:211], v[82:85]
	v_mfma_f32_16x16x32_bf16 v[70:73], v[176:179], v[216:219], v[70:73]
	v_mfma_f32_16x16x32_bf16 v[66:69], v[184:187], v[216:219], v[66:69]
	s_setprio 0
	s_barrier
	s_add_i32 s46, s61, s33
	v_lshl_add_u64 v[220:221], v[220:221], 0, s[20:21]
	s_mov_b32 m0, s46
	ds_read_b128 v[188:191], v155 offset:49152
	ds_read_b128 v[192:195], v155 offset:50176
	ds_read_b128 v[196:199], v155 offset:51200
	ds_read_b128 v[200:203], v155 offset:52224
	ds_read_b128 v[204:207], v155 offset:53248
	ds_read_b128 v[208:211], v155 offset:54272
	ds_read_b128 v[212:215], v155 offset:55296
	ds_read_b128 v[216:219], v155 offset:56320
	global_load_lds_dwordx4 v[220:221], off
	s_add_i32 m0, s46, 0x2000
	s_add_u32 s44, s44, 0xb0080
	v_lshl_add_u64 v[220:221], v[222:223], 0, s[20:21]
	s_addc_u32 s45, s45, 0
	s_add_i32 s46, s62, s33
	global_load_lds_dwordx4 v[220:221], off
	v_lshl_add_u64 v[220:221], s[44:45], 0, v[132:133]
	s_mov_b32 m0, s46
	s_nop 0
	global_load_lds_dwordx4 v[220:221], off
	v_lshl_add_u64 v[220:221], s[44:45], 0, v[136:137]
	s_add_i32 m0, s46, 0x2000
	s_nop 0
	global_load_lds_dwordx4 v[220:221], off
	v_lshl_add_u64 v[220:221], v[224:225], 0, s[20:21]
	s_mov_b32 m0, s51
	s_nop 0
	global_load_lds_dwordx4 v[220:221], off
	v_lshl_add_u64 v[220:221], v[226:227], 0, s[20:21]
	s_mov_b32 m0, s52
	s_nop 0
	global_load_lds_dwordx4 v[220:221], off
	s_waitcnt vmcnt(8)
	s_waitcnt lgkmcnt(0)
	s_barrier
	s_setprio 1
	s_waitcnt lgkmcnt(0)
	v_mfma_f32_16x16x32_bf16 v[62:65], v[156:159], v[188:191], v[62:65]
	v_mfma_f32_16x16x32_bf16 v[58:61], v[164:167], v[188:191], v[58:61]
	v_mfma_f32_16x16x32_bf16 v[46:49], v[156:159], v[196:199], v[46:49]
	v_mfma_f32_16x16x32_bf16 v[42:45], v[164:167], v[196:199], v[42:45]
	v_mfma_f32_16x16x32_bf16 v[30:33], v[156:159], v[204:207], v[30:33]
	v_mfma_f32_16x16x32_bf16 v[26:29], v[164:167], v[204:207], v[26:29]
	v_mfma_f32_16x16x32_bf16 v[14:17], v[156:159], v[212:215], v[14:17]
	v_mfma_f32_16x16x32_bf16 v[10:13], v[164:167], v[212:215], v[10:13]
	v_mfma_f32_16x16x32_bf16 v[62:65], v[160:163], v[192:195], v[62:65]
	v_mfma_f32_16x16x32_bf16 v[58:61], v[168:171], v[192:195], v[58:61]
	v_mfma_f32_16x16x32_bf16 v[46:49], v[160:163], v[200:203], v[46:49]
	v_mfma_f32_16x16x32_bf16 v[42:45], v[168:171], v[200:203], v[42:45]
	v_mfma_f32_16x16x32_bf16 v[30:33], v[160:163], v[208:211], v[30:33]
	v_mfma_f32_16x16x32_bf16 v[26:29], v[168:171], v[208:211], v[26:29]
	v_mfma_f32_16x16x32_bf16 v[14:17], v[160:163], v[216:219], v[14:17]
	v_mfma_f32_16x16x32_bf16 v[10:13], v[168:171], v[216:219], v[10:13]
	s_setprio 0
	s_setprio 1
	v_mfma_f32_16x16x32_bf16 v[54:57], v[172:175], v[188:191], v[54:57]
	v_mfma_f32_16x16x32_bf16 v[50:53], v[180:183], v[188:191], v[50:53]
	v_mfma_f32_16x16x32_bf16 v[38:41], v[172:175], v[196:199], v[38:41]
	v_mfma_f32_16x16x32_bf16 v[34:37], v[180:183], v[196:199], v[34:37]
	v_mfma_f32_16x16x32_bf16 v[22:25], v[172:175], v[204:207], v[22:25]
	v_mfma_f32_16x16x32_bf16 v[18:21], v[180:183], v[204:207], v[18:21]
	v_mfma_f32_16x16x32_bf16 v[6:9], v[172:175], v[212:215], v[6:9]
	v_mfma_f32_16x16x32_bf16 v[2:5], v[180:183], v[212:215], v[2:5]
	v_mfma_f32_16x16x32_bf16 v[54:57], v[176:179], v[192:195], v[54:57]
	v_mfma_f32_16x16x32_bf16 v[50:53], v[184:187], v[192:195], v[50:53]
	v_mfma_f32_16x16x32_bf16 v[38:41], v[176:179], v[200:203], v[38:41]
	v_mfma_f32_16x16x32_bf16 v[34:37], v[184:187], v[200:203], v[34:37]
	v_mfma_f32_16x16x32_bf16 v[22:25], v[176:179], v[208:211], v[22:25]
	v_mfma_f32_16x16x32_bf16 v[18:21], v[184:187], v[208:211], v[18:21]
	v_mfma_f32_16x16x32_bf16 v[6:9], v[176:179], v[216:219], v[6:9]
	v_mfma_f32_16x16x32_bf16 v[2:5], v[184:187], v[216:219], v[2:5]
	s_setprio 0
	s_add_i32 s60, s60, 2
	s_add_u32 s42, s42, 0x100
	s_addc_u32 s43, s43, 0
	s_cmp_gt_u32 s60, 41
	s_barrier
	s_cbranch_scc0 .LBB0_3455
	s_and_b64 vcc, exec, s[22:23]
	s_cbranch_vccz .LBB0_3458
	s_barrier

.LBB0_3600:
	s_or_b64 exec, exec, s[10:11]
	v_cvt_f32_u32_e32 v5, v3
	s_waitcnt vmcnt(0)
	v_readfirstlane_b32 s3, v4
	v_sub_u32_e32 v4, 0, v3
	v_rcp_iflag_f32_e32 v5, v5
	v_add_u32_e32 v6, s3, v2
	v_mul_f32_e32 v5, 0x4f7ffffe, v5
	v_cvt_u32_f32_e32 v5, v5
	v_mul_lo_u32 v2, v4, v5
	v_mul_hi_u32 v2, v5, v2
	v_add_u32_e32 v2, v5, v2
	v_mul_hi_u32 v2, v6, v2
	v_mul_lo_u32 v4, v2, v3
	v_sub_u32_e32 v4, v6, v4
	v_add_u32_e32 v5, 1, v2
	v_cmp_ge_u32_e32 vcc, v4, v3
	s_nop 1
	v_cndmask_b32_e32 v2, v2, v5, vcc
	v_sub_u32_e32 v5, v4, v3
	v_cndmask_b32_e32 v4, v4, v5, vcc
	v_add_u32_e32 v5, 1, v2
	v_cmp_ge_u32_e32 vcc, v4, v3
	v_add_u32_e32 v4, 1, v6
	s_nop 0
	v_cndmask_b32_e32 v2, v2, v5, vcc
	v_mul_lo_u32 v5, v3, v2
	v_add_u32_e32 v3, v5, v3
	v_cmp_ne_u32_e32 vcc, v4, v3
	s_and_saveexec_b64 s[8:9], vcc
	s_xor_b64 s[8:9], exec, s[8:9]
	s_cbranch_execz .LBB0_3614
	s_waitcnt lgkmcnt(0)
	s_add_u32 s14, s28, 0xf190900
	s_addc_u32 s15, s29, 0
	v_mov_b32_e32 v1, 0
	global_load_dword v1, v1, s[14:15] sc1
	s_waitcnt vmcnt(0)
	v_cmp_eq_u32_e32 vcc, v1, v2
	s_and_saveexec_b64 s[10:11], vcc
	s_cbranch_execz .LBB0_3613
	s_add_u32 s12, s28, 0xf18d600
	s_addc_u32 s13, s29, 0
	s_mov_b32 s3, 1
	s_mov_b64 s[18:19], 0
	v_mov_b32_e32 v1, 0
	s_branch .LBB0_3604
